# phase 1 row-norm loop rewritten: 3 rows in flight per wave, params resident, DPP wave reduce
# speedup vs baseline: 1.0012x; 1.0012x over previous
; __device__ __forceinline__ void store_bf4(bf16_t* p, f32x4 v) { uint2 o; o.x = pk2(v[0], v[1]); o.y = pk2(v[2], v[3]); *(uint2*)p = o; }
; __device__ __forceinline__ void norm_row_pre(const f32x4 (&v)[4], const float* __restrict__ g, const float* __restrict__ shift, const float* __restrict__ scale, bf16_t* __restrict__ dst, int lane) {
;     float ss = 0.f;
; #pragma unroll
;     for (int j = 0; j < 4; ++j) ss += v[j][0] * v[j][0] + v[j][1] * v[j][1] + v[j][2] * v[j][2] + v[j][3] * v[j][3];
;     ss = wave_sum(ss);
;     const float rstd = rsqrtf(ss * (1.f / 1024.f) + 1e-6f);
; #pragma unroll
;     for (int j = 0; j < 4; ++j) {
;         const int c4 = lane + 64 * j;
;         const f32x4 g4 = ((const f32x4*)g)[c4], sh = ((const f32x4*)shift)[c4], sc = ((const f32x4*)scale)[c4];
;         f32x4 h = (v[j] * rstd) * g4; h = h * (sc + 1.f) + sh;
;         store_bf4(dst + c4 * 4, h);
;     }
; }
; __device__ __forceinline__ void phase1(const Params& P) {
;     const int lane = threadIdx.x & 63, w = threadIdx.x >> 6;
;     const float* mod = (const float*)(P.ws + OFF_MOD);
;     bf16_t* H = (bf16_t*)(P.ws + OFF_H);
;     {
;         const int stride = gridDim.x * 8;
;         int row = blockIdx.x * 8 + w;
;         f32x4 vn[4];
;         if (row < NT) { const float* src = row < NL ? P.in[0] + (size_t)row * 1024 : P.in[2] + (size_t)(row - NL) * 1024;
; #pragma unroll
;             for (int j = 0; j < 4; ++j) vn[j] = ((const f32x4*)src)[lane + 64 * j]; }
;         while (row < NT) {
;             f32x4 v[4];
; #pragma unroll
;             for (int j = 0; j < 4; ++j) v[j] = vn[j];
;             const int nrow = row + stride;
;             if (nrow < NT) { const float* src = nrow < NL ? P.in[0] + (size_t)nrow * 1024 : P.in[2] + (size_t)(nrow - NL) * 1024;
; #pragma unroll
;                 for (int j = 0; j < 4; ++j) vn[j] = ((const f32x4*)src)[lane + 64 * j]; }
;             const int mr = row < NL ? (row >> 13) : 4;
;             norm_row_pre(v, P.in[6], mod + mr * 9216 + 0, mod + mr * 9216 + 1024, H + (size_t)row * 1024, lane);
.LBB0_131:
	s_cmp_lt_i32 s70, 2
	s_cselect_b64 s[0:1], -1, 0
	s_cmp_gt_i32 s71, 1
	s_cselect_b64 s[2:3], -1, 0
	s_and_b64 s[0:1], s[0:1], s[2:3]
	s_andn2_b64 vcc, exec, s[0:1]
	v_and_b32_e32 v170, 63, v168
	v_lshrrev_b32_e32 v171, 6, v168
	s_cbranch_vccnz .LBB0_269
	s_add_u32 s2, s68, 0x5188000
	v_lshl_add_u32 v36, s33, 3, v171
	s_mov_b32 s18, 0x8400
	s_addc_u32 s3, s69, 0
	v_cmp_gt_i32_e32 vcc, s18, v36
	v_lshlrev_b32_e32 v32, 4, v170
	s_and_saveexec_b64 s[4:5], vcc
	s_cbranch_execz .LBB0_139
	v_readfirstlane_b32 s20, v171
	v_lshlrev_b32_e32 v33, 3, v170
	s_nop 2
	s_lshl_b32 s10, s33, 3
	s_add_u32 s20, s20, s10
	s_lshl_b32 s10, s20, 12
	s_add_u32 s6, s36, s10
	s_addc_u32 s7, s37, 0
	s_lshl_b32 s10, s20, 11
	s_add_u32 s8, s68, s10
	s_addc_u32 s9, s69, 0
	s_add_u32 s8, s8, 0x52bd000
	s_addc_u32 s9, s9, 0
	s_cmpk_lt_u32 s20, 0x400
	s_cbranch_scc1 .Lp1n17_start
	global_load_dwordx4 v[48:51], v32, s[48:49]
	global_load_dwordx4 v[52:55], v32, s[48:49] offset:1024
	global_load_dwordx4 v[56:59], v32, s[48:49] offset:2048
	global_load_dwordx4 v[60:63], v32, s[48:49] offset:3072
	s_mov_b32 s10, 0
	s_add_u32 s12, s2, s10
	s_addc_u32 s13, s3, 0
	s_add_u32 s14, s12, 0x1000
	s_addc_u32 s15, s13, 0
	global_load_dwordx4 v[80:83], v32, s[12:13]
	global_load_dwordx4 v[84:87], v32, s[12:13] offset:1024
	global_load_dwordx4 v[88:91], v32, s[12:13] offset:2048
	global_load_dwordx4 v[92:95], v32, s[12:13] offset:3072
	global_load_dwordx4 v[64:67], v32, s[14:15]
	global_load_dwordx4 v[68:71], v32, s[14:15] offset:1024
	global_load_dwordx4 v[72:75], v32, s[14:15] offset:2048
	global_load_dwordx4 v[76:79], v32, s[14:15] offset:3072
	global_load_dwordx4 v[112:115], v32, s[6:7]
	global_load_dwordx4 v[116:119], v32, s[6:7] offset:1024
	global_load_dwordx4 v[120:123], v32, s[6:7] offset:2048
	global_load_dwordx4 v[124:127], v32, s[6:7] offset:3072
	s_add_u32 s6, s6, 0x800000
	s_addc_u32 s7, s7, 0
	global_load_dwordx4 v[128:131], v32, s[6:7]
	global_load_dwordx4 v[132:135], v32, s[6:7] offset:1024
	global_load_dwordx4 v[136:139], v32, s[6:7] offset:2048
	global_load_dwordx4 v[140:143], v32, s[6:7] offset:3072
	s_add_u32 s6, s6, 0x800000
	s_addc_u32 s7, s7, 0
	global_load_dwordx4 v[144:147], v32, s[6:7]
	global_load_dwordx4 v[148:151], v32, s[6:7] offset:1024
	global_load_dwordx4 v[152:155], v32, s[6:7] offset:2048
	global_load_dwordx4 v[156:159], v32, s[6:7] offset:3072
	s_waitcnt vmcnt(8)
	v_pk_add_f32 v[64:65], v[64:65], 1.0 op_sel_hi:[1,0]
	v_pk_add_f32 v[66:67], v[66:67], 1.0 op_sel_hi:[1,0]
	v_pk_add_f32 v[68:69], v[68:69], 1.0 op_sel_hi:[1,0]
	v_pk_add_f32 v[70:71], v[70:71], 1.0 op_sel_hi:[1,0]
	v_pk_add_f32 v[72:73], v[72:73], 1.0 op_sel_hi:[1,0]
	v_pk_add_f32 v[74:75], v[74:75], 1.0 op_sel_hi:[1,0]
	v_pk_add_f32 v[76:77], v[76:77], 1.0 op_sel_hi:[1,0]
	v_pk_add_f32 v[78:79], v[78:79], 1.0 op_sel_hi:[1,0]
	v_pk_mul_f32 v[96:97], v[112:113], v[112:113]
	v_pk_fma_f32 v[96:97], v[114:115], v[114:115], v[96:97]
	v_pk_fma_f32 v[96:97], v[116:117], v[116:117], v[96:97]
	v_pk_fma_f32 v[96:97], v[118:119], v[118:119], v[96:97]
	v_pk_fma_f32 v[96:97], v[120:121], v[120:121], v[96:97]
	v_pk_fma_f32 v[96:97], v[122:123], v[122:123], v[96:97]
	v_pk_fma_f32 v[96:97], v[124:125], v[124:125], v[96:97]
	v_pk_fma_f32 v[96:97], v[126:127], v[126:127], v[96:97]
	v_add_f32_e32 v96, v96, v97
	s_nop 1
	v_add_f32_dpp v97, v96, v96 quad_perm:[1,0,3,2] row_mask:0xf bank_mask:0xf
	s_nop 1
	v_add_f32_dpp v96, v97, v97 quad_perm:[2,3,0,1] row_mask:0xf bank_mask:0xf
	s_nop 1
	v_add_f32_dpp v97, v96, v96 row_half_mirror row_mask:0xf bank_mask:0xf
	s_nop 1
	v_add_f32_dpp v96, v97, v97 row_mirror row_mask:0xf bank_mask:0xf
	s_nop 1
	v_readlane_b32 s16, v96, 0
	v_readlane_b32 s17, v96, 16
	v_readlane_b32 s18, v96, 32
	v_readlane_b32 s19, v96, 48
	s_nop 1
	v_mov_b32_e32 v96, s16
	v_add_f32_e32 v96, s17, v96
	v_add_f32_e32 v96, s18, v96
	v_add_f32_e32 v96, s19, v96
	v_mov_b32_e32 v98, 0x358637bd
	v_fmamk_f32 v96, v96, 0x3a800000, v98
	v_rsq_f32_e32 v96, v96
	s_nop 0
	v_pk_mul_f32 v[112:113], v[112:113], v[96:97] op_sel_hi:[1,0]
	v_pk_mul_f32 v[114:115], v[114:115], v[96:97] op_sel_hi:[1,0]
	v_pk_mul_f32 v[116:117], v[116:117], v[96:97] op_sel_hi:[1,0]
	v_pk_mul_f32 v[118:119], v[118:119], v[96:97] op_sel_hi:[1,0]
	v_pk_mul_f32 v[120:121], v[120:121], v[96:97] op_sel_hi:[1,0]
	v_pk_mul_f32 v[122:123], v[122:123], v[96:97] op_sel_hi:[1,0]
	v_pk_mul_f32 v[124:125], v[124:125], v[96:97] op_sel_hi:[1,0]
	v_pk_mul_f32 v[126:127], v[126:127], v[96:97] op_sel_hi:[1,0]
	v_pk_mul_f32 v[112:113], v[48:49], v[112:113]
	v_pk_mul_f32 v[114:115], v[50:51], v[114:115]
	v_pk_mul_f32 v[116:117], v[52:53], v[116:117]
	v_pk_mul_f32 v[118:119], v[54:55], v[118:119]
	v_pk_mul_f32 v[120:121], v[56:57], v[120:121]
	v_pk_mul_f32 v[122:123], v[58:59], v[122:123]
	v_pk_mul_f32 v[124:125], v[60:61], v[124:125]
	v_pk_mul_f32 v[126:127], v[62:63], v[126:127]
	v_pk_fma_f32 v[112:113], v[64:65], v[112:113], v[80:81]
	v_pk_fma_f32 v[114:115], v[66:67], v[114:115], v[82:83]
	v_pk_fma_f32 v[116:117], v[68:69], v[116:117], v[84:85]
	v_pk_fma_f32 v[118:119], v[70:71], v[118:119], v[86:87]
	v_pk_fma_f32 v[120:121], v[72:73], v[120:121], v[88:89]
	v_pk_fma_f32 v[122:123], v[74:75], v[122:123], v[90:91]
	v_pk_fma_f32 v[124:125], v[76:77], v[124:125], v[92:93]
	v_pk_fma_f32 v[126:127], v[78:79], v[126:127], v[94:95]
	v_cvt_pk_bf16_f32 v100, v112, v113
	v_cvt_pk_bf16_f32 v101, v114, v115
	v_cvt_pk_bf16_f32 v102, v116, v117
	v_cvt_pk_bf16_f32 v103, v118, v119
	v_cvt_pk_bf16_f32 v104, v120, v121
	v_cvt_pk_bf16_f32 v105, v122, v123
	v_cvt_pk_bf16_f32 v106, v124, v125
	v_cvt_pk_bf16_f32 v107, v126, v127
	global_store_dwordx2 v33, v[100:101], s[8:9]
	global_store_dwordx2 v33, v[102:103], s[8:9] offset:512
	global_store_dwordx2 v33, v[104:105], s[8:9] offset:1024
	global_store_dwordx2 v33, v[106:107], s[8:9] offset:1536
	s_add_u32 s6, s6, 0x800000
	s_addc_u32 s7, s7, 0
	global_load_dwordx4 v[112:115], v32, s[6:7]
	global_load_dwordx4 v[116:119], v32, s[6:7] offset:1024
	global_load_dwordx4 v[120:123], v32, s[6:7] offset:2048
	global_load_dwordx4 v[124:127], v32, s[6:7] offset:3072
	s_waitcnt vmcnt(12)
; __device__ __forceinline__ void store_bf4(bf16_t* p, f32x4 v) { uint2 o; o.x = pk2(v[0], v[1]); o.y = pk2(v[2], v[3]); *(uint2*)p = o; }
; __device__ __forceinline__ void norm_row_pre(const f32x4 (&v)[4], const float* __restrict__ g, const float* __restrict__ shift, const float* __restrict__ scale, bf16_t* __restrict__ dst, int lane) {
;     float ss = 0.f;
; #pragma unroll
;     for (int j = 0; j < 4; ++j) ss += v[j][0] * v[j][0] + v[j][1] * v[j][1] + v[j][2] * v[j][2] + v[j][3] * v[j][3];
;     ss = wave_sum(ss);
;     const float rstd = rsqrtf(ss * (1.f / 1024.f) + 1e-6f);
; #pragma unroll
;     for (int j = 0; j < 4; ++j) {
;         const int c4 = lane + 64 * j;
;         const f32x4 g4 = ((const f32x4*)g)[c4], sh = ((const f32x4*)shift)[c4], sc = ((const f32x4*)scale)[c4];
;         f32x4 h = (v[j] * rstd) * g4; h = h * (sc + 1.f) + sh;
;         store_bf4(dst + c4 * 4, h);
;     }
; }
; __device__ __forceinline__ void phase1(const Params& P) {
;     ...
;         while (row < NT) {
;             f32x4 v[4];
; #pragma unroll
;             for (int j = 0; j < 4; ++j) v[j] = vn[j];
;             const int nrow = row + stride;
;             if (nrow < NT) { const float* src = nrow < NL ? P.in[0] + (size_t)nrow * 1024 : P.in[2] + (size_t)(nrow - NL) * 1024;
; #pragma unroll
;                 for (int j = 0; j < 4; ++j) vn[j] = ((const f32x4*)src)[lane + 64 * j]; }
;             const int mr = row < NL ? (row >> 13) : 4;
;             norm_row_pre(v, P.in[6], mod + mr * 9216 + 0, mod + mr * 9216 + 1024, H + (size_t)row * 1024, lane);
;             if (row >= NL) {
; #pragma unroll
;                 for (int j = 0; j < 4; ++j) ((f32x4*)((float*)(P.ws + OFF_E) + (size_t)(row - NL) * 1024))[lane + 64 * j] = v[j];
;             }
;             row = nrow;
;         }
	v_pk_mul_f32 v[96:97], v[128:129], v[128:129]
	v_pk_fma_f32 v[96:97], v[130:131], v[130:131], v[96:97]
	v_pk_fma_f32 v[96:97], v[132:133], v[132:133], v[96:97]
	v_pk_fma_f32 v[96:97], v[134:135], v[134:135], v[96:97]
	v_pk_fma_f32 v[96:97], v[136:137], v[136:137], v[96:97]
	v_pk_fma_f32 v[96:97], v[138:139], v[138:139], v[96:97]
	v_pk_fma_f32 v[96:97], v[140:141], v[140:141], v[96:97]
	v_pk_fma_f32 v[96:97], v[142:143], v[142:143], v[96:97]
	v_add_f32_e32 v96, v96, v97
	s_nop 1
	v_add_f32_dpp v97, v96, v96 quad_perm:[1,0,3,2] row_mask:0xf bank_mask:0xf
	s_nop 1
	v_add_f32_dpp v96, v97, v97 quad_perm:[2,3,0,1] row_mask:0xf bank_mask:0xf
	s_nop 1
	v_add_f32_dpp v97, v96, v96 row_half_mirror row_mask:0xf bank_mask:0xf
	s_nop 1
	v_add_f32_dpp v96, v97, v97 row_mirror row_mask:0xf bank_mask:0xf
	s_nop 1
	v_readlane_b32 s16, v96, 0
	v_readlane_b32 s17, v96, 16
	v_readlane_b32 s18, v96, 32
	v_readlane_b32 s19, v96, 48
	s_nop 1
	v_mov_b32_e32 v96, s16
	v_add_f32_e32 v96, s17, v96
	v_add_f32_e32 v96, s18, v96
	v_add_f32_e32 v96, s19, v96
	v_mov_b32_e32 v98, 0x358637bd
	v_fmamk_f32 v96, v96, 0x3a800000, v98
	v_rsq_f32_e32 v96, v96
	s_nop 0
	v_pk_mul_f32 v[128:129], v[128:129], v[96:97] op_sel_hi:[1,0]
	v_pk_mul_f32 v[130:131], v[130:131], v[96:97] op_sel_hi:[1,0]
	v_pk_mul_f32 v[132:133], v[132:133], v[96:97] op_sel_hi:[1,0]
	v_pk_mul_f32 v[134:135], v[134:135], v[96:97] op_sel_hi:[1,0]
	v_pk_mul_f32 v[136:137], v[136:137], v[96:97] op_sel_hi:[1,0]
	v_pk_mul_f32 v[138:139], v[138:139], v[96:97] op_sel_hi:[1,0]
	v_pk_mul_f32 v[140:141], v[140:141], v[96:97] op_sel_hi:[1,0]
	v_pk_mul_f32 v[142:143], v[142:143], v[96:97] op_sel_hi:[1,0]
	v_pk_mul_f32 v[128:129], v[48:49], v[128:129]
	v_pk_mul_f32 v[130:131], v[50:51], v[130:131]
	v_pk_mul_f32 v[132:133], v[52:53], v[132:133]
	v_pk_mul_f32 v[134:135], v[54:55], v[134:135]
	v_pk_mul_f32 v[136:137], v[56:57], v[136:137]
	v_pk_mul_f32 v[138:139], v[58:59], v[138:139]
	v_pk_mul_f32 v[140:141], v[60:61], v[140:141]
	v_pk_mul_f32 v[142:143], v[62:63], v[142:143]
	v_pk_fma_f32 v[128:129], v[64:65], v[128:129], v[80:81]
	v_pk_fma_f32 v[130:131], v[66:67], v[130:131], v[82:83]
	v_pk_fma_f32 v[132:133], v[68:69], v[132:133], v[84:85]
	v_pk_fma_f32 v[134:135], v[70:71], v[134:135], v[86:87]
	v_pk_fma_f32 v[136:137], v[72:73], v[136:137], v[88:89]
	v_pk_fma_f32 v[138:139], v[74:75], v[138:139], v[90:91]
	v_pk_fma_f32 v[140:141], v[76:77], v[140:141], v[92:93]
	v_pk_fma_f32 v[142:143], v[78:79], v[142:143], v[94:95]
	v_cvt_pk_bf16_f32 v100, v128, v129
	v_cvt_pk_bf16_f32 v101, v130, v131
	v_cvt_pk_bf16_f32 v102, v132, v133
	v_cvt_pk_bf16_f32 v103, v134, v135
	v_cvt_pk_bf16_f32 v104, v136, v137
	v_cvt_pk_bf16_f32 v105, v138, v139
	v_cvt_pk_bf16_f32 v106, v140, v141
	v_cvt_pk_bf16_f32 v107, v142, v143
	s_add_u32 s8, s8, 0x400000
	s_addc_u32 s9, s9, 0
	global_store_dwordx2 v33, v[100:101], s[8:9]
	global_store_dwordx2 v33, v[102:103], s[8:9] offset:512
	global_store_dwordx2 v33, v[104:105], s[8:9] offset:1024
	global_store_dwordx2 v33, v[106:107], s[8:9] offset:1536
	s_add_u32 s6, s6, 0x800000
	s_addc_u32 s7, s7, 0
	global_load_dwordx4 v[128:131], v32, s[6:7]
	global_load_dwordx4 v[132:135], v32, s[6:7] offset:1024
	global_load_dwordx4 v[136:139], v32, s[6:7] offset:2048
	global_load_dwordx4 v[140:143], v32, s[6:7] offset:3072
	s_mov_b32 s10, 36864
	s_add_u32 s12, s2, s10
	s_addc_u32 s13, s3, 0
	s_add_u32 s14, s12, 0x1000
	s_addc_u32 s15, s13, 0
	global_load_dwordx4 v[192:195], v32, s[12:13]
	global_load_dwordx4 v[196:199], v32, s[12:13] offset:1024
	global_load_dwordx4 v[200:203], v32, s[12:13] offset:2048
	global_load_dwordx4 v[204:207], v32, s[12:13] offset:3072
	global_load_dwordx4 v[176:179], v32, s[14:15]
	global_load_dwordx4 v[180:183], v32, s[14:15] offset:1024
	global_load_dwordx4 v[184:187], v32, s[14:15] offset:2048
	global_load_dwordx4 v[188:191], v32, s[14:15] offset:3072
	s_waitcnt vmcnt(24)
	v_pk_mul_f32 v[96:97], v[144:145], v[144:145]
	v_pk_fma_f32 v[96:97], v[146:147], v[146:147], v[96:97]
	v_pk_fma_f32 v[96:97], v[148:149], v[148:149], v[96:97]
	v_pk_fma_f32 v[96:97], v[150:151], v[150:151], v[96:97]
	v_pk_fma_f32 v[96:97], v[152:153], v[152:153], v[96:97]
	v_pk_fma_f32 v[96:97], v[154:155], v[154:155], v[96:97]
	v_pk_fma_f32 v[96:97], v[156:157], v[156:157], v[96:97]
	v_pk_fma_f32 v[96:97], v[158:159], v[158:159], v[96:97]
	v_add_f32_e32 v96, v96, v97
	s_nop 1
	v_add_f32_dpp v97, v96, v96 quad_perm:[1,0,3,2] row_mask:0xf bank_mask:0xf
	s_nop 1
	v_add_f32_dpp v96, v97, v97 quad_perm:[2,3,0,1] row_mask:0xf bank_mask:0xf
	s_nop 1
	v_add_f32_dpp v97, v96, v96 row_half_mirror row_mask:0xf bank_mask:0xf
	s_nop 1
	v_add_f32_dpp v96, v97, v97 row_mirror row_mask:0xf bank_mask:0xf
	s_nop 1
	v_readlane_b32 s16, v96, 0
	v_readlane_b32 s17, v96, 16
	v_readlane_b32 s18, v96, 32
	v_readlane_b32 s19, v96, 48
	s_nop 1
	v_mov_b32_e32 v96, s16
	v_add_f32_e32 v96, s17, v96
	v_add_f32_e32 v96, s18, v96
	v_add_f32_e32 v96, s19, v96
	v_mov_b32_e32 v98, 0x358637bd
	v_fmamk_f32 v96, v96, 0x3a800000, v98
	v_rsq_f32_e32 v96, v96
	s_nop 0
	v_pk_mul_f32 v[144:145], v[144:145], v[96:97] op_sel_hi:[1,0]
	v_pk_mul_f32 v[146:147], v[146:147], v[96:97] op_sel_hi:[1,0]
	v_pk_mul_f32 v[148:149], v[148:149], v[96:97] op_sel_hi:[1,0]
	v_pk_mul_f32 v[150:151], v[150:151], v[96:97] op_sel_hi:[1,0]
	v_pk_mul_f32 v[152:153], v[152:153], v[96:97] op_sel_hi:[1,0]
	v_pk_mul_f32 v[154:155], v[154:155], v[96:97] op_sel_hi:[1,0]
	v_pk_mul_f32 v[156:157], v[156:157], v[96:97] op_sel_hi:[1,0]
	v_pk_mul_f32 v[158:159], v[158:159], v[96:97] op_sel_hi:[1,0]
	v_pk_mul_f32 v[144:145], v[48:49], v[144:145]
	v_pk_mul_f32 v[146:147], v[50:51], v[146:147]
; __device__ __forceinline__ void store_bf4(bf16_t* p, f32x4 v) { uint2 o; o.x = pk2(v[0], v[1]); o.y = pk2(v[2], v[3]); *(uint2*)p = o; }
; __device__ __forceinline__ void norm_row_pre(const f32x4 (&v)[4], const float* __restrict__ g, const float* __restrict__ shift, const float* __restrict__ scale, bf16_t* __restrict__ dst, int lane) {
;     float ss = 0.f;
; #pragma unroll
;     for (int j = 0; j < 4; ++j) ss += v[j][0] * v[j][0] + v[j][1] * v[j][1] + v[j][2] * v[j][2] + v[j][3] * v[j][3];
;     ss = wave_sum(ss);
;     const float rstd = rsqrtf(ss * (1.f / 1024.f) + 1e-6f);
; #pragma unroll
;     for (int j = 0; j < 4; ++j) {
;         const int c4 = lane + 64 * j;
;         const f32x4 g4 = ((const f32x4*)g)[c4], sh = ((const f32x4*)shift)[c4], sc = ((const f32x4*)scale)[c4];
;         f32x4 h = (v[j] * rstd) * g4; h = h * (sc + 1.f) + sh;
;         store_bf4(dst + c4 * 4, h);
;     }
; }
; __device__ __forceinline__ void phase1(const Params& P) {
;     ...
;         while (row < NT) {
;             f32x4 v[4];
; #pragma unroll
;             for (int j = 0; j < 4; ++j) v[j] = vn[j];
;             const int nrow = row + stride;
;             if (nrow < NT) { const float* src = nrow < NL ? P.in[0] + (size_t)nrow * 1024 : P.in[2] + (size_t)(nrow - NL) * 1024;
; #pragma unroll
;                 for (int j = 0; j < 4; ++j) vn[j] = ((const f32x4*)src)[lane + 64 * j]; }
;             const int mr = row < NL ? (row >> 13) : 4;
;             norm_row_pre(v, P.in[6], mod + mr * 9216 + 0, mod + mr * 9216 + 1024, H + (size_t)row * 1024, lane);
;             if (row >= NL) {
; #pragma unroll
;                 for (int j = 0; j < 4; ++j) ((f32x4*)((float*)(P.ws + OFF_E) + (size_t)(row - NL) * 1024))[lane + 64 * j] = v[j];
;             }
;             row = nrow;
;         }
	v_pk_mul_f32 v[148:149], v[52:53], v[148:149]
	v_pk_mul_f32 v[150:151], v[54:55], v[150:151]
	v_pk_mul_f32 v[152:153], v[56:57], v[152:153]
	v_pk_mul_f32 v[154:155], v[58:59], v[154:155]
	v_pk_mul_f32 v[156:157], v[60:61], v[156:157]
	v_pk_mul_f32 v[158:159], v[62:63], v[158:159]
	v_pk_fma_f32 v[144:145], v[64:65], v[144:145], v[80:81]
	v_pk_fma_f32 v[146:147], v[66:67], v[146:147], v[82:83]
	v_pk_fma_f32 v[148:149], v[68:69], v[148:149], v[84:85]
	v_pk_fma_f32 v[150:151], v[70:71], v[150:151], v[86:87]
	v_pk_fma_f32 v[152:153], v[72:73], v[152:153], v[88:89]
	v_pk_fma_f32 v[154:155], v[74:75], v[154:155], v[90:91]
	v_pk_fma_f32 v[156:157], v[76:77], v[156:157], v[92:93]
	v_pk_fma_f32 v[158:159], v[78:79], v[158:159], v[94:95]
	v_cvt_pk_bf16_f32 v100, v144, v145
	v_cvt_pk_bf16_f32 v101, v146, v147
	v_cvt_pk_bf16_f32 v102, v148, v149
	v_cvt_pk_bf16_f32 v103, v150, v151
	v_cvt_pk_bf16_f32 v104, v152, v153
	v_cvt_pk_bf16_f32 v105, v154, v155
	v_cvt_pk_bf16_f32 v106, v156, v157
	v_cvt_pk_bf16_f32 v107, v158, v159
	s_add_u32 s8, s8, 0x400000
	s_addc_u32 s9, s9, 0
	global_store_dwordx2 v33, v[100:101], s[8:9]
	global_store_dwordx2 v33, v[102:103], s[8:9] offset:512
	global_store_dwordx2 v33, v[104:105], s[8:9] offset:1024
	global_store_dwordx2 v33, v[106:107], s[8:9] offset:1536
	s_add_u32 s6, s6, 0x800000
	s_addc_u32 s7, s7, 0
	global_load_dwordx4 v[144:147], v32, s[6:7]
	global_load_dwordx4 v[148:151], v32, s[6:7] offset:1024
	global_load_dwordx4 v[152:155], v32, s[6:7] offset:2048
	global_load_dwordx4 v[156:159], v32, s[6:7] offset:3072
	s_waitcnt vmcnt(24)
	v_pk_mul_f32 v[96:97], v[112:113], v[112:113]
	v_pk_fma_f32 v[96:97], v[114:115], v[114:115], v[96:97]
	v_pk_fma_f32 v[96:97], v[116:117], v[116:117], v[96:97]
	v_pk_fma_f32 v[96:97], v[118:119], v[118:119], v[96:97]
	v_pk_fma_f32 v[96:97], v[120:121], v[120:121], v[96:97]
	v_pk_fma_f32 v[96:97], v[122:123], v[122:123], v[96:97]
	v_pk_fma_f32 v[96:97], v[124:125], v[124:125], v[96:97]
	v_pk_fma_f32 v[96:97], v[126:127], v[126:127], v[96:97]
	v_add_f32_e32 v96, v96, v97
	s_nop 1
	v_add_f32_dpp v97, v96, v96 quad_perm:[1,0,3,2] row_mask:0xf bank_mask:0xf
	s_nop 1
	v_add_f32_dpp v96, v97, v97 quad_perm:[2,3,0,1] row_mask:0xf bank_mask:0xf
	s_nop 1
	v_add_f32_dpp v97, v96, v96 row_half_mirror row_mask:0xf bank_mask:0xf
	s_nop 1
	v_add_f32_dpp v96, v97, v97 row_mirror row_mask:0xf bank_mask:0xf
	s_nop 1
	v_readlane_b32 s16, v96, 0
	v_readlane_b32 s17, v96, 16
	v_readlane_b32 s18, v96, 32
	v_readlane_b32 s19, v96, 48
	s_nop 1
	v_mov_b32_e32 v96, s16
	v_add_f32_e32 v96, s17, v96
	v_add_f32_e32 v96, s18, v96
	v_add_f32_e32 v96, s19, v96
	v_mov_b32_e32 v98, 0x358637bd
	v_fmamk_f32 v96, v96, 0x3a800000, v98
	v_rsq_f32_e32 v96, v96
	s_nop 0
	v_pk_mul_f32 v[112:113], v[112:113], v[96:97] op_sel_hi:[1,0]
	v_pk_mul_f32 v[114:115], v[114:115], v[96:97] op_sel_hi:[1,0]
	v_pk_mul_f32 v[116:117], v[116:117], v[96:97] op_sel_hi:[1,0]
	v_pk_mul_f32 v[118:119], v[118:119], v[96:97] op_sel_hi:[1,0]
	v_pk_mul_f32 v[120:121], v[120:121], v[96:97] op_sel_hi:[1,0]
	v_pk_mul_f32 v[122:123], v[122:123], v[96:97] op_sel_hi:[1,0]
	v_pk_mul_f32 v[124:125], v[124:125], v[96:97] op_sel_hi:[1,0]
	v_pk_mul_f32 v[126:127], v[126:127], v[96:97] op_sel_hi:[1,0]
	v_pk_mul_f32 v[112:113], v[48:49], v[112:113]
	v_pk_mul_f32 v[114:115], v[50:51], v[114:115]
	v_pk_mul_f32 v[116:117], v[52:53], v[116:117]
	v_pk_mul_f32 v[118:119], v[54:55], v[118:119]
	v_pk_mul_f32 v[120:121], v[56:57], v[120:121]
	v_pk_mul_f32 v[122:123], v[58:59], v[122:123]
	v_pk_mul_f32 v[124:125], v[60:61], v[124:125]
	v_pk_mul_f32 v[126:127], v[62:63], v[126:127]
	v_pk_fma_f32 v[112:113], v[64:65], v[112:113], v[80:81]
	v_pk_fma_f32 v[114:115], v[66:67], v[114:115], v[82:83]
	v_pk_fma_f32 v[116:117], v[68:69], v[116:117], v[84:85]
	v_pk_fma_f32 v[118:119], v[70:71], v[118:119], v[86:87]
	v_pk_fma_f32 v[120:121], v[72:73], v[120:121], v[88:89]
	v_pk_fma_f32 v[122:123], v[74:75], v[122:123], v[90:91]
	v_pk_fma_f32 v[124:125], v[76:77], v[124:125], v[92:93]
	v_pk_fma_f32 v[126:127], v[78:79], v[126:127], v[94:95]
	v_cvt_pk_bf16_f32 v100, v112, v113
	v_cvt_pk_bf16_f32 v101, v114, v115
	v_cvt_pk_bf16_f32 v102, v116, v117
	v_cvt_pk_bf16_f32 v103, v118, v119
	v_cvt_pk_bf16_f32 v104, v120, v121
	v_cvt_pk_bf16_f32 v105, v122, v123
	v_cvt_pk_bf16_f32 v106, v124, v125
	v_cvt_pk_bf16_f32 v107, v126, v127
	s_add_u32 s8, s8, 0x400000
	s_addc_u32 s9, s9, 0
	global_store_dwordx2 v33, v[100:101], s[8:9]
	global_store_dwordx2 v33, v[102:103], s[8:9] offset:512
	global_store_dwordx2 v33, v[104:105], s[8:9] offset:1024
	global_store_dwordx2 v33, v[106:107], s[8:9] offset:1536
	s_add_u32 s6, s6, 0x800000
	s_addc_u32 s7, s7, 0
	global_load_dwordx4 v[112:115], v32, s[6:7]
	global_load_dwordx4 v[116:119], v32, s[6:7] offset:1024
	global_load_dwordx4 v[120:123], v32, s[6:7] offset:2048
	global_load_dwordx4 v[124:127], v32, s[6:7] offset:3072
	s_waitcnt vmcnt(16)
; __device__ __forceinline__ void store_bf4(bf16_t* p, f32x4 v) { uint2 o; o.x = pk2(v[0], v[1]); o.y = pk2(v[2], v[3]); *(uint2*)p = o; }
; __device__ __forceinline__ void norm_row_pre(const f32x4 (&v)[4], const float* __restrict__ g, const float* __restrict__ shift, const float* __restrict__ scale, bf16_t* __restrict__ dst, int lane) {
;     float ss = 0.f;
; #pragma unroll
;     for (int j = 0; j < 4; ++j) ss += v[j][0] * v[j][0] + v[j][1] * v[j][1] + v[j][2] * v[j][2] + v[j][3] * v[j][3];
;     ss = wave_sum(ss);
;     const float rstd = rsqrtf(ss * (1.f / 1024.f) + 1e-6f);
; #pragma unroll
;     for (int j = 0; j < 4; ++j) {
;         const int c4 = lane + 64 * j;
;         const f32x4 g4 = ((const f32x4*)g)[c4], sh = ((const f32x4*)shift)[c4], sc = ((const f32x4*)scale)[c4];
;         f32x4 h = (v[j] * rstd) * g4; h = h * (sc + 1.f) + sh;
;         store_bf4(dst + c4 * 4, h);
;     }
; }
; __device__ __forceinline__ void phase1(const Params& P) {
;     ...
;         while (row < NT) {
;             f32x4 v[4];
; #pragma unroll
;             for (int j = 0; j < 4; ++j) v[j] = vn[j];
;             const int nrow = row + stride;
;             if (nrow < NT) { const float* src = nrow < NL ? P.in[0] + (size_t)nrow * 1024 : P.in[2] + (size_t)(nrow - NL) * 1024;
; #pragma unroll
;                 for (int j = 0; j < 4; ++j) vn[j] = ((const f32x4*)src)[lane + 64 * j]; }
;             const int mr = row < NL ? (row >> 13) : 4;
;             norm_row_pre(v, P.in[6], mod + mr * 9216 + 0, mod + mr * 9216 + 1024, H + (size_t)row * 1024, lane);
;             if (row >= NL) {
; #pragma unroll
;                 for (int j = 0; j < 4; ++j) ((f32x4*)((float*)(P.ws + OFF_E) + (size_t)(row - NL) * 1024))[lane + 64 * j] = v[j];
;             }
;             row = nrow;
;         }
	v_pk_add_f32 v[176:177], v[176:177], 1.0 op_sel_hi:[1,0]
	v_pk_add_f32 v[178:179], v[178:179], 1.0 op_sel_hi:[1,0]
	v_pk_add_f32 v[180:181], v[180:181], 1.0 op_sel_hi:[1,0]
	v_pk_add_f32 v[182:183], v[182:183], 1.0 op_sel_hi:[1,0]
	v_pk_add_f32 v[184:185], v[184:185], 1.0 op_sel_hi:[1,0]
	v_pk_add_f32 v[186:187], v[186:187], 1.0 op_sel_hi:[1,0]
	v_pk_add_f32 v[188:189], v[188:189], 1.0 op_sel_hi:[1,0]
	v_pk_add_f32 v[190:191], v[190:191], 1.0 op_sel_hi:[1,0]
	v_pk_mul_f32 v[96:97], v[128:129], v[128:129]
	v_pk_fma_f32 v[96:97], v[130:131], v[130:131], v[96:97]
	v_pk_fma_f32 v[96:97], v[132:133], v[132:133], v[96:97]
	v_pk_fma_f32 v[96:97], v[134:135], v[134:135], v[96:97]
	v_pk_fma_f32 v[96:97], v[136:137], v[136:137], v[96:97]
	v_pk_fma_f32 v[96:97], v[138:139], v[138:139], v[96:97]
	v_pk_fma_f32 v[96:97], v[140:141], v[140:141], v[96:97]
	v_pk_fma_f32 v[96:97], v[142:143], v[142:143], v[96:97]
	v_add_f32_e32 v96, v96, v97
	s_nop 1
	v_add_f32_dpp v97, v96, v96 quad_perm:[1,0,3,2] row_mask:0xf bank_mask:0xf
	s_nop 1
	v_add_f32_dpp v96, v97, v97 quad_perm:[2,3,0,1] row_mask:0xf bank_mask:0xf
	s_nop 1
	v_add_f32_dpp v97, v96, v96 row_half_mirror row_mask:0xf bank_mask:0xf
	s_nop 1
	v_add_f32_dpp v96, v97, v97 row_mirror row_mask:0xf bank_mask:0xf
	s_nop 1
	v_readlane_b32 s16, v96, 0
	v_readlane_b32 s17, v96, 16
	v_readlane_b32 s18, v96, 32
	v_readlane_b32 s19, v96, 48
	s_nop 1
	v_mov_b32_e32 v96, s16
	v_add_f32_e32 v96, s17, v96
	v_add_f32_e32 v96, s18, v96
	v_add_f32_e32 v96, s19, v96
	v_mov_b32_e32 v98, 0x358637bd
	v_fmamk_f32 v96, v96, 0x3a800000, v98
	v_rsq_f32_e32 v96, v96
	s_nop 0
	v_pk_mul_f32 v[128:129], v[128:129], v[96:97] op_sel_hi:[1,0]
	v_pk_mul_f32 v[130:131], v[130:131], v[96:97] op_sel_hi:[1,0]
	v_pk_mul_f32 v[132:133], v[132:133], v[96:97] op_sel_hi:[1,0]
	v_pk_mul_f32 v[134:135], v[134:135], v[96:97] op_sel_hi:[1,0]
	v_pk_mul_f32 v[136:137], v[136:137], v[96:97] op_sel_hi:[1,0]
	v_pk_mul_f32 v[138:139], v[138:139], v[96:97] op_sel_hi:[1,0]
	v_pk_mul_f32 v[140:141], v[140:141], v[96:97] op_sel_hi:[1,0]
	v_pk_mul_f32 v[142:143], v[142:143], v[96:97] op_sel_hi:[1,0]
	v_pk_mul_f32 v[128:129], v[48:49], v[128:129]
	v_pk_mul_f32 v[130:131], v[50:51], v[130:131]
	v_pk_mul_f32 v[132:133], v[52:53], v[132:133]
	v_pk_mul_f32 v[134:135], v[54:55], v[134:135]
	v_pk_mul_f32 v[136:137], v[56:57], v[136:137]
	v_pk_mul_f32 v[138:139], v[58:59], v[138:139]
	v_pk_mul_f32 v[140:141], v[60:61], v[140:141]
	v_pk_mul_f32 v[142:143], v[62:63], v[142:143]
	v_pk_fma_f32 v[128:129], v[176:177], v[128:129], v[192:193]
	v_pk_fma_f32 v[130:131], v[178:179], v[130:131], v[194:195]
	v_pk_fma_f32 v[132:133], v[180:181], v[132:133], v[196:197]
	v_pk_fma_f32 v[134:135], v[182:183], v[134:135], v[198:199]
	v_pk_fma_f32 v[136:137], v[184:185], v[136:137], v[200:201]
	v_pk_fma_f32 v[138:139], v[186:187], v[138:139], v[202:203]
	v_pk_fma_f32 v[140:141], v[188:189], v[140:141], v[204:205]
	v_pk_fma_f32 v[142:143], v[190:191], v[142:143], v[206:207]
	v_cvt_pk_bf16_f32 v100, v128, v129
	v_cvt_pk_bf16_f32 v101, v130, v131
	v_cvt_pk_bf16_f32 v102, v132, v133
	v_cvt_pk_bf16_f32 v103, v134, v135
	v_cvt_pk_bf16_f32 v104, v136, v137
	v_cvt_pk_bf16_f32 v105, v138, v139
	v_cvt_pk_bf16_f32 v106, v140, v141
	v_cvt_pk_bf16_f32 v107, v142, v143
	s_add_u32 s8, s8, 0x400000
	s_addc_u32 s9, s9, 0
	global_store_dwordx2 v33, v[100:101], s[8:9]
	global_store_dwordx2 v33, v[102:103], s[8:9] offset:512
	global_store_dwordx2 v33, v[104:105], s[8:9] offset:1024
	global_store_dwordx2 v33, v[106:107], s[8:9] offset:1536
	s_add_u32 s6, s6, 0x800000
	s_addc_u32 s7, s7, 0
	global_load_dwordx4 v[128:131], v32, s[6:7]
	global_load_dwordx4 v[132:135], v32, s[6:7] offset:1024
	global_load_dwordx4 v[136:139], v32, s[6:7] offset:2048
	global_load_dwordx4 v[140:143], v32, s[6:7] offset:3072
	s_waitcnt vmcnt(16)
	v_pk_mul_f32 v[96:97], v[144:145], v[144:145]
	v_pk_fma_f32 v[96:97], v[146:147], v[146:147], v[96:97]
	v_pk_fma_f32 v[96:97], v[148:149], v[148:149], v[96:97]
	v_pk_fma_f32 v[96:97], v[150:151], v[150:151], v[96:97]
	v_pk_fma_f32 v[96:97], v[152:153], v[152:153], v[96:97]
	v_pk_fma_f32 v[96:97], v[154:155], v[154:155], v[96:97]
	v_pk_fma_f32 v[96:97], v[156:157], v[156:157], v[96:97]
	v_pk_fma_f32 v[96:97], v[158:159], v[158:159], v[96:97]
	v_add_f32_e32 v96, v96, v97
	s_nop 1
	v_add_f32_dpp v97, v96, v96 quad_perm:[1,0,3,2] row_mask:0xf bank_mask:0xf
	s_nop 1
	v_add_f32_dpp v96, v97, v97 quad_perm:[2,3,0,1] row_mask:0xf bank_mask:0xf
	s_nop 1
	v_add_f32_dpp v97, v96, v96 row_half_mirror row_mask:0xf bank_mask:0xf
	s_nop 1
	v_add_f32_dpp v96, v97, v97 row_mirror row_mask:0xf bank_mask:0xf
	s_nop 1
	v_readlane_b32 s16, v96, 0
	v_readlane_b32 s17, v96, 16
	v_readlane_b32 s18, v96, 32
	v_readlane_b32 s19, v96, 48
	s_nop 1
	v_mov_b32_e32 v96, s16
	v_add_f32_e32 v96, s17, v96
	v_add_f32_e32 v96, s18, v96
	v_add_f32_e32 v96, s19, v96
	v_mov_b32_e32 v98, 0x358637bd
	v_fmamk_f32 v96, v96, 0x3a800000, v98
	v_rsq_f32_e32 v96, v96
	s_nop 0
	v_pk_mul_f32 v[144:145], v[144:145], v[96:97] op_sel_hi:[1,0]
	v_pk_mul_f32 v[146:147], v[146:147], v[96:97] op_sel_hi:[1,0]
	v_pk_mul_f32 v[148:149], v[148:149], v[96:97] op_sel_hi:[1,0]
	v_pk_mul_f32 v[150:151], v[150:151], v[96:97] op_sel_hi:[1,0]
	v_pk_mul_f32 v[152:153], v[152:153], v[96:97] op_sel_hi:[1,0]
	v_pk_mul_f32 v[154:155], v[154:155], v[96:97] op_sel_hi:[1,0]
	v_pk_mul_f32 v[156:157], v[156:157], v[96:97] op_sel_hi:[1,0]
	v_pk_mul_f32 v[158:159], v[158:159], v[96:97] op_sel_hi:[1,0]
	v_pk_mul_f32 v[144:145], v[48:49], v[144:145]
	v_pk_mul_f32 v[146:147], v[50:51], v[146:147]
	v_pk_mul_f32 v[148:149], v[52:53], v[148:149]
; __device__ __forceinline__ void store_bf4(bf16_t* p, f32x4 v) { uint2 o; o.x = pk2(v[0], v[1]); o.y = pk2(v[2], v[3]); *(uint2*)p = o; }
; __device__ __forceinline__ void norm_row_pre(const f32x4 (&v)[4], const float* __restrict__ g, const float* __restrict__ shift, const float* __restrict__ scale, bf16_t* __restrict__ dst, int lane) {
;     float ss = 0.f;
; #pragma unroll
;     for (int j = 0; j < 4; ++j) ss += v[j][0] * v[j][0] + v[j][1] * v[j][1] + v[j][2] * v[j][2] + v[j][3] * v[j][3];
;     ss = wave_sum(ss);
;     const float rstd = rsqrtf(ss * (1.f / 1024.f) + 1e-6f);
; #pragma unroll
;     for (int j = 0; j < 4; ++j) {
;         const int c4 = lane + 64 * j;
;         const f32x4 g4 = ((const f32x4*)g)[c4], sh = ((const f32x4*)shift)[c4], sc = ((const f32x4*)scale)[c4];
;         f32x4 h = (v[j] * rstd) * g4; h = h * (sc + 1.f) + sh;
;         store_bf4(dst + c4 * 4, h);
;     }
; }
; __device__ __forceinline__ void phase1(const Params& P) {
;     ...
;         while (row < NT) {
;             f32x4 v[4];
; #pragma unroll
;             for (int j = 0; j < 4; ++j) v[j] = vn[j];
;             const int nrow = row + stride;
;             if (nrow < NT) { const float* src = nrow < NL ? P.in[0] + (size_t)nrow * 1024 : P.in[2] + (size_t)(nrow - NL) * 1024;
; #pragma unroll
;                 for (int j = 0; j < 4; ++j) vn[j] = ((const f32x4*)src)[lane + 64 * j]; }
;             const int mr = row < NL ? (row >> 13) : 4;
;             norm_row_pre(v, P.in[6], mod + mr * 9216 + 0, mod + mr * 9216 + 1024, H + (size_t)row * 1024, lane);
;             if (row >= NL) {
; #pragma unroll
;                 for (int j = 0; j < 4; ++j) ((f32x4*)((float*)(P.ws + OFF_E) + (size_t)(row - NL) * 1024))[lane + 64 * j] = v[j];
;             }
;             row = nrow;
;         }
	v_pk_mul_f32 v[150:151], v[54:55], v[150:151]
	v_pk_mul_f32 v[152:153], v[56:57], v[152:153]
	v_pk_mul_f32 v[154:155], v[58:59], v[154:155]
	v_pk_mul_f32 v[156:157], v[60:61], v[156:157]
	v_pk_mul_f32 v[158:159], v[62:63], v[158:159]
	v_pk_fma_f32 v[144:145], v[176:177], v[144:145], v[192:193]
	v_pk_fma_f32 v[146:147], v[178:179], v[146:147], v[194:195]
	v_pk_fma_f32 v[148:149], v[180:181], v[148:149], v[196:197]
	v_pk_fma_f32 v[150:151], v[182:183], v[150:151], v[198:199]
	v_pk_fma_f32 v[152:153], v[184:185], v[152:153], v[200:201]
	v_pk_fma_f32 v[154:155], v[186:187], v[154:155], v[202:203]
	v_pk_fma_f32 v[156:157], v[188:189], v[156:157], v[204:205]
	v_pk_fma_f32 v[158:159], v[190:191], v[158:159], v[206:207]
	v_cvt_pk_bf16_f32 v100, v144, v145
	v_cvt_pk_bf16_f32 v101, v146, v147
	v_cvt_pk_bf16_f32 v102, v148, v149
	v_cvt_pk_bf16_f32 v103, v150, v151
	v_cvt_pk_bf16_f32 v104, v152, v153
	v_cvt_pk_bf16_f32 v105, v154, v155
	v_cvt_pk_bf16_f32 v106, v156, v157
	v_cvt_pk_bf16_f32 v107, v158, v159
	s_add_u32 s8, s8, 0x400000
	s_addc_u32 s9, s9, 0
	global_store_dwordx2 v33, v[100:101], s[8:9]
	global_store_dwordx2 v33, v[102:103], s[8:9] offset:512
	global_store_dwordx2 v33, v[104:105], s[8:9] offset:1024
	global_store_dwordx2 v33, v[106:107], s[8:9] offset:1536
	s_add_u32 s6, s6, 0x800000
	s_addc_u32 s7, s7, 0
	global_load_dwordx4 v[144:147], v32, s[6:7]
	global_load_dwordx4 v[148:151], v32, s[6:7] offset:1024
	global_load_dwordx4 v[152:155], v32, s[6:7] offset:2048
	global_load_dwordx4 v[156:159], v32, s[6:7] offset:3072
	s_mov_b32 s10, 73728
	s_add_u32 s12, s2, s10
	s_addc_u32 s13, s3, 0
	s_add_u32 s14, s12, 0x1000
	s_addc_u32 s15, s13, 0
	global_load_dwordx4 v[80:83], v32, s[12:13]
	global_load_dwordx4 v[84:87], v32, s[12:13] offset:1024
	global_load_dwordx4 v[88:91], v32, s[12:13] offset:2048
	global_load_dwordx4 v[92:95], v32, s[12:13] offset:3072
	global_load_dwordx4 v[64:67], v32, s[14:15]
	global_load_dwordx4 v[68:71], v32, s[14:15] offset:1024
	global_load_dwordx4 v[72:75], v32, s[14:15] offset:2048
	global_load_dwordx4 v[76:79], v32, s[14:15] offset:3072
	s_waitcnt vmcnt(24)
	v_pk_mul_f32 v[96:97], v[112:113], v[112:113]
	v_pk_fma_f32 v[96:97], v[114:115], v[114:115], v[96:97]
	v_pk_fma_f32 v[96:97], v[116:117], v[116:117], v[96:97]
	v_pk_fma_f32 v[96:97], v[118:119], v[118:119], v[96:97]
	v_pk_fma_f32 v[96:97], v[120:121], v[120:121], v[96:97]
	v_pk_fma_f32 v[96:97], v[122:123], v[122:123], v[96:97]
	v_pk_fma_f32 v[96:97], v[124:125], v[124:125], v[96:97]
	v_pk_fma_f32 v[96:97], v[126:127], v[126:127], v[96:97]
	v_add_f32_e32 v96, v96, v97
	s_nop 1
	v_add_f32_dpp v97, v96, v96 quad_perm:[1,0,3,2] row_mask:0xf bank_mask:0xf
	s_nop 1
	v_add_f32_dpp v96, v97, v97 quad_perm:[2,3,0,1] row_mask:0xf bank_mask:0xf
	s_nop 1
	v_add_f32_dpp v97, v96, v96 row_half_mirror row_mask:0xf bank_mask:0xf
	s_nop 1
	v_add_f32_dpp v96, v97, v97 row_mirror row_mask:0xf bank_mask:0xf
	s_nop 1
	v_readlane_b32 s16, v96, 0
	v_readlane_b32 s17, v96, 16
	v_readlane_b32 s18, v96, 32
	v_readlane_b32 s19, v96, 48
	s_nop 1
	v_mov_b32_e32 v96, s16
	v_add_f32_e32 v96, s17, v96
	v_add_f32_e32 v96, s18, v96
	v_add_f32_e32 v96, s19, v96
	v_mov_b32_e32 v98, 0x358637bd
	v_fmamk_f32 v96, v96, 0x3a800000, v98
	v_rsq_f32_e32 v96, v96
	s_nop 0
	v_pk_mul_f32 v[112:113], v[112:113], v[96:97] op_sel_hi:[1,0]
	v_pk_mul_f32 v[114:115], v[114:115], v[96:97] op_sel_hi:[1,0]
	v_pk_mul_f32 v[116:117], v[116:117], v[96:97] op_sel_hi:[1,0]
	v_pk_mul_f32 v[118:119], v[118:119], v[96:97] op_sel_hi:[1,0]
	v_pk_mul_f32 v[120:121], v[120:121], v[96:97] op_sel_hi:[1,0]
	v_pk_mul_f32 v[122:123], v[122:123], v[96:97] op_sel_hi:[1,0]
	v_pk_mul_f32 v[124:125], v[124:125], v[96:97] op_sel_hi:[1,0]
	v_pk_mul_f32 v[126:127], v[126:127], v[96:97] op_sel_hi:[1,0]
	v_pk_mul_f32 v[112:113], v[48:49], v[112:113]
	v_pk_mul_f32 v[114:115], v[50:51], v[114:115]
	v_pk_mul_f32 v[116:117], v[52:53], v[116:117]
	v_pk_mul_f32 v[118:119], v[54:55], v[118:119]
	v_pk_mul_f32 v[120:121], v[56:57], v[120:121]
	v_pk_mul_f32 v[122:123], v[58:59], v[122:123]
	v_pk_mul_f32 v[124:125], v[60:61], v[124:125]
	v_pk_mul_f32 v[126:127], v[62:63], v[126:127]
	v_pk_fma_f32 v[112:113], v[176:177], v[112:113], v[192:193]
	v_pk_fma_f32 v[114:115], v[178:179], v[114:115], v[194:195]
	v_pk_fma_f32 v[116:117], v[180:181], v[116:117], v[196:197]
	v_pk_fma_f32 v[118:119], v[182:183], v[118:119], v[198:199]
	v_pk_fma_f32 v[120:121], v[184:185], v[120:121], v[200:201]
	v_pk_fma_f32 v[122:123], v[186:187], v[122:123], v[202:203]
	v_pk_fma_f32 v[124:125], v[188:189], v[124:125], v[204:205]
	v_pk_fma_f32 v[126:127], v[190:191], v[126:127], v[206:207]
	v_cvt_pk_bf16_f32 v100, v112, v113
	v_cvt_pk_bf16_f32 v101, v114, v115
	v_cvt_pk_bf16_f32 v102, v116, v117
	v_cvt_pk_bf16_f32 v103, v118, v119
	v_cvt_pk_bf16_f32 v104, v120, v121
	v_cvt_pk_bf16_f32 v105, v122, v123
	v_cvt_pk_bf16_f32 v106, v124, v125
	v_cvt_pk_bf16_f32 v107, v126, v127
	s_add_u32 s8, s8, 0x400000
	s_addc_u32 s9, s9, 0
	global_store_dwordx2 v33, v[100:101], s[8:9]
	global_store_dwordx2 v33, v[102:103], s[8:9] offset:512
	global_store_dwordx2 v33, v[104:105], s[8:9] offset:1024
	global_store_dwordx2 v33, v[106:107], s[8:9] offset:1536
	s_add_u32 s6, s6, 0x800000
	s_addc_u32 s7, s7, 0
	global_load_dwordx4 v[112:115], v32, s[6:7]
	global_load_dwordx4 v[116:119], v32, s[6:7] offset:1024
	global_load_dwordx4 v[120:123], v32, s[6:7] offset:2048
	global_load_dwordx4 v[124:127], v32, s[6:7] offset:3072
	s_waitcnt vmcnt(24)
; __device__ __forceinline__ void store_bf4(bf16_t* p, f32x4 v) { uint2 o; o.x = pk2(v[0], v[1]); o.y = pk2(v[2], v[3]); *(uint2*)p = o; }
; __device__ __forceinline__ void norm_row_pre(const f32x4 (&v)[4], const float* __restrict__ g, const float* __restrict__ shift, const float* __restrict__ scale, bf16_t* __restrict__ dst, int lane) {
;     float ss = 0.f;
; #pragma unroll
;     for (int j = 0; j < 4; ++j) ss += v[j][0] * v[j][0] + v[j][1] * v[j][1] + v[j][2] * v[j][2] + v[j][3] * v[j][3];
;     ss = wave_sum(ss);
;     const float rstd = rsqrtf(ss * (1.f / 1024.f) + 1e-6f);
; #pragma unroll
;     for (int j = 0; j < 4; ++j) {
;         const int c4 = lane + 64 * j;
;         const f32x4 g4 = ((const f32x4*)g)[c4], sh = ((const f32x4*)shift)[c4], sc = ((const f32x4*)scale)[c4];
;         f32x4 h = (v[j] * rstd) * g4; h = h * (sc + 1.f) + sh;
;         store_bf4(dst + c4 * 4, h);
;     }
; }
; __device__ __forceinline__ void phase1(const Params& P) {
;     ...
;         while (row < NT) {
;             f32x4 v[4];
; #pragma unroll
;             for (int j = 0; j < 4; ++j) v[j] = vn[j];
;             const int nrow = row + stride;
;             if (nrow < NT) { const float* src = nrow < NL ? P.in[0] + (size_t)nrow * 1024 : P.in[2] + (size_t)(nrow - NL) * 1024;
; #pragma unroll
;                 for (int j = 0; j < 4; ++j) vn[j] = ((const f32x4*)src)[lane + 64 * j]; }
;             const int mr = row < NL ? (row >> 13) : 4;
;             norm_row_pre(v, P.in[6], mod + mr * 9216 + 0, mod + mr * 9216 + 1024, H + (size_t)row * 1024, lane);
;             if (row >= NL) {
; #pragma unroll
;                 for (int j = 0; j < 4; ++j) ((f32x4*)((float*)(P.ws + OFF_E) + (size_t)(row - NL) * 1024))[lane + 64 * j] = v[j];
;             }
;             row = nrow;
;         }
	v_pk_mul_f32 v[96:97], v[128:129], v[128:129]
	v_pk_fma_f32 v[96:97], v[130:131], v[130:131], v[96:97]
	v_pk_fma_f32 v[96:97], v[132:133], v[132:133], v[96:97]
	v_pk_fma_f32 v[96:97], v[134:135], v[134:135], v[96:97]
	v_pk_fma_f32 v[96:97], v[136:137], v[136:137], v[96:97]
	v_pk_fma_f32 v[96:97], v[138:139], v[138:139], v[96:97]
	v_pk_fma_f32 v[96:97], v[140:141], v[140:141], v[96:97]
	v_pk_fma_f32 v[96:97], v[142:143], v[142:143], v[96:97]
	v_add_f32_e32 v96, v96, v97
	s_nop 1
	v_add_f32_dpp v97, v96, v96 quad_perm:[1,0,3,2] row_mask:0xf bank_mask:0xf
	s_nop 1
	v_add_f32_dpp v96, v97, v97 quad_perm:[2,3,0,1] row_mask:0xf bank_mask:0xf
	s_nop 1
	v_add_f32_dpp v97, v96, v96 row_half_mirror row_mask:0xf bank_mask:0xf
	s_nop 1
	v_add_f32_dpp v96, v97, v97 row_mirror row_mask:0xf bank_mask:0xf
	s_nop 1
	v_readlane_b32 s16, v96, 0
	v_readlane_b32 s17, v96, 16
	v_readlane_b32 s18, v96, 32
	v_readlane_b32 s19, v96, 48
	s_nop 1
	v_mov_b32_e32 v96, s16
	v_add_f32_e32 v96, s17, v96
	v_add_f32_e32 v96, s18, v96
	v_add_f32_e32 v96, s19, v96
	v_mov_b32_e32 v98, 0x358637bd
	v_fmamk_f32 v96, v96, 0x3a800000, v98
	v_rsq_f32_e32 v96, v96
	s_nop 0
	v_pk_mul_f32 v[128:129], v[128:129], v[96:97] op_sel_hi:[1,0]
	v_pk_mul_f32 v[130:131], v[130:131], v[96:97] op_sel_hi:[1,0]
	v_pk_mul_f32 v[132:133], v[132:133], v[96:97] op_sel_hi:[1,0]
	v_pk_mul_f32 v[134:135], v[134:135], v[96:97] op_sel_hi:[1,0]
	v_pk_mul_f32 v[136:137], v[136:137], v[96:97] op_sel_hi:[1,0]
	v_pk_mul_f32 v[138:139], v[138:139], v[96:97] op_sel_hi:[1,0]
	v_pk_mul_f32 v[140:141], v[140:141], v[96:97] op_sel_hi:[1,0]
	v_pk_mul_f32 v[142:143], v[142:143], v[96:97] op_sel_hi:[1,0]
	v_pk_mul_f32 v[128:129], v[48:49], v[128:129]
	v_pk_mul_f32 v[130:131], v[50:51], v[130:131]
	v_pk_mul_f32 v[132:133], v[52:53], v[132:133]
	v_pk_mul_f32 v[134:135], v[54:55], v[134:135]
	v_pk_mul_f32 v[136:137], v[56:57], v[136:137]
	v_pk_mul_f32 v[138:139], v[58:59], v[138:139]
	v_pk_mul_f32 v[140:141], v[60:61], v[140:141]
	v_pk_mul_f32 v[142:143], v[62:63], v[142:143]
	v_pk_fma_f32 v[128:129], v[176:177], v[128:129], v[192:193]
	v_pk_fma_f32 v[130:131], v[178:179], v[130:131], v[194:195]
	v_pk_fma_f32 v[132:133], v[180:181], v[132:133], v[196:197]
	v_pk_fma_f32 v[134:135], v[182:183], v[134:135], v[198:199]
	v_pk_fma_f32 v[136:137], v[184:185], v[136:137], v[200:201]
	v_pk_fma_f32 v[138:139], v[186:187], v[138:139], v[202:203]
	v_pk_fma_f32 v[140:141], v[188:189], v[140:141], v[204:205]
	v_pk_fma_f32 v[142:143], v[190:191], v[142:143], v[206:207]
	v_cvt_pk_bf16_f32 v100, v128, v129
	v_cvt_pk_bf16_f32 v101, v130, v131
	v_cvt_pk_bf16_f32 v102, v132, v133
	v_cvt_pk_bf16_f32 v103, v134, v135
	v_cvt_pk_bf16_f32 v104, v136, v137
	v_cvt_pk_bf16_f32 v105, v138, v139
	v_cvt_pk_bf16_f32 v106, v140, v141
	v_cvt_pk_bf16_f32 v107, v142, v143
	s_add_u32 s8, s8, 0x400000
	s_addc_u32 s9, s9, 0
	global_store_dwordx2 v33, v[100:101], s[8:9]
	global_store_dwordx2 v33, v[102:103], s[8:9] offset:512
	global_store_dwordx2 v33, v[104:105], s[8:9] offset:1024
	global_store_dwordx2 v33, v[106:107], s[8:9] offset:1536
	s_add_u32 s6, s6, 0x800000
	s_addc_u32 s7, s7, 0
	global_load_dwordx4 v[128:131], v32, s[6:7]
	global_load_dwordx4 v[132:135], v32, s[6:7] offset:1024
	global_load_dwordx4 v[136:139], v32, s[6:7] offset:2048
	global_load_dwordx4 v[140:143], v32, s[6:7] offset:3072
	s_waitcnt vmcnt(16)
	v_pk_add_f32 v[64:65], v[64:65], 1.0 op_sel_hi:[1,0]
	v_pk_add_f32 v[66:67], v[66:67], 1.0 op_sel_hi:[1,0]
	v_pk_add_f32 v[68:69], v[68:69], 1.0 op_sel_hi:[1,0]
	v_pk_add_f32 v[70:71], v[70:71], 1.0 op_sel_hi:[1,0]
	v_pk_add_f32 v[72:73], v[72:73], 1.0 op_sel_hi:[1,0]
	v_pk_add_f32 v[74:75], v[74:75], 1.0 op_sel_hi:[1,0]
	v_pk_add_f32 v[76:77], v[76:77], 1.0 op_sel_hi:[1,0]
	v_pk_add_f32 v[78:79], v[78:79], 1.0 op_sel_hi:[1,0]
	v_pk_mul_f32 v[96:97], v[144:145], v[144:145]
	v_pk_fma_f32 v[96:97], v[146:147], v[146:147], v[96:97]
	v_pk_fma_f32 v[96:97], v[148:149], v[148:149], v[96:97]
	v_pk_fma_f32 v[96:97], v[150:151], v[150:151], v[96:97]
	v_pk_fma_f32 v[96:97], v[152:153], v[152:153], v[96:97]
	v_pk_fma_f32 v[96:97], v[154:155], v[154:155], v[96:97]
	v_pk_fma_f32 v[96:97], v[156:157], v[156:157], v[96:97]
	v_pk_fma_f32 v[96:97], v[158:159], v[158:159], v[96:97]
	v_add_f32_e32 v96, v96, v97
	s_nop 1
	v_add_f32_dpp v97, v96, v96 quad_perm:[1,0,3,2] row_mask:0xf bank_mask:0xf
	s_nop 1
	v_add_f32_dpp v96, v97, v97 quad_perm:[2,3,0,1] row_mask:0xf bank_mask:0xf
	s_nop 1
	v_add_f32_dpp v97, v96, v96 row_half_mirror row_mask:0xf bank_mask:0xf
	s_nop 1
	v_add_f32_dpp v96, v97, v97 row_mirror row_mask:0xf bank_mask:0xf
	s_nop 1
	v_readlane_b32 s16, v96, 0
	v_readlane_b32 s17, v96, 16
	v_readlane_b32 s18, v96, 32
	v_readlane_b32 s19, v96, 48
	s_nop 1
	v_mov_b32_e32 v96, s16
	v_add_f32_e32 v96, s17, v96
	v_add_f32_e32 v96, s18, v96
	v_add_f32_e32 v96, s19, v96
	v_mov_b32_e32 v98, 0x358637bd
	v_fmamk_f32 v96, v96, 0x3a800000, v98
	v_rsq_f32_e32 v96, v96
	s_nop 0
	v_pk_mul_f32 v[144:145], v[144:145], v[96:97] op_sel_hi:[1,0]
	v_pk_mul_f32 v[146:147], v[146:147], v[96:97] op_sel_hi:[1,0]
	v_pk_mul_f32 v[148:149], v[148:149], v[96:97] op_sel_hi:[1,0]
	v_pk_mul_f32 v[150:151], v[150:151], v[96:97] op_sel_hi:[1,0]
	v_pk_mul_f32 v[152:153], v[152:153], v[96:97] op_sel_hi:[1,0]
	v_pk_mul_f32 v[154:155], v[154:155], v[96:97] op_sel_hi:[1,0]
	v_pk_mul_f32 v[156:157], v[156:157], v[96:97] op_sel_hi:[1,0]
	v_pk_mul_f32 v[158:159], v[158:159], v[96:97] op_sel_hi:[1,0]
	v_pk_mul_f32 v[144:145], v[48:49], v[144:145]
	v_pk_mul_f32 v[146:147], v[50:51], v[146:147]
	v_pk_mul_f32 v[148:149], v[52:53], v[148:149]
	v_pk_mul_f32 v[150:151], v[54:55], v[150:151]
; __device__ __forceinline__ void store_bf4(bf16_t* p, f32x4 v) { uint2 o; o.x = pk2(v[0], v[1]); o.y = pk2(v[2], v[3]); *(uint2*)p = o; }
; __device__ __forceinline__ void norm_row_pre(const f32x4 (&v)[4], const float* __restrict__ g, const float* __restrict__ shift, const float* __restrict__ scale, bf16_t* __restrict__ dst, int lane) {
;     float ss = 0.f;
; #pragma unroll
;     for (int j = 0; j < 4; ++j) ss += v[j][0] * v[j][0] + v[j][1] * v[j][1] + v[j][2] * v[j][2] + v[j][3] * v[j][3];
;     ss = wave_sum(ss);
;     const float rstd = rsqrtf(ss * (1.f / 1024.f) + 1e-6f);
; #pragma unroll
;     for (int j = 0; j < 4; ++j) {
;         const int c4 = lane + 64 * j;
;         const f32x4 g4 = ((const f32x4*)g)[c4], sh = ((const f32x4*)shift)[c4], sc = ((const f32x4*)scale)[c4];
;         f32x4 h = (v[j] * rstd) * g4; h = h * (sc + 1.f) + sh;
;         store_bf4(dst + c4 * 4, h);
;     }
; }
; __device__ __forceinline__ void phase1(const Params& P) {
;     ...
;         while (row < NT) {
;             f32x4 v[4];
; #pragma unroll
;             for (int j = 0; j < 4; ++j) v[j] = vn[j];
;             const int nrow = row + stride;
;             if (nrow < NT) { const float* src = nrow < NL ? P.in[0] + (size_t)nrow * 1024 : P.in[2] + (size_t)(nrow - NL) * 1024;
; #pragma unroll
;                 for (int j = 0; j < 4; ++j) vn[j] = ((const f32x4*)src)[lane + 64 * j]; }
;             const int mr = row < NL ? (row >> 13) : 4;
;             norm_row_pre(v, P.in[6], mod + mr * 9216 + 0, mod + mr * 9216 + 1024, H + (size_t)row * 1024, lane);
;             if (row >= NL) {
; #pragma unroll
;                 for (int j = 0; j < 4; ++j) ((f32x4*)((float*)(P.ws + OFF_E) + (size_t)(row - NL) * 1024))[lane + 64 * j] = v[j];
;             }
;             row = nrow;
;         }
	v_pk_mul_f32 v[152:153], v[56:57], v[152:153]
	v_pk_mul_f32 v[154:155], v[58:59], v[154:155]
	v_pk_mul_f32 v[156:157], v[60:61], v[156:157]
	v_pk_mul_f32 v[158:159], v[62:63], v[158:159]
	v_pk_fma_f32 v[144:145], v[64:65], v[144:145], v[80:81]
	v_pk_fma_f32 v[146:147], v[66:67], v[146:147], v[82:83]
	v_pk_fma_f32 v[148:149], v[68:69], v[148:149], v[84:85]
	v_pk_fma_f32 v[150:151], v[70:71], v[150:151], v[86:87]
	v_pk_fma_f32 v[152:153], v[72:73], v[152:153], v[88:89]
	v_pk_fma_f32 v[154:155], v[74:75], v[154:155], v[90:91]
	v_pk_fma_f32 v[156:157], v[76:77], v[156:157], v[92:93]
	v_pk_fma_f32 v[158:159], v[78:79], v[158:159], v[94:95]
	v_cvt_pk_bf16_f32 v100, v144, v145
	v_cvt_pk_bf16_f32 v101, v146, v147
	v_cvt_pk_bf16_f32 v102, v148, v149
	v_cvt_pk_bf16_f32 v103, v150, v151
	v_cvt_pk_bf16_f32 v104, v152, v153
	v_cvt_pk_bf16_f32 v105, v154, v155
	v_cvt_pk_bf16_f32 v106, v156, v157
	v_cvt_pk_bf16_f32 v107, v158, v159
	s_add_u32 s8, s8, 0x400000
	s_addc_u32 s9, s9, 0
	global_store_dwordx2 v33, v[100:101], s[8:9]
	global_store_dwordx2 v33, v[102:103], s[8:9] offset:512
	global_store_dwordx2 v33, v[104:105], s[8:9] offset:1024
	global_store_dwordx2 v33, v[106:107], s[8:9] offset:1536
	s_add_u32 s6, s6, 0x800000
	s_addc_u32 s7, s7, 0
	global_load_dwordx4 v[144:147], v32, s[6:7]
	global_load_dwordx4 v[148:151], v32, s[6:7] offset:1024
	global_load_dwordx4 v[152:155], v32, s[6:7] offset:2048
	global_load_dwordx4 v[156:159], v32, s[6:7] offset:3072
	s_waitcnt vmcnt(16)
	v_pk_mul_f32 v[96:97], v[112:113], v[112:113]
	v_pk_fma_f32 v[96:97], v[114:115], v[114:115], v[96:97]
	v_pk_fma_f32 v[96:97], v[116:117], v[116:117], v[96:97]
	v_pk_fma_f32 v[96:97], v[118:119], v[118:119], v[96:97]
	v_pk_fma_f32 v[96:97], v[120:121], v[120:121], v[96:97]
	v_pk_fma_f32 v[96:97], v[122:123], v[122:123], v[96:97]
	v_pk_fma_f32 v[96:97], v[124:125], v[124:125], v[96:97]
	v_pk_fma_f32 v[96:97], v[126:127], v[126:127], v[96:97]
	v_add_f32_e32 v96, v96, v97
	s_nop 1
	v_add_f32_dpp v97, v96, v96 quad_perm:[1,0,3,2] row_mask:0xf bank_mask:0xf
	s_nop 1
	v_add_f32_dpp v96, v97, v97 quad_perm:[2,3,0,1] row_mask:0xf bank_mask:0xf
	s_nop 1
	v_add_f32_dpp v97, v96, v96 row_half_mirror row_mask:0xf bank_mask:0xf
	s_nop 1
	v_add_f32_dpp v96, v97, v97 row_mirror row_mask:0xf bank_mask:0xf
	s_nop 1
	v_readlane_b32 s16, v96, 0
	v_readlane_b32 s17, v96, 16
	v_readlane_b32 s18, v96, 32
	v_readlane_b32 s19, v96, 48
	s_nop 1
	v_mov_b32_e32 v96, s16
	v_add_f32_e32 v96, s17, v96
	v_add_f32_e32 v96, s18, v96
	v_add_f32_e32 v96, s19, v96
	v_mov_b32_e32 v98, 0x358637bd
	v_fmamk_f32 v96, v96, 0x3a800000, v98
	v_rsq_f32_e32 v96, v96
	s_nop 0
	v_pk_mul_f32 v[112:113], v[112:113], v[96:97] op_sel_hi:[1,0]
	v_pk_mul_f32 v[114:115], v[114:115], v[96:97] op_sel_hi:[1,0]
	v_pk_mul_f32 v[116:117], v[116:117], v[96:97] op_sel_hi:[1,0]
	v_pk_mul_f32 v[118:119], v[118:119], v[96:97] op_sel_hi:[1,0]
	v_pk_mul_f32 v[120:121], v[120:121], v[96:97] op_sel_hi:[1,0]
	v_pk_mul_f32 v[122:123], v[122:123], v[96:97] op_sel_hi:[1,0]
	v_pk_mul_f32 v[124:125], v[124:125], v[96:97] op_sel_hi:[1,0]
	v_pk_mul_f32 v[126:127], v[126:127], v[96:97] op_sel_hi:[1,0]
	v_pk_mul_f32 v[112:113], v[48:49], v[112:113]
	v_pk_mul_f32 v[114:115], v[50:51], v[114:115]
	v_pk_mul_f32 v[116:117], v[52:53], v[116:117]
	v_pk_mul_f32 v[118:119], v[54:55], v[118:119]
	v_pk_mul_f32 v[120:121], v[56:57], v[120:121]
	v_pk_mul_f32 v[122:123], v[58:59], v[122:123]
	v_pk_mul_f32 v[124:125], v[60:61], v[124:125]
	v_pk_mul_f32 v[126:127], v[62:63], v[126:127]
	v_pk_fma_f32 v[112:113], v[64:65], v[112:113], v[80:81]
	v_pk_fma_f32 v[114:115], v[66:67], v[114:115], v[82:83]
	v_pk_fma_f32 v[116:117], v[68:69], v[116:117], v[84:85]
	v_pk_fma_f32 v[118:119], v[70:71], v[118:119], v[86:87]
	v_pk_fma_f32 v[120:121], v[72:73], v[120:121], v[88:89]
	v_pk_fma_f32 v[122:123], v[74:75], v[122:123], v[90:91]
	v_pk_fma_f32 v[124:125], v[76:77], v[124:125], v[92:93]
	v_pk_fma_f32 v[126:127], v[78:79], v[126:127], v[94:95]
	v_cvt_pk_bf16_f32 v100, v112, v113
	v_cvt_pk_bf16_f32 v101, v114, v115
	v_cvt_pk_bf16_f32 v102, v116, v117
	v_cvt_pk_bf16_f32 v103, v118, v119
	v_cvt_pk_bf16_f32 v104, v120, v121
	v_cvt_pk_bf16_f32 v105, v122, v123
	v_cvt_pk_bf16_f32 v106, v124, v125
	v_cvt_pk_bf16_f32 v107, v126, v127
	s_add_u32 s8, s8, 0x400000
	s_addc_u32 s9, s9, 0
	global_store_dwordx2 v33, v[100:101], s[8:9]
	global_store_dwordx2 v33, v[102:103], s[8:9] offset:512
	global_store_dwordx2 v33, v[104:105], s[8:9] offset:1024
	global_store_dwordx2 v33, v[106:107], s[8:9] offset:1536
	s_add_u32 s6, s6, 0x800000
	s_addc_u32 s7, s7, 0
	global_load_dwordx4 v[112:115], v32, s[6:7]
	global_load_dwordx4 v[116:119], v32, s[6:7] offset:1024
	global_load_dwordx4 v[120:123], v32, s[6:7] offset:2048
	global_load_dwordx4 v[124:127], v32, s[6:7] offset:3072
	s_mov_b32 s10, 110592
	s_add_u32 s12, s2, s10
	s_addc_u32 s13, s3, 0
	s_add_u32 s14, s12, 0x1000
	s_addc_u32 s15, s13, 0
	global_load_dwordx4 v[192:195], v32, s[12:13]
	global_load_dwordx4 v[196:199], v32, s[12:13] offset:1024
	global_load_dwordx4 v[200:203], v32, s[12:13] offset:2048
	global_load_dwordx4 v[204:207], v32, s[12:13] offset:3072
	global_load_dwordx4 v[176:179], v32, s[14:15]
	global_load_dwordx4 v[180:183], v32, s[14:15] offset:1024
	global_load_dwordx4 v[184:187], v32, s[14:15] offset:2048
	global_load_dwordx4 v[188:191], v32, s[14:15] offset:3072
	s_waitcnt vmcnt(24)
; __device__ __forceinline__ void store_bf4(bf16_t* p, f32x4 v) { uint2 o; o.x = pk2(v[0], v[1]); o.y = pk2(v[2], v[3]); *(uint2*)p = o; }
; __device__ __forceinline__ void norm_row_pre(const f32x4 (&v)[4], const float* __restrict__ g, const float* __restrict__ shift, const float* __restrict__ scale, bf16_t* __restrict__ dst, int lane) {
;     float ss = 0.f;
; #pragma unroll
;     for (int j = 0; j < 4; ++j) ss += v[j][0] * v[j][0] + v[j][1] * v[j][1] + v[j][2] * v[j][2] + v[j][3] * v[j][3];
;     ss = wave_sum(ss);
;     const float rstd = rsqrtf(ss * (1.f / 1024.f) + 1e-6f);
; #pragma unroll
;     for (int j = 0; j < 4; ++j) {
;         const int c4 = lane + 64 * j;
;         const f32x4 g4 = ((const f32x4*)g)[c4], sh = ((const f32x4*)shift)[c4], sc = ((const f32x4*)scale)[c4];
;         f32x4 h = (v[j] * rstd) * g4; h = h * (sc + 1.f) + sh;
;         store_bf4(dst + c4 * 4, h);
;     }
; }
; __device__ __forceinline__ void phase1(const Params& P) {
;     ...
;         while (row < NT) {
;             f32x4 v[4];
; #pragma unroll
;             for (int j = 0; j < 4; ++j) v[j] = vn[j];
;             const int nrow = row + stride;
;             if (nrow < NT) { const float* src = nrow < NL ? P.in[0] + (size_t)nrow * 1024 : P.in[2] + (size_t)(nrow - NL) * 1024;
; #pragma unroll
;                 for (int j = 0; j < 4; ++j) vn[j] = ((const f32x4*)src)[lane + 64 * j]; }
;             const int mr = row < NL ? (row >> 13) : 4;
;             norm_row_pre(v, P.in[6], mod + mr * 9216 + 0, mod + mr * 9216 + 1024, H + (size_t)row * 1024, lane);
;             if (row >= NL) {
; #pragma unroll
;                 for (int j = 0; j < 4; ++j) ((f32x4*)((float*)(P.ws + OFF_E) + (size_t)(row - NL) * 1024))[lane + 64 * j] = v[j];
;             }
;             row = nrow;
;         }
	v_pk_mul_f32 v[96:97], v[128:129], v[128:129]
	v_pk_fma_f32 v[96:97], v[130:131], v[130:131], v[96:97]
	v_pk_fma_f32 v[96:97], v[132:133], v[132:133], v[96:97]
	v_pk_fma_f32 v[96:97], v[134:135], v[134:135], v[96:97]
	v_pk_fma_f32 v[96:97], v[136:137], v[136:137], v[96:97]
	v_pk_fma_f32 v[96:97], v[138:139], v[138:139], v[96:97]
	v_pk_fma_f32 v[96:97], v[140:141], v[140:141], v[96:97]
	v_pk_fma_f32 v[96:97], v[142:143], v[142:143], v[96:97]
	v_add_f32_e32 v96, v96, v97
	s_nop 1
	v_add_f32_dpp v97, v96, v96 quad_perm:[1,0,3,2] row_mask:0xf bank_mask:0xf
	s_nop 1
	v_add_f32_dpp v96, v97, v97 quad_perm:[2,3,0,1] row_mask:0xf bank_mask:0xf
	s_nop 1
	v_add_f32_dpp v97, v96, v96 row_half_mirror row_mask:0xf bank_mask:0xf
	s_nop 1
	v_add_f32_dpp v96, v97, v97 row_mirror row_mask:0xf bank_mask:0xf
	s_nop 1
	v_readlane_b32 s16, v96, 0
	v_readlane_b32 s17, v96, 16
	v_readlane_b32 s18, v96, 32
	v_readlane_b32 s19, v96, 48
	s_nop 1
	v_mov_b32_e32 v96, s16
	v_add_f32_e32 v96, s17, v96
	v_add_f32_e32 v96, s18, v96
	v_add_f32_e32 v96, s19, v96
	v_mov_b32_e32 v98, 0x358637bd
	v_fmamk_f32 v96, v96, 0x3a800000, v98
	v_rsq_f32_e32 v96, v96
	s_nop 0
	v_pk_mul_f32 v[128:129], v[128:129], v[96:97] op_sel_hi:[1,0]
	v_pk_mul_f32 v[130:131], v[130:131], v[96:97] op_sel_hi:[1,0]
	v_pk_mul_f32 v[132:133], v[132:133], v[96:97] op_sel_hi:[1,0]
	v_pk_mul_f32 v[134:135], v[134:135], v[96:97] op_sel_hi:[1,0]
	v_pk_mul_f32 v[136:137], v[136:137], v[96:97] op_sel_hi:[1,0]
	v_pk_mul_f32 v[138:139], v[138:139], v[96:97] op_sel_hi:[1,0]
	v_pk_mul_f32 v[140:141], v[140:141], v[96:97] op_sel_hi:[1,0]
	v_pk_mul_f32 v[142:143], v[142:143], v[96:97] op_sel_hi:[1,0]
	v_pk_mul_f32 v[128:129], v[48:49], v[128:129]
	v_pk_mul_f32 v[130:131], v[50:51], v[130:131]
	v_pk_mul_f32 v[132:133], v[52:53], v[132:133]
	v_pk_mul_f32 v[134:135], v[54:55], v[134:135]
	v_pk_mul_f32 v[136:137], v[56:57], v[136:137]
	v_pk_mul_f32 v[138:139], v[58:59], v[138:139]
	v_pk_mul_f32 v[140:141], v[60:61], v[140:141]
	v_pk_mul_f32 v[142:143], v[62:63], v[142:143]
	v_pk_fma_f32 v[128:129], v[64:65], v[128:129], v[80:81]
	v_pk_fma_f32 v[130:131], v[66:67], v[130:131], v[82:83]
	v_pk_fma_f32 v[132:133], v[68:69], v[132:133], v[84:85]
	v_pk_fma_f32 v[134:135], v[70:71], v[134:135], v[86:87]
	v_pk_fma_f32 v[136:137], v[72:73], v[136:137], v[88:89]
	v_pk_fma_f32 v[138:139], v[74:75], v[138:139], v[90:91]
	v_pk_fma_f32 v[140:141], v[76:77], v[140:141], v[92:93]
	v_pk_fma_f32 v[142:143], v[78:79], v[142:143], v[94:95]
	v_cvt_pk_bf16_f32 v100, v128, v129
	v_cvt_pk_bf16_f32 v101, v130, v131
	v_cvt_pk_bf16_f32 v102, v132, v133
	v_cvt_pk_bf16_f32 v103, v134, v135
	v_cvt_pk_bf16_f32 v104, v136, v137
	v_cvt_pk_bf16_f32 v105, v138, v139
	v_cvt_pk_bf16_f32 v106, v140, v141
	v_cvt_pk_bf16_f32 v107, v142, v143
	s_add_u32 s8, s8, 0x400000
	s_addc_u32 s9, s9, 0
	global_store_dwordx2 v33, v[100:101], s[8:9]
	global_store_dwordx2 v33, v[102:103], s[8:9] offset:512
	global_store_dwordx2 v33, v[104:105], s[8:9] offset:1024
	global_store_dwordx2 v33, v[106:107], s[8:9] offset:1536
	s_add_u32 s6, s6, 0x800000
	s_addc_u32 s7, s7, 0
	global_load_dwordx4 v[128:131], v32, s[6:7]
	global_load_dwordx4 v[132:135], v32, s[6:7] offset:1024
	global_load_dwordx4 v[136:139], v32, s[6:7] offset:2048
	global_load_dwordx4 v[140:143], v32, s[6:7] offset:3072
	s_waitcnt vmcnt(24)
	v_pk_mul_f32 v[96:97], v[144:145], v[144:145]
	v_pk_fma_f32 v[96:97], v[146:147], v[146:147], v[96:97]
	v_pk_fma_f32 v[96:97], v[148:149], v[148:149], v[96:97]
	v_pk_fma_f32 v[96:97], v[150:151], v[150:151], v[96:97]
	v_pk_fma_f32 v[96:97], v[152:153], v[152:153], v[96:97]
	v_pk_fma_f32 v[96:97], v[154:155], v[154:155], v[96:97]
	v_pk_fma_f32 v[96:97], v[156:157], v[156:157], v[96:97]
	v_pk_fma_f32 v[96:97], v[158:159], v[158:159], v[96:97]
	v_add_f32_e32 v96, v96, v97
	s_nop 1
	v_add_f32_dpp v97, v96, v96 quad_perm:[1,0,3,2] row_mask:0xf bank_mask:0xf
	s_nop 1
	v_add_f32_dpp v96, v97, v97 quad_perm:[2,3,0,1] row_mask:0xf bank_mask:0xf
	s_nop 1
	v_add_f32_dpp v97, v96, v96 row_half_mirror row_mask:0xf bank_mask:0xf
	s_nop 1
	v_add_f32_dpp v96, v97, v97 row_mirror row_mask:0xf bank_mask:0xf
	s_nop 1
	v_readlane_b32 s16, v96, 0
	v_readlane_b32 s17, v96, 16
	v_readlane_b32 s18, v96, 32
	v_readlane_b32 s19, v96, 48
	s_nop 1
	v_mov_b32_e32 v96, s16
	v_add_f32_e32 v96, s17, v96
	v_add_f32_e32 v96, s18, v96
	v_add_f32_e32 v96, s19, v96
	v_mov_b32_e32 v98, 0x358637bd
	v_fmamk_f32 v96, v96, 0x3a800000, v98
	v_rsq_f32_e32 v96, v96
	s_nop 0
	v_pk_mul_f32 v[144:145], v[144:145], v[96:97] op_sel_hi:[1,0]
	v_pk_mul_f32 v[146:147], v[146:147], v[96:97] op_sel_hi:[1,0]
	v_pk_mul_f32 v[148:149], v[148:149], v[96:97] op_sel_hi:[1,0]
	v_pk_mul_f32 v[150:151], v[150:151], v[96:97] op_sel_hi:[1,0]
	v_pk_mul_f32 v[152:153], v[152:153], v[96:97] op_sel_hi:[1,0]
	v_pk_mul_f32 v[154:155], v[154:155], v[96:97] op_sel_hi:[1,0]
	v_pk_mul_f32 v[156:157], v[156:157], v[96:97] op_sel_hi:[1,0]
	v_pk_mul_f32 v[158:159], v[158:159], v[96:97] op_sel_hi:[1,0]
	v_pk_mul_f32 v[144:145], v[48:49], v[144:145]
	v_pk_mul_f32 v[146:147], v[50:51], v[146:147]
	v_pk_mul_f32 v[148:149], v[52:53], v[148:149]
	v_pk_mul_f32 v[150:151], v[54:55], v[150:151]
	v_pk_mul_f32 v[152:153], v[56:57], v[152:153]
	v_pk_mul_f32 v[154:155], v[58:59], v[154:155]
	v_pk_mul_f32 v[156:157], v[60:61], v[156:157]
	v_pk_mul_f32 v[158:159], v[62:63], v[158:159]
	v_pk_fma_f32 v[144:145], v[64:65], v[144:145], v[80:81]
	v_pk_fma_f32 v[146:147], v[66:67], v[146:147], v[82:83]
	v_pk_fma_f32 v[148:149], v[68:69], v[148:149], v[84:85]
	v_pk_fma_f32 v[150:151], v[70:71], v[150:151], v[86:87]
	v_pk_fma_f32 v[152:153], v[72:73], v[152:153], v[88:89]
	v_pk_fma_f32 v[154:155], v[74:75], v[154:155], v[90:91]
	v_pk_fma_f32 v[156:157], v[76:77], v[156:157], v[92:93]
	v_pk_fma_f32 v[158:159], v[78:79], v[158:159], v[94:95]
	v_cvt_pk_bf16_f32 v100, v144, v145
	v_cvt_pk_bf16_f32 v101, v146, v147
	v_cvt_pk_bf16_f32 v102, v148, v149
	v_cvt_pk_bf16_f32 v103, v150, v151
	v_cvt_pk_bf16_f32 v104, v152, v153
	v_cvt_pk_bf16_f32 v105, v154, v155
	v_cvt_pk_bf16_f32 v106, v156, v157
	v_cvt_pk_bf16_f32 v107, v158, v159
	s_add_u32 s8, s8, 0x400000
	s_addc_u32 s9, s9, 0
	global_store_dwordx2 v33, v[100:101], s[8:9]
	global_store_dwordx2 v33, v[102:103], s[8:9] offset:512
	global_store_dwordx2 v33, v[104:105], s[8:9] offset:1024
	global_store_dwordx2 v33, v[106:107], s[8:9] offset:1536
	s_add_u32 s6, s6, 0x800000
	s_addc_u32 s7, s7, 0
	global_load_dwordx4 v[144:147], v32, s[6:7]
	global_load_dwordx4 v[148:151], v32, s[6:7] offset:1024
	global_load_dwordx4 v[152:155], v32, s[6:7] offset:2048
	global_load_dwordx4 v[156:159], v32, s[6:7] offset:3072
	s_waitcnt vmcnt(16)
; __device__ __forceinline__ void store_bf4(bf16_t* p, f32x4 v) { uint2 o; o.x = pk2(v[0], v[1]); o.y = pk2(v[2], v[3]); *(uint2*)p = o; }
; __device__ __forceinline__ void norm_row_pre(const f32x4 (&v)[4], const float* __restrict__ g, const float* __restrict__ shift, const float* __restrict__ scale, bf16_t* __restrict__ dst, int lane) {
;     float ss = 0.f;
; #pragma unroll
;     for (int j = 0; j < 4; ++j) ss += v[j][0] * v[j][0] + v[j][1] * v[j][1] + v[j][2] * v[j][2] + v[j][3] * v[j][3];
;     ss = wave_sum(ss);
;     const float rstd = rsqrtf(ss * (1.f / 1024.f) + 1e-6f);
; #pragma unroll
;     for (int j = 0; j < 4; ++j) {
;         const int c4 = lane + 64 * j;
;         const f32x4 g4 = ((const f32x4*)g)[c4], sh = ((const f32x4*)shift)[c4], sc = ((const f32x4*)scale)[c4];
;         f32x4 h = (v[j] * rstd) * g4; h = h * (sc + 1.f) + sh;
;         store_bf4(dst + c4 * 4, h);
;     }
; }
; __device__ __forceinline__ void phase1(const Params& P) {
;     ...
;         while (row < NT) {
;             f32x4 v[4];
; #pragma unroll
;             for (int j = 0; j < 4; ++j) v[j] = vn[j];
;             const int nrow = row + stride;
;             if (nrow < NT) { const float* src = nrow < NL ? P.in[0] + (size_t)nrow * 1024 : P.in[2] + (size_t)(nrow - NL) * 1024;
; #pragma unroll
;                 for (int j = 0; j < 4; ++j) vn[j] = ((const f32x4*)src)[lane + 64 * j]; }
;             const int mr = row < NL ? (row >> 13) : 4;
;             norm_row_pre(v, P.in[6], mod + mr * 9216 + 0, mod + mr * 9216 + 1024, H + (size_t)row * 1024, lane);
;             if (row >= NL) {
; #pragma unroll
;                 for (int j = 0; j < 4; ++j) ((f32x4*)((float*)(P.ws + OFF_E) + (size_t)(row - NL) * 1024))[lane + 64 * j] = v[j];
;             }
;             row = nrow;
;         }
	v_pk_add_f32 v[176:177], v[176:177], 1.0 op_sel_hi:[1,0]
	v_pk_add_f32 v[178:179], v[178:179], 1.0 op_sel_hi:[1,0]
	v_pk_add_f32 v[180:181], v[180:181], 1.0 op_sel_hi:[1,0]
	v_pk_add_f32 v[182:183], v[182:183], 1.0 op_sel_hi:[1,0]
	v_pk_add_f32 v[184:185], v[184:185], 1.0 op_sel_hi:[1,0]
	v_pk_add_f32 v[186:187], v[186:187], 1.0 op_sel_hi:[1,0]
	v_pk_add_f32 v[188:189], v[188:189], 1.0 op_sel_hi:[1,0]
	v_pk_add_f32 v[190:191], v[190:191], 1.0 op_sel_hi:[1,0]
	v_pk_mul_f32 v[96:97], v[112:113], v[112:113]
	v_pk_fma_f32 v[96:97], v[114:115], v[114:115], v[96:97]
	v_pk_fma_f32 v[96:97], v[116:117], v[116:117], v[96:97]
	v_pk_fma_f32 v[96:97], v[118:119], v[118:119], v[96:97]
	v_pk_fma_f32 v[96:97], v[120:121], v[120:121], v[96:97]
	v_pk_fma_f32 v[96:97], v[122:123], v[122:123], v[96:97]
	v_pk_fma_f32 v[96:97], v[124:125], v[124:125], v[96:97]
	v_pk_fma_f32 v[96:97], v[126:127], v[126:127], v[96:97]
	v_add_f32_e32 v96, v96, v97
	s_nop 1
	v_add_f32_dpp v97, v96, v96 quad_perm:[1,0,3,2] row_mask:0xf bank_mask:0xf
	s_nop 1
	v_add_f32_dpp v96, v97, v97 quad_perm:[2,3,0,1] row_mask:0xf bank_mask:0xf
	s_nop 1
	v_add_f32_dpp v97, v96, v96 row_half_mirror row_mask:0xf bank_mask:0xf
	s_nop 1
	v_add_f32_dpp v96, v97, v97 row_mirror row_mask:0xf bank_mask:0xf
	s_nop 1
	v_readlane_b32 s16, v96, 0
	v_readlane_b32 s17, v96, 16
	v_readlane_b32 s18, v96, 32
	v_readlane_b32 s19, v96, 48
	s_nop 1
	v_mov_b32_e32 v96, s16
	v_add_f32_e32 v96, s17, v96
	v_add_f32_e32 v96, s18, v96
	v_add_f32_e32 v96, s19, v96
	v_mov_b32_e32 v98, 0x358637bd
	v_fmamk_f32 v96, v96, 0x3a800000, v98
	v_rsq_f32_e32 v96, v96
	s_nop 0
	v_pk_mul_f32 v[112:113], v[112:113], v[96:97] op_sel_hi:[1,0]
	v_pk_mul_f32 v[114:115], v[114:115], v[96:97] op_sel_hi:[1,0]
	v_pk_mul_f32 v[116:117], v[116:117], v[96:97] op_sel_hi:[1,0]
	v_pk_mul_f32 v[118:119], v[118:119], v[96:97] op_sel_hi:[1,0]
	v_pk_mul_f32 v[120:121], v[120:121], v[96:97] op_sel_hi:[1,0]
	v_pk_mul_f32 v[122:123], v[122:123], v[96:97] op_sel_hi:[1,0]
	v_pk_mul_f32 v[124:125], v[124:125], v[96:97] op_sel_hi:[1,0]
	v_pk_mul_f32 v[126:127], v[126:127], v[96:97] op_sel_hi:[1,0]
	v_pk_mul_f32 v[112:113], v[48:49], v[112:113]
	v_pk_mul_f32 v[114:115], v[50:51], v[114:115]
	v_pk_mul_f32 v[116:117], v[52:53], v[116:117]
	v_pk_mul_f32 v[118:119], v[54:55], v[118:119]
	v_pk_mul_f32 v[120:121], v[56:57], v[120:121]
	v_pk_mul_f32 v[122:123], v[58:59], v[122:123]
	v_pk_mul_f32 v[124:125], v[60:61], v[124:125]
	v_pk_mul_f32 v[126:127], v[62:63], v[126:127]
	v_pk_fma_f32 v[112:113], v[176:177], v[112:113], v[192:193]
	v_pk_fma_f32 v[114:115], v[178:179], v[114:115], v[194:195]
	v_pk_fma_f32 v[116:117], v[180:181], v[116:117], v[196:197]
	v_pk_fma_f32 v[118:119], v[182:183], v[118:119], v[198:199]
	v_pk_fma_f32 v[120:121], v[184:185], v[120:121], v[200:201]
	v_pk_fma_f32 v[122:123], v[186:187], v[122:123], v[202:203]
	v_pk_fma_f32 v[124:125], v[188:189], v[124:125], v[204:205]
	v_pk_fma_f32 v[126:127], v[190:191], v[126:127], v[206:207]
	v_cvt_pk_bf16_f32 v100, v112, v113
	v_cvt_pk_bf16_f32 v101, v114, v115
	v_cvt_pk_bf16_f32 v102, v116, v117
	v_cvt_pk_bf16_f32 v103, v118, v119
	v_cvt_pk_bf16_f32 v104, v120, v121
	v_cvt_pk_bf16_f32 v105, v122, v123
	v_cvt_pk_bf16_f32 v106, v124, v125
	v_cvt_pk_bf16_f32 v107, v126, v127
	s_add_u32 s8, s8, 0x400000
	s_addc_u32 s9, s9, 0
	global_store_dwordx2 v33, v[100:101], s[8:9]
	global_store_dwordx2 v33, v[102:103], s[8:9] offset:512
	global_store_dwordx2 v33, v[104:105], s[8:9] offset:1024
	global_store_dwordx2 v33, v[106:107], s[8:9] offset:1536
	s_add_u32 s6, s6, 0x800000
	s_addc_u32 s7, s7, 0
	global_load_dwordx4 v[112:115], v32, s[6:7]
	global_load_dwordx4 v[116:119], v32, s[6:7] offset:1024
	global_load_dwordx4 v[120:123], v32, s[6:7] offset:2048
	global_load_dwordx4 v[124:127], v32, s[6:7] offset:3072
	s_waitcnt vmcnt(16)
	v_pk_mul_f32 v[96:97], v[128:129], v[128:129]
	v_pk_fma_f32 v[96:97], v[130:131], v[130:131], v[96:97]
	v_pk_fma_f32 v[96:97], v[132:133], v[132:133], v[96:97]
	v_pk_fma_f32 v[96:97], v[134:135], v[134:135], v[96:97]
	v_pk_fma_f32 v[96:97], v[136:137], v[136:137], v[96:97]
	v_pk_fma_f32 v[96:97], v[138:139], v[138:139], v[96:97]
	v_pk_fma_f32 v[96:97], v[140:141], v[140:141], v[96:97]
	v_pk_fma_f32 v[96:97], v[142:143], v[142:143], v[96:97]
	v_add_f32_e32 v96, v96, v97
	s_nop 1
	v_add_f32_dpp v97, v96, v96 quad_perm:[1,0,3,2] row_mask:0xf bank_mask:0xf
	s_nop 1
	v_add_f32_dpp v96, v97, v97 quad_perm:[2,3,0,1] row_mask:0xf bank_mask:0xf
	s_nop 1
	v_add_f32_dpp v97, v96, v96 row_half_mirror row_mask:0xf bank_mask:0xf
	s_nop 1
	v_add_f32_dpp v96, v97, v97 row_mirror row_mask:0xf bank_mask:0xf
	s_nop 1
	v_readlane_b32 s16, v96, 0
	v_readlane_b32 s17, v96, 16
	v_readlane_b32 s18, v96, 32
	v_readlane_b32 s19, v96, 48
	s_nop 1
	v_mov_b32_e32 v96, s16
	v_add_f32_e32 v96, s17, v96
	v_add_f32_e32 v96, s18, v96
	v_add_f32_e32 v96, s19, v96
	v_mov_b32_e32 v98, 0x358637bd
	v_fmamk_f32 v96, v96, 0x3a800000, v98
	v_rsq_f32_e32 v96, v96
	s_nop 0
	v_pk_mul_f32 v[128:129], v[128:129], v[96:97] op_sel_hi:[1,0]
	v_pk_mul_f32 v[130:131], v[130:131], v[96:97] op_sel_hi:[1,0]
	v_pk_mul_f32 v[132:133], v[132:133], v[96:97] op_sel_hi:[1,0]
	v_pk_mul_f32 v[134:135], v[134:135], v[96:97] op_sel_hi:[1,0]
	v_pk_mul_f32 v[136:137], v[136:137], v[96:97] op_sel_hi:[1,0]
	v_pk_mul_f32 v[138:139], v[138:139], v[96:97] op_sel_hi:[1,0]
	v_pk_mul_f32 v[140:141], v[140:141], v[96:97] op_sel_hi:[1,0]
	v_pk_mul_f32 v[142:143], v[142:143], v[96:97] op_sel_hi:[1,0]
	v_pk_mul_f32 v[128:129], v[48:49], v[128:129]
	v_pk_mul_f32 v[130:131], v[50:51], v[130:131]
	v_pk_mul_f32 v[132:133], v[52:53], v[132:133]
	v_pk_mul_f32 v[134:135], v[54:55], v[134:135]
	v_pk_mul_f32 v[136:137], v[56:57], v[136:137]
	v_pk_mul_f32 v[138:139], v[58:59], v[138:139]
	v_pk_mul_f32 v[140:141], v[60:61], v[140:141]
	v_pk_mul_f32 v[142:143], v[62:63], v[142:143]
	v_pk_fma_f32 v[128:129], v[176:177], v[128:129], v[192:193]
	v_pk_fma_f32 v[130:131], v[178:179], v[130:131], v[194:195]
	v_pk_fma_f32 v[132:133], v[180:181], v[132:133], v[196:197]
	v_pk_fma_f32 v[134:135], v[182:183], v[134:135], v[198:199]
	v_pk_fma_f32 v[136:137], v[184:185], v[136:137], v[200:201]
	v_pk_fma_f32 v[138:139], v[186:187], v[138:139], v[202:203]
	v_pk_fma_f32 v[140:141], v[188:189], v[140:141], v[204:205]
	v_pk_fma_f32 v[142:143], v[190:191], v[142:143], v[206:207]
	v_cvt_pk_bf16_f32 v100, v128, v129
	v_cvt_pk_bf16_f32 v101, v130, v131
	v_cvt_pk_bf16_f32 v102, v132, v133
	v_cvt_pk_bf16_f32 v103, v134, v135
	v_cvt_pk_bf16_f32 v104, v136, v137
	v_cvt_pk_bf16_f32 v105, v138, v139
	v_cvt_pk_bf16_f32 v106, v140, v141
	v_cvt_pk_bf16_f32 v107, v142, v143
	s_add_u32 s8, s8, 0x400000
	s_addc_u32 s9, s9, 0
	global_store_dwordx2 v33, v[100:101], s[8:9]
	global_store_dwordx2 v33, v[102:103], s[8:9] offset:512
	global_store_dwordx2 v33, v[104:105], s[8:9] offset:1024
	global_store_dwordx2 v33, v[106:107], s[8:9] offset:1536
	s_waitcnt vmcnt(12)
; __device__ __forceinline__ void store_bf4(bf16_t* p, f32x4 v) { uint2 o; o.x = pk2(v[0], v[1]); o.y = pk2(v[2], v[3]); *(uint2*)p = o; }
; __device__ __forceinline__ void norm_row_pre(const f32x4 (&v)[4], const float* __restrict__ g, const float* __restrict__ shift, const float* __restrict__ scale, bf16_t* __restrict__ dst, int lane) {
;     float ss = 0.f;
; #pragma unroll
;     for (int j = 0; j < 4; ++j) ss += v[j][0] * v[j][0] + v[j][1] * v[j][1] + v[j][2] * v[j][2] + v[j][3] * v[j][3];
;     ss = wave_sum(ss);
;     const float rstd = rsqrtf(ss * (1.f / 1024.f) + 1e-6f);
; #pragma unroll
;     for (int j = 0; j < 4; ++j) {
;         const int c4 = lane + 64 * j;
;         const f32x4 g4 = ((const f32x4*)g)[c4], sh = ((const f32x4*)shift)[c4], sc = ((const f32x4*)scale)[c4];
;         f32x4 h = (v[j] * rstd) * g4; h = h * (sc + 1.f) + sh;
;         store_bf4(dst + c4 * 4, h);
;     }
; }
; __device__ __forceinline__ void phase1(const Params& P) {
;     ...
;         while (row < NT) {
;             f32x4 v[4];
; #pragma unroll
;             for (int j = 0; j < 4; ++j) v[j] = vn[j];
;             const int nrow = row + stride;
;             if (nrow < NT) { const float* src = nrow < NL ? P.in[0] + (size_t)nrow * 1024 : P.in[2] + (size_t)(nrow - NL) * 1024;
; #pragma unroll
;                 for (int j = 0; j < 4; ++j) vn[j] = ((const f32x4*)src)[lane + 64 * j]; }
;             const int mr = row < NL ? (row >> 13) : 4;
;             norm_row_pre(v, P.in[6], mod + mr * 9216 + 0, mod + mr * 9216 + 1024, H + (size_t)row * 1024, lane);
;             if (row >= NL) {
; #pragma unroll
;                 for (int j = 0; j < 4; ++j) ((f32x4*)((float*)(P.ws + OFF_E) + (size_t)(row - NL) * 1024))[lane + 64 * j] = v[j];
;             }
;             row = nrow;
;         }
	v_pk_mul_f32 v[96:97], v[144:145], v[144:145]
	v_pk_fma_f32 v[96:97], v[146:147], v[146:147], v[96:97]
	v_pk_fma_f32 v[96:97], v[148:149], v[148:149], v[96:97]
	v_pk_fma_f32 v[96:97], v[150:151], v[150:151], v[96:97]
	v_pk_fma_f32 v[96:97], v[152:153], v[152:153], v[96:97]
	v_pk_fma_f32 v[96:97], v[154:155], v[154:155], v[96:97]
	v_pk_fma_f32 v[96:97], v[156:157], v[156:157], v[96:97]
	v_pk_fma_f32 v[96:97], v[158:159], v[158:159], v[96:97]
	v_add_f32_e32 v96, v96, v97
	s_nop 1
	v_add_f32_dpp v97, v96, v96 quad_perm:[1,0,3,2] row_mask:0xf bank_mask:0xf
	s_nop 1
	v_add_f32_dpp v96, v97, v97 quad_perm:[2,3,0,1] row_mask:0xf bank_mask:0xf
	s_nop 1
	v_add_f32_dpp v97, v96, v96 row_half_mirror row_mask:0xf bank_mask:0xf
	s_nop 1
	v_add_f32_dpp v96, v97, v97 row_mirror row_mask:0xf bank_mask:0xf
	s_nop 1
	v_readlane_b32 s16, v96, 0
	v_readlane_b32 s17, v96, 16
	v_readlane_b32 s18, v96, 32
	v_readlane_b32 s19, v96, 48
	s_nop 1
	v_mov_b32_e32 v96, s16
	v_add_f32_e32 v96, s17, v96
	v_add_f32_e32 v96, s18, v96
	v_add_f32_e32 v96, s19, v96
	v_mov_b32_e32 v98, 0x358637bd
	v_fmamk_f32 v96, v96, 0x3a800000, v98
	v_rsq_f32_e32 v96, v96
	s_nop 0
	v_pk_mul_f32 v[144:145], v[144:145], v[96:97] op_sel_hi:[1,0]
	v_pk_mul_f32 v[146:147], v[146:147], v[96:97] op_sel_hi:[1,0]
	v_pk_mul_f32 v[148:149], v[148:149], v[96:97] op_sel_hi:[1,0]
	v_pk_mul_f32 v[150:151], v[150:151], v[96:97] op_sel_hi:[1,0]
	v_pk_mul_f32 v[152:153], v[152:153], v[96:97] op_sel_hi:[1,0]
	v_pk_mul_f32 v[154:155], v[154:155], v[96:97] op_sel_hi:[1,0]
	v_pk_mul_f32 v[156:157], v[156:157], v[96:97] op_sel_hi:[1,0]
	v_pk_mul_f32 v[158:159], v[158:159], v[96:97] op_sel_hi:[1,0]
	v_pk_mul_f32 v[144:145], v[48:49], v[144:145]
	v_pk_mul_f32 v[146:147], v[50:51], v[146:147]
	v_pk_mul_f32 v[148:149], v[52:53], v[148:149]
	v_pk_mul_f32 v[150:151], v[54:55], v[150:151]
	v_pk_mul_f32 v[152:153], v[56:57], v[152:153]
	v_pk_mul_f32 v[154:155], v[58:59], v[154:155]
	v_pk_mul_f32 v[156:157], v[60:61], v[156:157]
	v_pk_mul_f32 v[158:159], v[62:63], v[158:159]
	v_pk_fma_f32 v[144:145], v[176:177], v[144:145], v[192:193]
	v_pk_fma_f32 v[146:147], v[178:179], v[146:147], v[194:195]
	v_pk_fma_f32 v[148:149], v[180:181], v[148:149], v[196:197]
	v_pk_fma_f32 v[150:151], v[182:183], v[150:151], v[198:199]
	v_pk_fma_f32 v[152:153], v[184:185], v[152:153], v[200:201]
	v_pk_fma_f32 v[154:155], v[186:187], v[154:155], v[202:203]
	v_pk_fma_f32 v[156:157], v[188:189], v[156:157], v[204:205]
	v_pk_fma_f32 v[158:159], v[190:191], v[158:159], v[206:207]
	v_cvt_pk_bf16_f32 v100, v144, v145
	v_cvt_pk_bf16_f32 v101, v146, v147
	v_cvt_pk_bf16_f32 v102, v148, v149
	v_cvt_pk_bf16_f32 v103, v150, v151
	v_cvt_pk_bf16_f32 v104, v152, v153
	v_cvt_pk_bf16_f32 v105, v154, v155
	v_cvt_pk_bf16_f32 v106, v156, v157
	v_cvt_pk_bf16_f32 v107, v158, v159
	s_add_u32 s8, s8, 0x400000
	s_addc_u32 s9, s9, 0
	global_store_dwordx2 v33, v[100:101], s[8:9]
	global_store_dwordx2 v33, v[102:103], s[8:9] offset:512
	global_store_dwordx2 v33, v[104:105], s[8:9] offset:1024
	global_store_dwordx2 v33, v[106:107], s[8:9] offset:1536
	s_waitcnt vmcnt(8)
	v_pk_mul_f32 v[96:97], v[112:113], v[112:113]
	v_pk_fma_f32 v[96:97], v[114:115], v[114:115], v[96:97]
	v_pk_fma_f32 v[96:97], v[116:117], v[116:117], v[96:97]
	v_pk_fma_f32 v[96:97], v[118:119], v[118:119], v[96:97]
	v_pk_fma_f32 v[96:97], v[120:121], v[120:121], v[96:97]
	v_pk_fma_f32 v[96:97], v[122:123], v[122:123], v[96:97]
	v_pk_fma_f32 v[96:97], v[124:125], v[124:125], v[96:97]
	v_pk_fma_f32 v[96:97], v[126:127], v[126:127], v[96:97]
	v_add_f32_e32 v96, v96, v97
	s_nop 1
	v_add_f32_dpp v97, v96, v96 quad_perm:[1,0,3,2] row_mask:0xf bank_mask:0xf
	s_nop 1
	v_add_f32_dpp v96, v97, v97 quad_perm:[2,3,0,1] row_mask:0xf bank_mask:0xf
	s_nop 1
	v_add_f32_dpp v97, v96, v96 row_half_mirror row_mask:0xf bank_mask:0xf
	s_nop 1
	v_add_f32_dpp v96, v97, v97 row_mirror row_mask:0xf bank_mask:0xf
	s_nop 1
	v_readlane_b32 s16, v96, 0
	v_readlane_b32 s17, v96, 16
	v_readlane_b32 s18, v96, 32
	v_readlane_b32 s19, v96, 48
	s_nop 1
	v_mov_b32_e32 v96, s16
	v_add_f32_e32 v96, s17, v96
	v_add_f32_e32 v96, s18, v96
	v_add_f32_e32 v96, s19, v96
	v_mov_b32_e32 v98, 0x358637bd
	v_fmamk_f32 v96, v96, 0x3a800000, v98
	v_rsq_f32_e32 v96, v96
	s_nop 0
	v_pk_mul_f32 v[112:113], v[112:113], v[96:97] op_sel_hi:[1,0]
	v_pk_mul_f32 v[114:115], v[114:115], v[96:97] op_sel_hi:[1,0]
	v_pk_mul_f32 v[116:117], v[116:117], v[96:97] op_sel_hi:[1,0]
	v_pk_mul_f32 v[118:119], v[118:119], v[96:97] op_sel_hi:[1,0]
	v_pk_mul_f32 v[120:121], v[120:121], v[96:97] op_sel_hi:[1,0]
	v_pk_mul_f32 v[122:123], v[122:123], v[96:97] op_sel_hi:[1,0]
	v_pk_mul_f32 v[124:125], v[124:125], v[96:97] op_sel_hi:[1,0]
	v_pk_mul_f32 v[126:127], v[126:127], v[96:97] op_sel_hi:[1,0]
	v_pk_mul_f32 v[112:113], v[48:49], v[112:113]
	v_pk_mul_f32 v[114:115], v[50:51], v[114:115]
	v_pk_mul_f32 v[116:117], v[52:53], v[116:117]
	v_pk_mul_f32 v[118:119], v[54:55], v[118:119]
	v_pk_mul_f32 v[120:121], v[56:57], v[120:121]
	v_pk_mul_f32 v[122:123], v[58:59], v[122:123]
	v_pk_mul_f32 v[124:125], v[60:61], v[124:125]
	v_pk_mul_f32 v[126:127], v[62:63], v[126:127]
	v_pk_fma_f32 v[112:113], v[176:177], v[112:113], v[192:193]
	v_pk_fma_f32 v[114:115], v[178:179], v[114:115], v[194:195]
	v_pk_fma_f32 v[116:117], v[180:181], v[116:117], v[196:197]
	v_pk_fma_f32 v[118:119], v[182:183], v[118:119], v[198:199]
	v_pk_fma_f32 v[120:121], v[184:185], v[120:121], v[200:201]
	v_pk_fma_f32 v[122:123], v[186:187], v[122:123], v[202:203]
	v_pk_fma_f32 v[124:125], v[188:189], v[124:125], v[204:205]
	v_pk_fma_f32 v[126:127], v[190:191], v[126:127], v[206:207]
	v_cvt_pk_bf16_f32 v100, v112, v113
	v_cvt_pk_bf16_f32 v101, v114, v115
	v_cvt_pk_bf16_f32 v102, v116, v117
	v_cvt_pk_bf16_f32 v103, v118, v119
	v_cvt_pk_bf16_f32 v104, v120, v121
	v_cvt_pk_bf16_f32 v105, v122, v123
	v_cvt_pk_bf16_f32 v106, v124, v125
	v_cvt_pk_bf16_f32 v107, v126, v127
	s_add_u32 s8, s8, 0x400000
	s_addc_u32 s9, s9, 0
	global_store_dwordx2 v33, v[100:101], s[8:9]
	global_store_dwordx2 v33, v[102:103], s[8:9] offset:512
	global_store_dwordx2 v33, v[104:105], s[8:9] offset:1024
	global_store_dwordx2 v33, v[106:107], s[8:9] offset:1536
	s_branch .Lp1n_done
; __device__ __forceinline__ void store_bf4(bf16_t* p, f32x4 v) { uint2 o; o.x = pk2(v[0], v[1]); o.y = pk2(v[2], v[3]); *(uint2*)p = o; }
; __device__ __forceinline__ void norm_row_pre(const f32x4 (&v)[4], const float* __restrict__ g, const float* __restrict__ shift, const float* __restrict__ scale, bf16_t* __restrict__ dst, int lane) {
;     float ss = 0.f;
; #pragma unroll
;     for (int j = 0; j < 4; ++j) ss += v[j][0] * v[j][0] + v[j][1] * v[j][1] + v[j][2] * v[j][2] + v[j][3] * v[j][3];
;     ss = wave_sum(ss);
;     const float rstd = rsqrtf(ss * (1.f / 1024.f) + 1e-6f);
; #pragma unroll
;     for (int j = 0; j < 4; ++j) {
;         const int c4 = lane + 64 * j;
;         const f32x4 g4 = ((const f32x4*)g)[c4], sh = ((const f32x4*)shift)[c4], sc = ((const f32x4*)scale)[c4];
;         f32x4 h = (v[j] * rstd) * g4; h = h * (sc + 1.f) + sh;
;         store_bf4(dst + c4 * 4, h);
;     }
; }
; __device__ __forceinline__ void phase1(const Params& P) {
;     ...
;     {
;         const int stride = gridDim.x * 8;
;         int row = blockIdx.x * 8 + w;
;         f32x4 vn[4];
;         if (row < NT) { const float* src = row < NL ? P.in[0] + (size_t)row * 1024 : P.in[2] + (size_t)(row - NL) * 1024;
; #pragma unroll
;             for (int j = 0; j < 4; ++j) vn[j] = ((const f32x4*)src)[lane + 64 * j]; }
;         while (row < NT) {
;             f32x4 v[4];
; #pragma unroll
;             for (int j = 0; j < 4; ++j) v[j] = vn[j];
;             const int nrow = row + stride;
;             if (nrow < NT) { const float* src = nrow < NL ? P.in[0] + (size_t)nrow * 1024 : P.in[2] + (size_t)(nrow - NL) * 1024;
; #pragma unroll
;                 for (int j = 0; j < 4; ++j) vn[j] = ((const f32x4*)src)[lane + 64 * j]; }
;             const int mr = row < NL ? (row >> 13) : 4;
;             norm_row_pre(v, P.in[6], mod + mr * 9216 + 0, mod + mr * 9216 + 1024, H + (size_t)row * 1024, lane);
.Lp1n17_start:
	global_load_dwordx4 v[48:51], v32, s[48:49]
	global_load_dwordx4 v[52:55], v32, s[48:49] offset:1024
	global_load_dwordx4 v[56:59], v32, s[48:49] offset:2048
	global_load_dwordx4 v[60:63], v32, s[48:49] offset:3072
	s_mov_b32 s10, 0
	s_add_u32 s12, s2, s10
	s_addc_u32 s13, s3, 0
	s_add_u32 s14, s12, 0x1000
	s_addc_u32 s15, s13, 0
	global_load_dwordx4 v[80:83], v32, s[12:13]
	global_load_dwordx4 v[84:87], v32, s[12:13] offset:1024
	global_load_dwordx4 v[88:91], v32, s[12:13] offset:2048
	global_load_dwordx4 v[92:95], v32, s[12:13] offset:3072
	global_load_dwordx4 v[64:67], v32, s[14:15]
	global_load_dwordx4 v[68:71], v32, s[14:15] offset:1024
	global_load_dwordx4 v[72:75], v32, s[14:15] offset:2048
	global_load_dwordx4 v[76:79], v32, s[14:15] offset:3072
	global_load_dwordx4 v[112:115], v32, s[6:7]
	global_load_dwordx4 v[116:119], v32, s[6:7] offset:1024
	global_load_dwordx4 v[120:123], v32, s[6:7] offset:2048
	global_load_dwordx4 v[124:127], v32, s[6:7] offset:3072
	s_add_u32 s6, s6, 0x800000
	s_addc_u32 s7, s7, 0
	global_load_dwordx4 v[128:131], v32, s[6:7]
	global_load_dwordx4 v[132:135], v32, s[6:7] offset:1024
	global_load_dwordx4 v[136:139], v32, s[6:7] offset:2048
	global_load_dwordx4 v[140:143], v32, s[6:7] offset:3072
	s_add_u32 s6, s6, 0x800000
	s_addc_u32 s7, s7, 0
	global_load_dwordx4 v[144:147], v32, s[6:7]
	global_load_dwordx4 v[148:151], v32, s[6:7] offset:1024
	global_load_dwordx4 v[152:155], v32, s[6:7] offset:2048
	global_load_dwordx4 v[156:159], v32, s[6:7] offset:3072
	s_waitcnt vmcnt(8)
	v_pk_add_f32 v[64:65], v[64:65], 1.0 op_sel_hi:[1,0]
	v_pk_add_f32 v[66:67], v[66:67], 1.0 op_sel_hi:[1,0]
	v_pk_add_f32 v[68:69], v[68:69], 1.0 op_sel_hi:[1,0]
	v_pk_add_f32 v[70:71], v[70:71], 1.0 op_sel_hi:[1,0]
	v_pk_add_f32 v[72:73], v[72:73], 1.0 op_sel_hi:[1,0]
	v_pk_add_f32 v[74:75], v[74:75], 1.0 op_sel_hi:[1,0]
	v_pk_add_f32 v[76:77], v[76:77], 1.0 op_sel_hi:[1,0]
	v_pk_add_f32 v[78:79], v[78:79], 1.0 op_sel_hi:[1,0]
	v_pk_mul_f32 v[96:97], v[112:113], v[112:113]
	v_pk_fma_f32 v[96:97], v[114:115], v[114:115], v[96:97]
	v_pk_fma_f32 v[96:97], v[116:117], v[116:117], v[96:97]
	v_pk_fma_f32 v[96:97], v[118:119], v[118:119], v[96:97]
	v_pk_fma_f32 v[96:97], v[120:121], v[120:121], v[96:97]
	v_pk_fma_f32 v[96:97], v[122:123], v[122:123], v[96:97]
	v_pk_fma_f32 v[96:97], v[124:125], v[124:125], v[96:97]
	v_pk_fma_f32 v[96:97], v[126:127], v[126:127], v[96:97]
	v_add_f32_e32 v96, v96, v97
	s_nop 1
	v_add_f32_dpp v97, v96, v96 quad_perm:[1,0,3,2] row_mask:0xf bank_mask:0xf
	s_nop 1
	v_add_f32_dpp v96, v97, v97 quad_perm:[2,3,0,1] row_mask:0xf bank_mask:0xf
	s_nop 1
	v_add_f32_dpp v97, v96, v96 row_half_mirror row_mask:0xf bank_mask:0xf
	s_nop 1
	v_add_f32_dpp v96, v97, v97 row_mirror row_mask:0xf bank_mask:0xf
	s_nop 1
	v_readlane_b32 s16, v96, 0
	v_readlane_b32 s17, v96, 16
	v_readlane_b32 s18, v96, 32
	v_readlane_b32 s19, v96, 48
	s_nop 1
	v_mov_b32_e32 v96, s16
	v_add_f32_e32 v96, s17, v96
	v_add_f32_e32 v96, s18, v96
	v_add_f32_e32 v96, s19, v96
	v_mov_b32_e32 v98, 0x358637bd
	v_fmamk_f32 v96, v96, 0x3a800000, v98
	v_rsq_f32_e32 v96, v96
	s_nop 0
	v_pk_mul_f32 v[112:113], v[112:113], v[96:97] op_sel_hi:[1,0]
	v_pk_mul_f32 v[114:115], v[114:115], v[96:97] op_sel_hi:[1,0]
	v_pk_mul_f32 v[116:117], v[116:117], v[96:97] op_sel_hi:[1,0]
	v_pk_mul_f32 v[118:119], v[118:119], v[96:97] op_sel_hi:[1,0]
	v_pk_mul_f32 v[120:121], v[120:121], v[96:97] op_sel_hi:[1,0]
	v_pk_mul_f32 v[122:123], v[122:123], v[96:97] op_sel_hi:[1,0]
	v_pk_mul_f32 v[124:125], v[124:125], v[96:97] op_sel_hi:[1,0]
	v_pk_mul_f32 v[126:127], v[126:127], v[96:97] op_sel_hi:[1,0]
	v_pk_mul_f32 v[112:113], v[48:49], v[112:113]
	v_pk_mul_f32 v[114:115], v[50:51], v[114:115]
	v_pk_mul_f32 v[116:117], v[52:53], v[116:117]
	v_pk_mul_f32 v[118:119], v[54:55], v[118:119]
	v_pk_mul_f32 v[120:121], v[56:57], v[120:121]
	v_pk_mul_f32 v[122:123], v[58:59], v[122:123]
	v_pk_mul_f32 v[124:125], v[60:61], v[124:125]
	v_pk_mul_f32 v[126:127], v[62:63], v[126:127]
	v_pk_fma_f32 v[112:113], v[64:65], v[112:113], v[80:81]
	v_pk_fma_f32 v[114:115], v[66:67], v[114:115], v[82:83]
	v_pk_fma_f32 v[116:117], v[68:69], v[116:117], v[84:85]
	v_pk_fma_f32 v[118:119], v[70:71], v[118:119], v[86:87]
	v_pk_fma_f32 v[120:121], v[72:73], v[120:121], v[88:89]
	v_pk_fma_f32 v[122:123], v[74:75], v[122:123], v[90:91]
	v_pk_fma_f32 v[124:125], v[76:77], v[124:125], v[92:93]
	v_pk_fma_f32 v[126:127], v[78:79], v[126:127], v[94:95]
	v_cvt_pk_bf16_f32 v100, v112, v113
	v_cvt_pk_bf16_f32 v101, v114, v115
	v_cvt_pk_bf16_f32 v102, v116, v117
	v_cvt_pk_bf16_f32 v103, v118, v119
	v_cvt_pk_bf16_f32 v104, v120, v121
	v_cvt_pk_bf16_f32 v105, v122, v123
	v_cvt_pk_bf16_f32 v106, v124, v125
	v_cvt_pk_bf16_f32 v107, v126, v127
	global_store_dwordx2 v33, v[100:101], s[8:9]
	global_store_dwordx2 v33, v[102:103], s[8:9] offset:512
	global_store_dwordx2 v33, v[104:105], s[8:9] offset:1024
	global_store_dwordx2 v33, v[106:107], s[8:9] offset:1536
	s_add_u32 s6, s6, 0x800000
	s_addc_u32 s7, s7, 0
	global_load_dwordx4 v[112:115], v32, s[6:7]
	global_load_dwordx4 v[116:119], v32, s[6:7] offset:1024
	global_load_dwordx4 v[120:123], v32, s[6:7] offset:2048
	global_load_dwordx4 v[124:127], v32, s[6:7] offset:3072
	s_waitcnt vmcnt(12)
; __device__ __forceinline__ void store_bf4(bf16_t* p, f32x4 v) { uint2 o; o.x = pk2(v[0], v[1]); o.y = pk2(v[2], v[3]); *(uint2*)p = o; }
; __device__ __forceinline__ void norm_row_pre(const f32x4 (&v)[4], const float* __restrict__ g, const float* __restrict__ shift, const float* __restrict__ scale, bf16_t* __restrict__ dst, int lane) {
;     float ss = 0.f;
; #pragma unroll
;     for (int j = 0; j < 4; ++j) ss += v[j][0] * v[j][0] + v[j][1] * v[j][1] + v[j][2] * v[j][2] + v[j][3] * v[j][3];
;     ss = wave_sum(ss);
;     const float rstd = rsqrtf(ss * (1.f / 1024.f) + 1e-6f);
; #pragma unroll
;     for (int j = 0; j < 4; ++j) {
;         const int c4 = lane + 64 * j;
;         const f32x4 g4 = ((const f32x4*)g)[c4], sh = ((const f32x4*)shift)[c4], sc = ((const f32x4*)scale)[c4];
;         f32x4 h = (v[j] * rstd) * g4; h = h * (sc + 1.f) + sh;
;         store_bf4(dst + c4 * 4, h);
;     }
; }
; __device__ __forceinline__ void phase1(const Params& P) {
;     ...
;         while (row < NT) {
;             f32x4 v[4];
; #pragma unroll
;             for (int j = 0; j < 4; ++j) v[j] = vn[j];
;             const int nrow = row + stride;
;             if (nrow < NT) { const float* src = nrow < NL ? P.in[0] + (size_t)nrow * 1024 : P.in[2] + (size_t)(nrow - NL) * 1024;
; #pragma unroll
;                 for (int j = 0; j < 4; ++j) vn[j] = ((const f32x4*)src)[lane + 64 * j]; }
;             const int mr = row < NL ? (row >> 13) : 4;
;             norm_row_pre(v, P.in[6], mod + mr * 9216 + 0, mod + mr * 9216 + 1024, H + (size_t)row * 1024, lane);
;             if (row >= NL) {
; #pragma unroll
;                 for (int j = 0; j < 4; ++j) ((f32x4*)((float*)(P.ws + OFF_E) + (size_t)(row - NL) * 1024))[lane + 64 * j] = v[j];
;             }
;             row = nrow;
;         }
	v_pk_mul_f32 v[96:97], v[128:129], v[128:129]
	v_pk_fma_f32 v[96:97], v[130:131], v[130:131], v[96:97]
	v_pk_fma_f32 v[96:97], v[132:133], v[132:133], v[96:97]
	v_pk_fma_f32 v[96:97], v[134:135], v[134:135], v[96:97]
	v_pk_fma_f32 v[96:97], v[136:137], v[136:137], v[96:97]
	v_pk_fma_f32 v[96:97], v[138:139], v[138:139], v[96:97]
	v_pk_fma_f32 v[96:97], v[140:141], v[140:141], v[96:97]
	v_pk_fma_f32 v[96:97], v[142:143], v[142:143], v[96:97]
	v_add_f32_e32 v96, v96, v97
	s_nop 1
	v_add_f32_dpp v97, v96, v96 quad_perm:[1,0,3,2] row_mask:0xf bank_mask:0xf
	s_nop 1
	v_add_f32_dpp v96, v97, v97 quad_perm:[2,3,0,1] row_mask:0xf bank_mask:0xf
	s_nop 1
	v_add_f32_dpp v97, v96, v96 row_half_mirror row_mask:0xf bank_mask:0xf
	s_nop 1
	v_add_f32_dpp v96, v97, v97 row_mirror row_mask:0xf bank_mask:0xf
	s_nop 1
	v_readlane_b32 s16, v96, 0
	v_readlane_b32 s17, v96, 16
	v_readlane_b32 s18, v96, 32
	v_readlane_b32 s19, v96, 48
	s_nop 1
	v_mov_b32_e32 v96, s16
	v_add_f32_e32 v96, s17, v96
	v_add_f32_e32 v96, s18, v96
	v_add_f32_e32 v96, s19, v96
	v_mov_b32_e32 v98, 0x358637bd
	v_fmamk_f32 v96, v96, 0x3a800000, v98
	v_rsq_f32_e32 v96, v96
	s_nop 0
	v_pk_mul_f32 v[128:129], v[128:129], v[96:97] op_sel_hi:[1,0]
	v_pk_mul_f32 v[130:131], v[130:131], v[96:97] op_sel_hi:[1,0]
	v_pk_mul_f32 v[132:133], v[132:133], v[96:97] op_sel_hi:[1,0]
	v_pk_mul_f32 v[134:135], v[134:135], v[96:97] op_sel_hi:[1,0]
	v_pk_mul_f32 v[136:137], v[136:137], v[96:97] op_sel_hi:[1,0]
	v_pk_mul_f32 v[138:139], v[138:139], v[96:97] op_sel_hi:[1,0]
	v_pk_mul_f32 v[140:141], v[140:141], v[96:97] op_sel_hi:[1,0]
	v_pk_mul_f32 v[142:143], v[142:143], v[96:97] op_sel_hi:[1,0]
	v_pk_mul_f32 v[128:129], v[48:49], v[128:129]
	v_pk_mul_f32 v[130:131], v[50:51], v[130:131]
	v_pk_mul_f32 v[132:133], v[52:53], v[132:133]
	v_pk_mul_f32 v[134:135], v[54:55], v[134:135]
	v_pk_mul_f32 v[136:137], v[56:57], v[136:137]
	v_pk_mul_f32 v[138:139], v[58:59], v[138:139]
	v_pk_mul_f32 v[140:141], v[60:61], v[140:141]
	v_pk_mul_f32 v[142:143], v[62:63], v[142:143]
	v_pk_fma_f32 v[128:129], v[64:65], v[128:129], v[80:81]
	v_pk_fma_f32 v[130:131], v[66:67], v[130:131], v[82:83]
	v_pk_fma_f32 v[132:133], v[68:69], v[132:133], v[84:85]
	v_pk_fma_f32 v[134:135], v[70:71], v[134:135], v[86:87]
	v_pk_fma_f32 v[136:137], v[72:73], v[136:137], v[88:89]
	v_pk_fma_f32 v[138:139], v[74:75], v[138:139], v[90:91]
	v_pk_fma_f32 v[140:141], v[76:77], v[140:141], v[92:93]
	v_pk_fma_f32 v[142:143], v[78:79], v[142:143], v[94:95]
	v_cvt_pk_bf16_f32 v100, v128, v129
	v_cvt_pk_bf16_f32 v101, v130, v131
	v_cvt_pk_bf16_f32 v102, v132, v133
	v_cvt_pk_bf16_f32 v103, v134, v135
	v_cvt_pk_bf16_f32 v104, v136, v137
	v_cvt_pk_bf16_f32 v105, v138, v139
	v_cvt_pk_bf16_f32 v106, v140, v141
	v_cvt_pk_bf16_f32 v107, v142, v143
	s_add_u32 s8, s8, 0x400000
	s_addc_u32 s9, s9, 0
	global_store_dwordx2 v33, v[100:101], s[8:9]
	global_store_dwordx2 v33, v[102:103], s[8:9] offset:512
	global_store_dwordx2 v33, v[104:105], s[8:9] offset:1024
	global_store_dwordx2 v33, v[106:107], s[8:9] offset:1536
	s_add_u32 s6, s6, 0x800000
	s_addc_u32 s7, s7, 0
	global_load_dwordx4 v[128:131], v32, s[6:7]
	global_load_dwordx4 v[132:135], v32, s[6:7] offset:1024
	global_load_dwordx4 v[136:139], v32, s[6:7] offset:2048
	global_load_dwordx4 v[140:143], v32, s[6:7] offset:3072
	s_mov_b32 s10, 36864
	s_add_u32 s12, s2, s10
	s_addc_u32 s13, s3, 0
	s_add_u32 s14, s12, 0x1000
	s_addc_u32 s15, s13, 0
	global_load_dwordx4 v[192:195], v32, s[12:13]
	global_load_dwordx4 v[196:199], v32, s[12:13] offset:1024
	global_load_dwordx4 v[200:203], v32, s[12:13] offset:2048
	global_load_dwordx4 v[204:207], v32, s[12:13] offset:3072
	global_load_dwordx4 v[176:179], v32, s[14:15]
	global_load_dwordx4 v[180:183], v32, s[14:15] offset:1024
	global_load_dwordx4 v[184:187], v32, s[14:15] offset:2048
	global_load_dwordx4 v[188:191], v32, s[14:15] offset:3072
	s_waitcnt vmcnt(24)
	v_pk_mul_f32 v[96:97], v[144:145], v[144:145]
	v_pk_fma_f32 v[96:97], v[146:147], v[146:147], v[96:97]
	v_pk_fma_f32 v[96:97], v[148:149], v[148:149], v[96:97]
	v_pk_fma_f32 v[96:97], v[150:151], v[150:151], v[96:97]
	v_pk_fma_f32 v[96:97], v[152:153], v[152:153], v[96:97]
	v_pk_fma_f32 v[96:97], v[154:155], v[154:155], v[96:97]
	v_pk_fma_f32 v[96:97], v[156:157], v[156:157], v[96:97]
	v_pk_fma_f32 v[96:97], v[158:159], v[158:159], v[96:97]
	v_add_f32_e32 v96, v96, v97
	s_nop 1
	v_add_f32_dpp v97, v96, v96 quad_perm:[1,0,3,2] row_mask:0xf bank_mask:0xf
	s_nop 1
	v_add_f32_dpp v96, v97, v97 quad_perm:[2,3,0,1] row_mask:0xf bank_mask:0xf
	s_nop 1
	v_add_f32_dpp v97, v96, v96 row_half_mirror row_mask:0xf bank_mask:0xf
	s_nop 1
	v_add_f32_dpp v96, v97, v97 row_mirror row_mask:0xf bank_mask:0xf
	s_nop 1
	v_readlane_b32 s16, v96, 0
	v_readlane_b32 s17, v96, 16
	v_readlane_b32 s18, v96, 32
	v_readlane_b32 s19, v96, 48
	s_nop 1
	v_mov_b32_e32 v96, s16
	v_add_f32_e32 v96, s17, v96
	v_add_f32_e32 v96, s18, v96
	v_add_f32_e32 v96, s19, v96
	v_mov_b32_e32 v98, 0x358637bd
	v_fmamk_f32 v96, v96, 0x3a800000, v98
	v_rsq_f32_e32 v96, v96
	s_nop 0
	v_pk_mul_f32 v[144:145], v[144:145], v[96:97] op_sel_hi:[1,0]
	v_pk_mul_f32 v[146:147], v[146:147], v[96:97] op_sel_hi:[1,0]
	v_pk_mul_f32 v[148:149], v[148:149], v[96:97] op_sel_hi:[1,0]
	v_pk_mul_f32 v[150:151], v[150:151], v[96:97] op_sel_hi:[1,0]
	v_pk_mul_f32 v[152:153], v[152:153], v[96:97] op_sel_hi:[1,0]
	v_pk_mul_f32 v[154:155], v[154:155], v[96:97] op_sel_hi:[1,0]
	v_pk_mul_f32 v[156:157], v[156:157], v[96:97] op_sel_hi:[1,0]
	v_pk_mul_f32 v[158:159], v[158:159], v[96:97] op_sel_hi:[1,0]
	v_pk_mul_f32 v[144:145], v[48:49], v[144:145]
	v_pk_mul_f32 v[146:147], v[50:51], v[146:147]
; __device__ __forceinline__ void store_bf4(bf16_t* p, f32x4 v) { uint2 o; o.x = pk2(v[0], v[1]); o.y = pk2(v[2], v[3]); *(uint2*)p = o; }
; __device__ __forceinline__ void norm_row_pre(const f32x4 (&v)[4], const float* __restrict__ g, const float* __restrict__ shift, const float* __restrict__ scale, bf16_t* __restrict__ dst, int lane) {
;     float ss = 0.f;
; #pragma unroll
;     for (int j = 0; j < 4; ++j) ss += v[j][0] * v[j][0] + v[j][1] * v[j][1] + v[j][2] * v[j][2] + v[j][3] * v[j][3];
;     ss = wave_sum(ss);
;     const float rstd = rsqrtf(ss * (1.f / 1024.f) + 1e-6f);
; #pragma unroll
;     for (int j = 0; j < 4; ++j) {
;         const int c4 = lane + 64 * j;
;         const f32x4 g4 = ((const f32x4*)g)[c4], sh = ((const f32x4*)shift)[c4], sc = ((const f32x4*)scale)[c4];
;         f32x4 h = (v[j] * rstd) * g4; h = h * (sc + 1.f) + sh;
;         store_bf4(dst + c4 * 4, h);
;     }
; }
; __device__ __forceinline__ void phase1(const Params& P) {
;     ...
;         while (row < NT) {
;             f32x4 v[4];
; #pragma unroll
;             for (int j = 0; j < 4; ++j) v[j] = vn[j];
;             const int nrow = row + stride;
;             if (nrow < NT) { const float* src = nrow < NL ? P.in[0] + (size_t)nrow * 1024 : P.in[2] + (size_t)(nrow - NL) * 1024;
; #pragma unroll
;                 for (int j = 0; j < 4; ++j) vn[j] = ((const f32x4*)src)[lane + 64 * j]; }
;             const int mr = row < NL ? (row >> 13) : 4;
;             norm_row_pre(v, P.in[6], mod + mr * 9216 + 0, mod + mr * 9216 + 1024, H + (size_t)row * 1024, lane);
;             if (row >= NL) {
; #pragma unroll
;                 for (int j = 0; j < 4; ++j) ((f32x4*)((float*)(P.ws + OFF_E) + (size_t)(row - NL) * 1024))[lane + 64 * j] = v[j];
;             }
;             row = nrow;
;         }
	v_pk_mul_f32 v[148:149], v[52:53], v[148:149]
	v_pk_mul_f32 v[150:151], v[54:55], v[150:151]
	v_pk_mul_f32 v[152:153], v[56:57], v[152:153]
	v_pk_mul_f32 v[154:155], v[58:59], v[154:155]
	v_pk_mul_f32 v[156:157], v[60:61], v[156:157]
	v_pk_mul_f32 v[158:159], v[62:63], v[158:159]
	v_pk_fma_f32 v[144:145], v[64:65], v[144:145], v[80:81]
	v_pk_fma_f32 v[146:147], v[66:67], v[146:147], v[82:83]
	v_pk_fma_f32 v[148:149], v[68:69], v[148:149], v[84:85]
	v_pk_fma_f32 v[150:151], v[70:71], v[150:151], v[86:87]
	v_pk_fma_f32 v[152:153], v[72:73], v[152:153], v[88:89]
	v_pk_fma_f32 v[154:155], v[74:75], v[154:155], v[90:91]
	v_pk_fma_f32 v[156:157], v[76:77], v[156:157], v[92:93]
	v_pk_fma_f32 v[158:159], v[78:79], v[158:159], v[94:95]
	v_cvt_pk_bf16_f32 v100, v144, v145
	v_cvt_pk_bf16_f32 v101, v146, v147
	v_cvt_pk_bf16_f32 v102, v148, v149
	v_cvt_pk_bf16_f32 v103, v150, v151
	v_cvt_pk_bf16_f32 v104, v152, v153
	v_cvt_pk_bf16_f32 v105, v154, v155
	v_cvt_pk_bf16_f32 v106, v156, v157
	v_cvt_pk_bf16_f32 v107, v158, v159
	s_add_u32 s8, s8, 0x400000
	s_addc_u32 s9, s9, 0
	global_store_dwordx2 v33, v[100:101], s[8:9]
	global_store_dwordx2 v33, v[102:103], s[8:9] offset:512
	global_store_dwordx2 v33, v[104:105], s[8:9] offset:1024
	global_store_dwordx2 v33, v[106:107], s[8:9] offset:1536
	s_add_u32 s6, s6, 0x800000
	s_addc_u32 s7, s7, 0
	global_load_dwordx4 v[144:147], v32, s[6:7]
	global_load_dwordx4 v[148:151], v32, s[6:7] offset:1024
	global_load_dwordx4 v[152:155], v32, s[6:7] offset:2048
	global_load_dwordx4 v[156:159], v32, s[6:7] offset:3072
	s_waitcnt vmcnt(24)
	v_pk_mul_f32 v[96:97], v[112:113], v[112:113]
	v_pk_fma_f32 v[96:97], v[114:115], v[114:115], v[96:97]
	v_pk_fma_f32 v[96:97], v[116:117], v[116:117], v[96:97]
	v_pk_fma_f32 v[96:97], v[118:119], v[118:119], v[96:97]
	v_pk_fma_f32 v[96:97], v[120:121], v[120:121], v[96:97]
	v_pk_fma_f32 v[96:97], v[122:123], v[122:123], v[96:97]
	v_pk_fma_f32 v[96:97], v[124:125], v[124:125], v[96:97]
	v_pk_fma_f32 v[96:97], v[126:127], v[126:127], v[96:97]
	v_add_f32_e32 v96, v96, v97
	s_nop 1
	v_add_f32_dpp v97, v96, v96 quad_perm:[1,0,3,2] row_mask:0xf bank_mask:0xf
	s_nop 1
	v_add_f32_dpp v96, v97, v97 quad_perm:[2,3,0,1] row_mask:0xf bank_mask:0xf
	s_nop 1
	v_add_f32_dpp v97, v96, v96 row_half_mirror row_mask:0xf bank_mask:0xf
	s_nop 1
	v_add_f32_dpp v96, v97, v97 row_mirror row_mask:0xf bank_mask:0xf
	s_nop 1
	v_readlane_b32 s16, v96, 0
	v_readlane_b32 s17, v96, 16
	v_readlane_b32 s18, v96, 32
	v_readlane_b32 s19, v96, 48
	s_nop 1
	v_mov_b32_e32 v96, s16
	v_add_f32_e32 v96, s17, v96
	v_add_f32_e32 v96, s18, v96
	v_add_f32_e32 v96, s19, v96
	v_mov_b32_e32 v98, 0x358637bd
	v_fmamk_f32 v96, v96, 0x3a800000, v98
	v_rsq_f32_e32 v96, v96
	s_nop 0
	v_pk_mul_f32 v[112:113], v[112:113], v[96:97] op_sel_hi:[1,0]
	v_pk_mul_f32 v[114:115], v[114:115], v[96:97] op_sel_hi:[1,0]
	v_pk_mul_f32 v[116:117], v[116:117], v[96:97] op_sel_hi:[1,0]
	v_pk_mul_f32 v[118:119], v[118:119], v[96:97] op_sel_hi:[1,0]
	v_pk_mul_f32 v[120:121], v[120:121], v[96:97] op_sel_hi:[1,0]
	v_pk_mul_f32 v[122:123], v[122:123], v[96:97] op_sel_hi:[1,0]
	v_pk_mul_f32 v[124:125], v[124:125], v[96:97] op_sel_hi:[1,0]
	v_pk_mul_f32 v[126:127], v[126:127], v[96:97] op_sel_hi:[1,0]
	v_pk_mul_f32 v[112:113], v[48:49], v[112:113]
	v_pk_mul_f32 v[114:115], v[50:51], v[114:115]
	v_pk_mul_f32 v[116:117], v[52:53], v[116:117]
	v_pk_mul_f32 v[118:119], v[54:55], v[118:119]
	v_pk_mul_f32 v[120:121], v[56:57], v[120:121]
	v_pk_mul_f32 v[122:123], v[58:59], v[122:123]
	v_pk_mul_f32 v[124:125], v[60:61], v[124:125]
	v_pk_mul_f32 v[126:127], v[62:63], v[126:127]
	v_pk_fma_f32 v[112:113], v[64:65], v[112:113], v[80:81]
	v_pk_fma_f32 v[114:115], v[66:67], v[114:115], v[82:83]
	v_pk_fma_f32 v[116:117], v[68:69], v[116:117], v[84:85]
	v_pk_fma_f32 v[118:119], v[70:71], v[118:119], v[86:87]
	v_pk_fma_f32 v[120:121], v[72:73], v[120:121], v[88:89]
	v_pk_fma_f32 v[122:123], v[74:75], v[122:123], v[90:91]
	v_pk_fma_f32 v[124:125], v[76:77], v[124:125], v[92:93]
	v_pk_fma_f32 v[126:127], v[78:79], v[126:127], v[94:95]
	v_cvt_pk_bf16_f32 v100, v112, v113
	v_cvt_pk_bf16_f32 v101, v114, v115
	v_cvt_pk_bf16_f32 v102, v116, v117
	v_cvt_pk_bf16_f32 v103, v118, v119
	v_cvt_pk_bf16_f32 v104, v120, v121
	v_cvt_pk_bf16_f32 v105, v122, v123
	v_cvt_pk_bf16_f32 v106, v124, v125
	v_cvt_pk_bf16_f32 v107, v126, v127
	s_add_u32 s8, s8, 0x400000
	s_addc_u32 s9, s9, 0
	global_store_dwordx2 v33, v[100:101], s[8:9]
	global_store_dwordx2 v33, v[102:103], s[8:9] offset:512
	global_store_dwordx2 v33, v[104:105], s[8:9] offset:1024
	global_store_dwordx2 v33, v[106:107], s[8:9] offset:1536
	s_add_u32 s6, s6, 0x800000
	s_addc_u32 s7, s7, 0
	global_load_dwordx4 v[112:115], v32, s[6:7]
	global_load_dwordx4 v[116:119], v32, s[6:7] offset:1024
	global_load_dwordx4 v[120:123], v32, s[6:7] offset:2048
	global_load_dwordx4 v[124:127], v32, s[6:7] offset:3072
	s_waitcnt vmcnt(16)
; __device__ __forceinline__ void store_bf4(bf16_t* p, f32x4 v) { uint2 o; o.x = pk2(v[0], v[1]); o.y = pk2(v[2], v[3]); *(uint2*)p = o; }
; __device__ __forceinline__ void norm_row_pre(const f32x4 (&v)[4], const float* __restrict__ g, const float* __restrict__ shift, const float* __restrict__ scale, bf16_t* __restrict__ dst, int lane) {
;     float ss = 0.f;
; #pragma unroll
;     for (int j = 0; j < 4; ++j) ss += v[j][0] * v[j][0] + v[j][1] * v[j][1] + v[j][2] * v[j][2] + v[j][3] * v[j][3];
;     ss = wave_sum(ss);
;     const float rstd = rsqrtf(ss * (1.f / 1024.f) + 1e-6f);
; #pragma unroll
;     for (int j = 0; j < 4; ++j) {
;         const int c4 = lane + 64 * j;
;         const f32x4 g4 = ((const f32x4*)g)[c4], sh = ((const f32x4*)shift)[c4], sc = ((const f32x4*)scale)[c4];
;         f32x4 h = (v[j] * rstd) * g4; h = h * (sc + 1.f) + sh;
;         store_bf4(dst + c4 * 4, h);
;     }
; __device__ __forceinline__ void phase1(const Params& P) {
;     ...
;         while (row < NT) {
;             f32x4 v[4];
; #pragma unroll
;             for (int j = 0; j < 4; ++j) v[j] = vn[j];
;             const int nrow = row + stride;
;             if (nrow < NT) { const float* src = nrow < NL ? P.in[0] + (size_t)nrow * 1024 : P.in[2] + (size_t)(nrow - NL) * 1024;
; #pragma unroll
;                 for (int j = 0; j < 4; ++j) vn[j] = ((const f32x4*)src)[lane + 64 * j]; }
;             const int mr = row < NL ? (row >> 13) : 4;
;             norm_row_pre(v, P.in[6], mod + mr * 9216 + 0, mod + mr * 9216 + 1024, H + (size_t)row * 1024, lane);
;             if (row >= NL) {
; #pragma unroll
;                 for (int j = 0; j < 4; ++j) ((f32x4*)((float*)(P.ws + OFF_E) + (size_t)(row - NL) * 1024))[lane + 64 * j] = v[j];
;             }
;             row = nrow;
	v_pk_add_f32 v[176:177], v[176:177], 1.0 op_sel_hi:[1,0]
	v_pk_add_f32 v[178:179], v[178:179], 1.0 op_sel_hi:[1,0]
	v_pk_add_f32 v[180:181], v[180:181], 1.0 op_sel_hi:[1,0]
	v_pk_add_f32 v[182:183], v[182:183], 1.0 op_sel_hi:[1,0]
	v_pk_add_f32 v[184:185], v[184:185], 1.0 op_sel_hi:[1,0]
	v_pk_add_f32 v[186:187], v[186:187], 1.0 op_sel_hi:[1,0]
	v_pk_add_f32 v[188:189], v[188:189], 1.0 op_sel_hi:[1,0]
	v_pk_add_f32 v[190:191], v[190:191], 1.0 op_sel_hi:[1,0]
	v_pk_mul_f32 v[96:97], v[128:129], v[128:129]
	v_pk_fma_f32 v[96:97], v[130:131], v[130:131], v[96:97]
	v_pk_fma_f32 v[96:97], v[132:133], v[132:133], v[96:97]
	v_pk_fma_f32 v[96:97], v[134:135], v[134:135], v[96:97]
	v_pk_fma_f32 v[96:97], v[136:137], v[136:137], v[96:97]
	v_pk_fma_f32 v[96:97], v[138:139], v[138:139], v[96:97]
	v_pk_fma_f32 v[96:97], v[140:141], v[140:141], v[96:97]
	v_pk_fma_f32 v[96:97], v[142:143], v[142:143], v[96:97]
	v_add_f32_e32 v96, v96, v97
	s_nop 1
	v_add_f32_dpp v97, v96, v96 quad_perm:[1,0,3,2] row_mask:0xf bank_mask:0xf
	s_nop 1
	v_add_f32_dpp v96, v97, v97 quad_perm:[2,3,0,1] row_mask:0xf bank_mask:0xf
	s_nop 1
	v_add_f32_dpp v97, v96, v96 row_half_mirror row_mask:0xf bank_mask:0xf
	s_nop 1
	v_add_f32_dpp v96, v97, v97 row_mirror row_mask:0xf bank_mask:0xf
	s_nop 1
	v_readlane_b32 s16, v96, 0
	v_readlane_b32 s17, v96, 16
	v_readlane_b32 s18, v96, 32
	v_readlane_b32 s19, v96, 48
	s_nop 1
	v_mov_b32_e32 v96, s16
	v_add_f32_e32 v96, s17, v96
	v_add_f32_e32 v96, s18, v96
	v_add_f32_e32 v96, s19, v96
	v_mov_b32_e32 v98, 0x358637bd
	v_fmamk_f32 v96, v96, 0x3a800000, v98
	v_rsq_f32_e32 v96, v96
	s_nop 0
	v_pk_mul_f32 v[128:129], v[128:129], v[96:97] op_sel_hi:[1,0]
	v_pk_mul_f32 v[130:131], v[130:131], v[96:97] op_sel_hi:[1,0]
	v_pk_mul_f32 v[132:133], v[132:133], v[96:97] op_sel_hi:[1,0]
	v_pk_mul_f32 v[134:135], v[134:135], v[96:97] op_sel_hi:[1,0]
	v_pk_mul_f32 v[136:137], v[136:137], v[96:97] op_sel_hi:[1,0]
	v_pk_mul_f32 v[138:139], v[138:139], v[96:97] op_sel_hi:[1,0]
	v_pk_mul_f32 v[140:141], v[140:141], v[96:97] op_sel_hi:[1,0]
	v_pk_mul_f32 v[142:143], v[142:143], v[96:97] op_sel_hi:[1,0]
	v_pk_mul_f32 v[128:129], v[48:49], v[128:129]
	v_pk_mul_f32 v[130:131], v[50:51], v[130:131]
	v_pk_mul_f32 v[132:133], v[52:53], v[132:133]
	v_pk_mul_f32 v[134:135], v[54:55], v[134:135]
	v_pk_mul_f32 v[136:137], v[56:57], v[136:137]
	v_pk_mul_f32 v[138:139], v[58:59], v[138:139]
	v_pk_mul_f32 v[140:141], v[60:61], v[140:141]
	v_pk_mul_f32 v[142:143], v[62:63], v[142:143]
	v_pk_fma_f32 v[128:129], v[176:177], v[128:129], v[192:193]
	v_pk_fma_f32 v[130:131], v[178:179], v[130:131], v[194:195]
	v_pk_fma_f32 v[132:133], v[180:181], v[132:133], v[196:197]
	v_pk_fma_f32 v[134:135], v[182:183], v[134:135], v[198:199]
	v_pk_fma_f32 v[136:137], v[184:185], v[136:137], v[200:201]
	v_pk_fma_f32 v[138:139], v[186:187], v[138:139], v[202:203]
	v_pk_fma_f32 v[140:141], v[188:189], v[140:141], v[204:205]
	v_pk_fma_f32 v[142:143], v[190:191], v[142:143], v[206:207]
	v_cvt_pk_bf16_f32 v100, v128, v129
	v_cvt_pk_bf16_f32 v101, v130, v131
	v_cvt_pk_bf16_f32 v102, v132, v133
	v_cvt_pk_bf16_f32 v103, v134, v135
	v_cvt_pk_bf16_f32 v104, v136, v137
	v_cvt_pk_bf16_f32 v105, v138, v139
	v_cvt_pk_bf16_f32 v106, v140, v141
	v_cvt_pk_bf16_f32 v107, v142, v143
	s_add_u32 s8, s8, 0x400000
	s_addc_u32 s9, s9, 0
	global_store_dwordx2 v33, v[100:101], s[8:9]
	global_store_dwordx2 v33, v[102:103], s[8:9] offset:512
	global_store_dwordx2 v33, v[104:105], s[8:9] offset:1024
	global_store_dwordx2 v33, v[106:107], s[8:9] offset:1536
	s_add_u32 s6, s6, 0x800000
	s_addc_u32 s7, s7, 0
	global_load_dwordx4 v[128:131], v32, s[6:7]
	global_load_dwordx4 v[132:135], v32, s[6:7] offset:1024
	global_load_dwordx4 v[136:139], v32, s[6:7] offset:2048
	global_load_dwordx4 v[140:143], v32, s[6:7] offset:3072
	s_waitcnt vmcnt(16)
	v_pk_mul_f32 v[96:97], v[144:145], v[144:145]
	v_pk_fma_f32 v[96:97], v[146:147], v[146:147], v[96:97]
	v_pk_fma_f32 v[96:97], v[148:149], v[148:149], v[96:97]
	v_pk_fma_f32 v[96:97], v[150:151], v[150:151], v[96:97]
	v_pk_fma_f32 v[96:97], v[152:153], v[152:153], v[96:97]
	v_pk_fma_f32 v[96:97], v[154:155], v[154:155], v[96:97]
	v_pk_fma_f32 v[96:97], v[156:157], v[156:157], v[96:97]
	v_pk_fma_f32 v[96:97], v[158:159], v[158:159], v[96:97]
	v_add_f32_e32 v96, v96, v97
	s_nop 1
	v_add_f32_dpp v97, v96, v96 quad_perm:[1,0,3,2] row_mask:0xf bank_mask:0xf
	s_nop 1
	v_add_f32_dpp v96, v97, v97 quad_perm:[2,3,0,1] row_mask:0xf bank_mask:0xf
	s_nop 1
	v_add_f32_dpp v97, v96, v96 row_half_mirror row_mask:0xf bank_mask:0xf
	s_nop 1
	v_add_f32_dpp v96, v97, v97 row_mirror row_mask:0xf bank_mask:0xf
	s_nop 1
	v_readlane_b32 s16, v96, 0
	v_readlane_b32 s17, v96, 16
	v_readlane_b32 s18, v96, 32
	v_readlane_b32 s19, v96, 48
	s_nop 1
	v_mov_b32_e32 v96, s16
	v_add_f32_e32 v96, s17, v96
	v_add_f32_e32 v96, s18, v96
	v_add_f32_e32 v96, s19, v96
	v_mov_b32_e32 v98, 0x358637bd
	v_fmamk_f32 v96, v96, 0x3a800000, v98
	v_rsq_f32_e32 v96, v96
	s_nop 0
	v_pk_mul_f32 v[144:145], v[144:145], v[96:97] op_sel_hi:[1,0]
	v_pk_mul_f32 v[146:147], v[146:147], v[96:97] op_sel_hi:[1,0]
	v_pk_mul_f32 v[148:149], v[148:149], v[96:97] op_sel_hi:[1,0]
	v_pk_mul_f32 v[150:151], v[150:151], v[96:97] op_sel_hi:[1,0]
	v_pk_mul_f32 v[152:153], v[152:153], v[96:97] op_sel_hi:[1,0]
	v_pk_mul_f32 v[154:155], v[154:155], v[96:97] op_sel_hi:[1,0]
	v_pk_mul_f32 v[156:157], v[156:157], v[96:97] op_sel_hi:[1,0]
	v_pk_mul_f32 v[158:159], v[158:159], v[96:97] op_sel_hi:[1,0]
	v_pk_mul_f32 v[144:145], v[48:49], v[144:145]
	v_pk_mul_f32 v[146:147], v[50:51], v[146:147]
	v_pk_mul_f32 v[148:149], v[52:53], v[148:149]
; __device__ __forceinline__ void store_bf4(bf16_t* p, f32x4 v) { uint2 o; o.x = pk2(v[0], v[1]); o.y = pk2(v[2], v[3]); *(uint2*)p = o; }
; __device__ __forceinline__ void norm_row_pre(const f32x4 (&v)[4], const float* __restrict__ g, const float* __restrict__ shift, const float* __restrict__ scale, bf16_t* __restrict__ dst, int lane) {
;     float ss = 0.f;
; #pragma unroll
;     for (int j = 0; j < 4; ++j) ss += v[j][0] * v[j][0] + v[j][1] * v[j][1] + v[j][2] * v[j][2] + v[j][3] * v[j][3];
;     ss = wave_sum(ss);
;     const float rstd = rsqrtf(ss * (1.f / 1024.f) + 1e-6f);
; #pragma unroll
;     for (int j = 0; j < 4; ++j) {
;         const int c4 = lane + 64 * j;
;         const f32x4 g4 = ((const f32x4*)g)[c4], sh = ((const f32x4*)shift)[c4], sc = ((const f32x4*)scale)[c4];
;         f32x4 h = (v[j] * rstd) * g4; h = h * (sc + 1.f) + sh;
;         store_bf4(dst + c4 * 4, h);
;     }
; __device__ __forceinline__ void phase1(const Params& P) {
;     ...
;         while (row < NT) {
;             f32x4 v[4];
; #pragma unroll
;             for (int j = 0; j < 4; ++j) v[j] = vn[j];
;             const int nrow = row + stride;
;             if (nrow < NT) { const float* src = nrow < NL ? P.in[0] + (size_t)nrow * 1024 : P.in[2] + (size_t)(nrow - NL) * 1024;
; #pragma unroll
;                 for (int j = 0; j < 4; ++j) vn[j] = ((const f32x4*)src)[lane + 64 * j]; }
;             const int mr = row < NL ? (row >> 13) : 4;
;             norm_row_pre(v, P.in[6], mod + mr * 9216 + 0, mod + mr * 9216 + 1024, H + (size_t)row * 1024, lane);
;             if (row >= NL) {
; #pragma unroll
;                 for (int j = 0; j < 4; ++j) ((f32x4*)((float*)(P.ws + OFF_E) + (size_t)(row - NL) * 1024))[lane + 64 * j] = v[j];
;             }
;             row = nrow;
	v_pk_mul_f32 v[150:151], v[54:55], v[150:151]
	v_pk_mul_f32 v[152:153], v[56:57], v[152:153]
	v_pk_mul_f32 v[154:155], v[58:59], v[154:155]
	v_pk_mul_f32 v[156:157], v[60:61], v[156:157]
	v_pk_mul_f32 v[158:159], v[62:63], v[158:159]
	v_pk_fma_f32 v[144:145], v[176:177], v[144:145], v[192:193]
	v_pk_fma_f32 v[146:147], v[178:179], v[146:147], v[194:195]
	v_pk_fma_f32 v[148:149], v[180:181], v[148:149], v[196:197]
	v_pk_fma_f32 v[150:151], v[182:183], v[150:151], v[198:199]
	v_pk_fma_f32 v[152:153], v[184:185], v[152:153], v[200:201]
	v_pk_fma_f32 v[154:155], v[186:187], v[154:155], v[202:203]
	v_pk_fma_f32 v[156:157], v[188:189], v[156:157], v[204:205]
	v_pk_fma_f32 v[158:159], v[190:191], v[158:159], v[206:207]
	v_cvt_pk_bf16_f32 v100, v144, v145
	v_cvt_pk_bf16_f32 v101, v146, v147
	v_cvt_pk_bf16_f32 v102, v148, v149
	v_cvt_pk_bf16_f32 v103, v150, v151
	v_cvt_pk_bf16_f32 v104, v152, v153
	v_cvt_pk_bf16_f32 v105, v154, v155
	v_cvt_pk_bf16_f32 v106, v156, v157
	v_cvt_pk_bf16_f32 v107, v158, v159
	s_add_u32 s8, s8, 0x400000
	s_addc_u32 s9, s9, 0
	global_store_dwordx2 v33, v[100:101], s[8:9]
	global_store_dwordx2 v33, v[102:103], s[8:9] offset:512
	global_store_dwordx2 v33, v[104:105], s[8:9] offset:1024
	global_store_dwordx2 v33, v[106:107], s[8:9] offset:1536
	s_add_u32 s6, s6, 0x800000
	s_addc_u32 s7, s7, 0
	global_load_dwordx4 v[144:147], v32, s[6:7]
	global_load_dwordx4 v[148:151], v32, s[6:7] offset:1024
	global_load_dwordx4 v[152:155], v32, s[6:7] offset:2048
	global_load_dwordx4 v[156:159], v32, s[6:7] offset:3072
	s_mov_b32 s10, 73728
	s_add_u32 s12, s2, s10
	s_addc_u32 s13, s3, 0
	s_add_u32 s14, s12, 0x1000
	s_addc_u32 s15, s13, 0
	global_load_dwordx4 v[80:83], v32, s[12:13]
	global_load_dwordx4 v[84:87], v32, s[12:13] offset:1024
	global_load_dwordx4 v[88:91], v32, s[12:13] offset:2048
	global_load_dwordx4 v[92:95], v32, s[12:13] offset:3072
	global_load_dwordx4 v[64:67], v32, s[14:15]
	global_load_dwordx4 v[68:71], v32, s[14:15] offset:1024
	global_load_dwordx4 v[72:75], v32, s[14:15] offset:2048
	global_load_dwordx4 v[76:79], v32, s[14:15] offset:3072
	s_waitcnt vmcnt(24)
	v_pk_mul_f32 v[96:97], v[112:113], v[112:113]
	v_pk_fma_f32 v[96:97], v[114:115], v[114:115], v[96:97]
	v_pk_fma_f32 v[96:97], v[116:117], v[116:117], v[96:97]
	v_pk_fma_f32 v[96:97], v[118:119], v[118:119], v[96:97]
	v_pk_fma_f32 v[96:97], v[120:121], v[120:121], v[96:97]
	v_pk_fma_f32 v[96:97], v[122:123], v[122:123], v[96:97]
	v_pk_fma_f32 v[96:97], v[124:125], v[124:125], v[96:97]
	v_pk_fma_f32 v[96:97], v[126:127], v[126:127], v[96:97]
	v_add_f32_e32 v96, v96, v97
	s_nop 1
	v_add_f32_dpp v97, v96, v96 quad_perm:[1,0,3,2] row_mask:0xf bank_mask:0xf
	s_nop 1
	v_add_f32_dpp v96, v97, v97 quad_perm:[2,3,0,1] row_mask:0xf bank_mask:0xf
	s_nop 1
	v_add_f32_dpp v97, v96, v96 row_half_mirror row_mask:0xf bank_mask:0xf
	s_nop 1
	v_add_f32_dpp v96, v97, v97 row_mirror row_mask:0xf bank_mask:0xf
	s_nop 1
	v_readlane_b32 s16, v96, 0
	v_readlane_b32 s17, v96, 16
	v_readlane_b32 s18, v96, 32
	v_readlane_b32 s19, v96, 48
	s_nop 1
	v_mov_b32_e32 v96, s16
	v_add_f32_e32 v96, s17, v96
	v_add_f32_e32 v96, s18, v96
	v_add_f32_e32 v96, s19, v96
	v_mov_b32_e32 v98, 0x358637bd
	v_fmamk_f32 v96, v96, 0x3a800000, v98
	v_rsq_f32_e32 v96, v96
	s_nop 0
	v_pk_mul_f32 v[112:113], v[112:113], v[96:97] op_sel_hi:[1,0]
	v_pk_mul_f32 v[114:115], v[114:115], v[96:97] op_sel_hi:[1,0]
	v_pk_mul_f32 v[116:117], v[116:117], v[96:97] op_sel_hi:[1,0]
	v_pk_mul_f32 v[118:119], v[118:119], v[96:97] op_sel_hi:[1,0]
	v_pk_mul_f32 v[120:121], v[120:121], v[96:97] op_sel_hi:[1,0]
	v_pk_mul_f32 v[122:123], v[122:123], v[96:97] op_sel_hi:[1,0]
	v_pk_mul_f32 v[124:125], v[124:125], v[96:97] op_sel_hi:[1,0]
	v_pk_mul_f32 v[126:127], v[126:127], v[96:97] op_sel_hi:[1,0]
	v_pk_mul_f32 v[112:113], v[48:49], v[112:113]
	v_pk_mul_f32 v[114:115], v[50:51], v[114:115]
	v_pk_mul_f32 v[116:117], v[52:53], v[116:117]
	v_pk_mul_f32 v[118:119], v[54:55], v[118:119]
	v_pk_mul_f32 v[120:121], v[56:57], v[120:121]
	v_pk_mul_f32 v[122:123], v[58:59], v[122:123]
	v_pk_mul_f32 v[124:125], v[60:61], v[124:125]
	v_pk_mul_f32 v[126:127], v[62:63], v[126:127]
	v_pk_fma_f32 v[112:113], v[176:177], v[112:113], v[192:193]
	v_pk_fma_f32 v[114:115], v[178:179], v[114:115], v[194:195]
	v_pk_fma_f32 v[116:117], v[180:181], v[116:117], v[196:197]
	v_pk_fma_f32 v[118:119], v[182:183], v[118:119], v[198:199]
	v_pk_fma_f32 v[120:121], v[184:185], v[120:121], v[200:201]
	v_pk_fma_f32 v[122:123], v[186:187], v[122:123], v[202:203]
	v_pk_fma_f32 v[124:125], v[188:189], v[124:125], v[204:205]
	v_pk_fma_f32 v[126:127], v[190:191], v[126:127], v[206:207]
	v_cvt_pk_bf16_f32 v100, v112, v113
	v_cvt_pk_bf16_f32 v101, v114, v115
	v_cvt_pk_bf16_f32 v102, v116, v117
	v_cvt_pk_bf16_f32 v103, v118, v119
	v_cvt_pk_bf16_f32 v104, v120, v121
	v_cvt_pk_bf16_f32 v105, v122, v123
	v_cvt_pk_bf16_f32 v106, v124, v125
	v_cvt_pk_bf16_f32 v107, v126, v127
	s_add_u32 s8, s8, 0x400000
	s_addc_u32 s9, s9, 0
	global_store_dwordx2 v33, v[100:101], s[8:9]
	global_store_dwordx2 v33, v[102:103], s[8:9] offset:512
	global_store_dwordx2 v33, v[104:105], s[8:9] offset:1024
	global_store_dwordx2 v33, v[106:107], s[8:9] offset:1536
	s_add_u32 s6, s6, 0x800000
	s_addc_u32 s7, s7, 0
	global_load_dwordx4 v[112:115], v32, s[6:7]
	global_load_dwordx4 v[116:119], v32, s[6:7] offset:1024
	global_load_dwordx4 v[120:123], v32, s[6:7] offset:2048
	global_load_dwordx4 v[124:127], v32, s[6:7] offset:3072
	s_waitcnt vmcnt(24)
; __device__ __forceinline__ void store_bf4(bf16_t* p, f32x4 v) { uint2 o; o.x = pk2(v[0], v[1]); o.y = pk2(v[2], v[3]); *(uint2*)p = o; }
; __device__ __forceinline__ void norm_row_pre(const f32x4 (&v)[4], const float* __restrict__ g, const float* __restrict__ shift, const float* __restrict__ scale, bf16_t* __restrict__ dst, int lane) {
;     float ss = 0.f;
; #pragma unroll
;     for (int j = 0; j < 4; ++j) ss += v[j][0] * v[j][0] + v[j][1] * v[j][1] + v[j][2] * v[j][2] + v[j][3] * v[j][3];
;     ss = wave_sum(ss);
;     const float rstd = rsqrtf(ss * (1.f / 1024.f) + 1e-6f);
; #pragma unroll
;     for (int j = 0; j < 4; ++j) {
;         const int c4 = lane + 64 * j;
;         const f32x4 g4 = ((const f32x4*)g)[c4], sh = ((const f32x4*)shift)[c4], sc = ((const f32x4*)scale)[c4];
;         f32x4 h = (v[j] * rstd) * g4; h = h * (sc + 1.f) + sh;
;         store_bf4(dst + c4 * 4, h);
;     }
; __device__ __forceinline__ void phase1(const Params& P) {
;     ...
;         while (row < NT) {
;             f32x4 v[4];
; #pragma unroll
;             for (int j = 0; j < 4; ++j) v[j] = vn[j];
;             const int nrow = row + stride;
;             if (nrow < NT) { const float* src = nrow < NL ? P.in[0] + (size_t)nrow * 1024 : P.in[2] + (size_t)(nrow - NL) * 1024;
; #pragma unroll
;                 for (int j = 0; j < 4; ++j) vn[j] = ((const f32x4*)src)[lane + 64 * j]; }
;             const int mr = row < NL ? (row >> 13) : 4;
;             norm_row_pre(v, P.in[6], mod + mr * 9216 + 0, mod + mr * 9216 + 1024, H + (size_t)row * 1024, lane);
;             if (row >= NL) {
; #pragma unroll
;                 for (int j = 0; j < 4; ++j) ((f32x4*)((float*)(P.ws + OFF_E) + (size_t)(row - NL) * 1024))[lane + 64 * j] = v[j];
;             }
;             row = nrow;
	v_pk_mul_f32 v[96:97], v[128:129], v[128:129]
	v_pk_fma_f32 v[96:97], v[130:131], v[130:131], v[96:97]
	v_pk_fma_f32 v[96:97], v[132:133], v[132:133], v[96:97]
	v_pk_fma_f32 v[96:97], v[134:135], v[134:135], v[96:97]
	v_pk_fma_f32 v[96:97], v[136:137], v[136:137], v[96:97]
	v_pk_fma_f32 v[96:97], v[138:139], v[138:139], v[96:97]
	v_pk_fma_f32 v[96:97], v[140:141], v[140:141], v[96:97]
	v_pk_fma_f32 v[96:97], v[142:143], v[142:143], v[96:97]
	v_add_f32_e32 v96, v96, v97
	s_nop 1
	v_add_f32_dpp v97, v96, v96 quad_perm:[1,0,3,2] row_mask:0xf bank_mask:0xf
	s_nop 1
	v_add_f32_dpp v96, v97, v97 quad_perm:[2,3,0,1] row_mask:0xf bank_mask:0xf
	s_nop 1
	v_add_f32_dpp v97, v96, v96 row_half_mirror row_mask:0xf bank_mask:0xf
	s_nop 1
	v_add_f32_dpp v96, v97, v97 row_mirror row_mask:0xf bank_mask:0xf
	s_nop 1
	v_readlane_b32 s16, v96, 0
	v_readlane_b32 s17, v96, 16
	v_readlane_b32 s18, v96, 32
	v_readlane_b32 s19, v96, 48
	s_nop 1
	v_mov_b32_e32 v96, s16
	v_add_f32_e32 v96, s17, v96
	v_add_f32_e32 v96, s18, v96
	v_add_f32_e32 v96, s19, v96
	v_mov_b32_e32 v98, 0x358637bd
	v_fmamk_f32 v96, v96, 0x3a800000, v98
	v_rsq_f32_e32 v96, v96
	s_nop 0
	v_pk_mul_f32 v[128:129], v[128:129], v[96:97] op_sel_hi:[1,0]
	v_pk_mul_f32 v[130:131], v[130:131], v[96:97] op_sel_hi:[1,0]
	v_pk_mul_f32 v[132:133], v[132:133], v[96:97] op_sel_hi:[1,0]
	v_pk_mul_f32 v[134:135], v[134:135], v[96:97] op_sel_hi:[1,0]
	v_pk_mul_f32 v[136:137], v[136:137], v[96:97] op_sel_hi:[1,0]
	v_pk_mul_f32 v[138:139], v[138:139], v[96:97] op_sel_hi:[1,0]
	v_pk_mul_f32 v[140:141], v[140:141], v[96:97] op_sel_hi:[1,0]
	v_pk_mul_f32 v[142:143], v[142:143], v[96:97] op_sel_hi:[1,0]
	v_pk_mul_f32 v[128:129], v[48:49], v[128:129]
	v_pk_mul_f32 v[130:131], v[50:51], v[130:131]
	v_pk_mul_f32 v[132:133], v[52:53], v[132:133]
	v_pk_mul_f32 v[134:135], v[54:55], v[134:135]
	v_pk_mul_f32 v[136:137], v[56:57], v[136:137]
	v_pk_mul_f32 v[138:139], v[58:59], v[138:139]
	v_pk_mul_f32 v[140:141], v[60:61], v[140:141]
	v_pk_mul_f32 v[142:143], v[62:63], v[142:143]
	v_pk_fma_f32 v[128:129], v[176:177], v[128:129], v[192:193]
	v_pk_fma_f32 v[130:131], v[178:179], v[130:131], v[194:195]
	v_pk_fma_f32 v[132:133], v[180:181], v[132:133], v[196:197]
	v_pk_fma_f32 v[134:135], v[182:183], v[134:135], v[198:199]
	v_pk_fma_f32 v[136:137], v[184:185], v[136:137], v[200:201]
	v_pk_fma_f32 v[138:139], v[186:187], v[138:139], v[202:203]
	v_pk_fma_f32 v[140:141], v[188:189], v[140:141], v[204:205]
	v_pk_fma_f32 v[142:143], v[190:191], v[142:143], v[206:207]
	v_cvt_pk_bf16_f32 v100, v128, v129
	v_cvt_pk_bf16_f32 v101, v130, v131
	v_cvt_pk_bf16_f32 v102, v132, v133
	v_cvt_pk_bf16_f32 v103, v134, v135
	v_cvt_pk_bf16_f32 v104, v136, v137
	v_cvt_pk_bf16_f32 v105, v138, v139
	v_cvt_pk_bf16_f32 v106, v140, v141
	v_cvt_pk_bf16_f32 v107, v142, v143
	s_add_u32 s8, s8, 0x400000
	s_addc_u32 s9, s9, 0
	global_store_dwordx2 v33, v[100:101], s[8:9]
	global_store_dwordx2 v33, v[102:103], s[8:9] offset:512
	global_store_dwordx2 v33, v[104:105], s[8:9] offset:1024
	global_store_dwordx2 v33, v[106:107], s[8:9] offset:1536
	s_add_u32 s6, s6, 0x800000
	s_addc_u32 s7, s7, 0
	global_load_dwordx4 v[128:131], v32, s[6:7]
	global_load_dwordx4 v[132:135], v32, s[6:7] offset:1024
	global_load_dwordx4 v[136:139], v32, s[6:7] offset:2048
	global_load_dwordx4 v[140:143], v32, s[6:7] offset:3072
	s_waitcnt vmcnt(16)
	v_pk_add_f32 v[64:65], v[64:65], 1.0 op_sel_hi:[1,0]
	v_pk_add_f32 v[66:67], v[66:67], 1.0 op_sel_hi:[1,0]
	v_pk_add_f32 v[68:69], v[68:69], 1.0 op_sel_hi:[1,0]
	v_pk_add_f32 v[70:71], v[70:71], 1.0 op_sel_hi:[1,0]
	v_pk_add_f32 v[72:73], v[72:73], 1.0 op_sel_hi:[1,0]
	v_pk_add_f32 v[74:75], v[74:75], 1.0 op_sel_hi:[1,0]
	v_pk_add_f32 v[76:77], v[76:77], 1.0 op_sel_hi:[1,0]
	v_pk_add_f32 v[78:79], v[78:79], 1.0 op_sel_hi:[1,0]
	v_pk_mul_f32 v[96:97], v[144:145], v[144:145]
	v_pk_fma_f32 v[96:97], v[146:147], v[146:147], v[96:97]
	v_pk_fma_f32 v[96:97], v[148:149], v[148:149], v[96:97]
	v_pk_fma_f32 v[96:97], v[150:151], v[150:151], v[96:97]
	v_pk_fma_f32 v[96:97], v[152:153], v[152:153], v[96:97]
	v_pk_fma_f32 v[96:97], v[154:155], v[154:155], v[96:97]
	v_pk_fma_f32 v[96:97], v[156:157], v[156:157], v[96:97]
	v_pk_fma_f32 v[96:97], v[158:159], v[158:159], v[96:97]
	v_add_f32_e32 v96, v96, v97
	s_nop 1
	v_add_f32_dpp v97, v96, v96 quad_perm:[1,0,3,2] row_mask:0xf bank_mask:0xf
	s_nop 1
	v_add_f32_dpp v96, v97, v97 quad_perm:[2,3,0,1] row_mask:0xf bank_mask:0xf
	s_nop 1
	v_add_f32_dpp v97, v96, v96 row_half_mirror row_mask:0xf bank_mask:0xf
	s_nop 1
	v_add_f32_dpp v96, v97, v97 row_mirror row_mask:0xf bank_mask:0xf
	s_nop 1
	v_readlane_b32 s16, v96, 0
	v_readlane_b32 s17, v96, 16
	v_readlane_b32 s18, v96, 32
	v_readlane_b32 s19, v96, 48
	s_nop 1
	v_mov_b32_e32 v96, s16
	v_add_f32_e32 v96, s17, v96
	v_add_f32_e32 v96, s18, v96
	v_add_f32_e32 v96, s19, v96
	v_mov_b32_e32 v98, 0x358637bd
	v_fmamk_f32 v96, v96, 0x3a800000, v98
	v_rsq_f32_e32 v96, v96
	s_nop 0
	v_pk_mul_f32 v[144:145], v[144:145], v[96:97] op_sel_hi:[1,0]
	v_pk_mul_f32 v[146:147], v[146:147], v[96:97] op_sel_hi:[1,0]
	v_pk_mul_f32 v[148:149], v[148:149], v[96:97] op_sel_hi:[1,0]
	v_pk_mul_f32 v[150:151], v[150:151], v[96:97] op_sel_hi:[1,0]
	v_pk_mul_f32 v[152:153], v[152:153], v[96:97] op_sel_hi:[1,0]
	v_pk_mul_f32 v[154:155], v[154:155], v[96:97] op_sel_hi:[1,0]
	v_pk_mul_f32 v[156:157], v[156:157], v[96:97] op_sel_hi:[1,0]
	v_pk_mul_f32 v[158:159], v[158:159], v[96:97] op_sel_hi:[1,0]
	v_pk_mul_f32 v[144:145], v[48:49], v[144:145]
	v_pk_mul_f32 v[146:147], v[50:51], v[146:147]
	v_pk_mul_f32 v[148:149], v[52:53], v[148:149]
	v_pk_mul_f32 v[150:151], v[54:55], v[150:151]
; __device__ __forceinline__ void store_bf4(bf16_t* p, f32x4 v) { uint2 o; o.x = pk2(v[0], v[1]); o.y = pk2(v[2], v[3]); *(uint2*)p = o; }
; __device__ __forceinline__ void norm_row_pre(const f32x4 (&v)[4], const float* __restrict__ g, const float* __restrict__ shift, const float* __restrict__ scale, bf16_t* __restrict__ dst, int lane) {
;     float ss = 0.f;
; #pragma unroll
;     for (int j = 0; j < 4; ++j) ss += v[j][0] * v[j][0] + v[j][1] * v[j][1] + v[j][2] * v[j][2] + v[j][3] * v[j][3];
;     ss = wave_sum(ss);
;     const float rstd = rsqrtf(ss * (1.f / 1024.f) + 1e-6f);
; #pragma unroll
;     for (int j = 0; j < 4; ++j) {
;         const int c4 = lane + 64 * j;
;         const f32x4 g4 = ((const f32x4*)g)[c4], sh = ((const f32x4*)shift)[c4], sc = ((const f32x4*)scale)[c4];
;         f32x4 h = (v[j] * rstd) * g4; h = h * (sc + 1.f) + sh;
;         store_bf4(dst + c4 * 4, h);
;     }
; __device__ __forceinline__ void phase1(const Params& P) {
;     ...
;         while (row < NT) {
;             f32x4 v[4];
; #pragma unroll
;             for (int j = 0; j < 4; ++j) v[j] = vn[j];
;             const int nrow = row + stride;
;             if (nrow < NT) { const float* src = nrow < NL ? P.in[0] + (size_t)nrow * 1024 : P.in[2] + (size_t)(nrow - NL) * 1024;
; #pragma unroll
;                 for (int j = 0; j < 4; ++j) vn[j] = ((const f32x4*)src)[lane + 64 * j]; }
;             const int mr = row < NL ? (row >> 13) : 4;
;             norm_row_pre(v, P.in[6], mod + mr * 9216 + 0, mod + mr * 9216 + 1024, H + (size_t)row * 1024, lane);
;             if (row >= NL) {
; #pragma unroll
;                 for (int j = 0; j < 4; ++j) ((f32x4*)((float*)(P.ws + OFF_E) + (size_t)(row - NL) * 1024))[lane + 64 * j] = v[j];
;             }
;             row = nrow;
	v_pk_mul_f32 v[152:153], v[56:57], v[152:153]
	v_pk_mul_f32 v[154:155], v[58:59], v[154:155]
	v_pk_mul_f32 v[156:157], v[60:61], v[156:157]
	v_pk_mul_f32 v[158:159], v[62:63], v[158:159]
	v_pk_fma_f32 v[144:145], v[64:65], v[144:145], v[80:81]
	v_pk_fma_f32 v[146:147], v[66:67], v[146:147], v[82:83]
	v_pk_fma_f32 v[148:149], v[68:69], v[148:149], v[84:85]
	v_pk_fma_f32 v[150:151], v[70:71], v[150:151], v[86:87]
	v_pk_fma_f32 v[152:153], v[72:73], v[152:153], v[88:89]
	v_pk_fma_f32 v[154:155], v[74:75], v[154:155], v[90:91]
	v_pk_fma_f32 v[156:157], v[76:77], v[156:157], v[92:93]
	v_pk_fma_f32 v[158:159], v[78:79], v[158:159], v[94:95]
	v_cvt_pk_bf16_f32 v100, v144, v145
	v_cvt_pk_bf16_f32 v101, v146, v147
	v_cvt_pk_bf16_f32 v102, v148, v149
	v_cvt_pk_bf16_f32 v103, v150, v151
	v_cvt_pk_bf16_f32 v104, v152, v153
	v_cvt_pk_bf16_f32 v105, v154, v155
	v_cvt_pk_bf16_f32 v106, v156, v157
	v_cvt_pk_bf16_f32 v107, v158, v159
	s_add_u32 s8, s8, 0x400000
	s_addc_u32 s9, s9, 0
	global_store_dwordx2 v33, v[100:101], s[8:9]
	global_store_dwordx2 v33, v[102:103], s[8:9] offset:512
	global_store_dwordx2 v33, v[104:105], s[8:9] offset:1024
	global_store_dwordx2 v33, v[106:107], s[8:9] offset:1536
	s_add_u32 s6, s6, 0x800000
	s_addc_u32 s7, s7, 0
	global_load_dwordx4 v[144:147], v32, s[6:7]
	global_load_dwordx4 v[148:151], v32, s[6:7] offset:1024
	global_load_dwordx4 v[152:155], v32, s[6:7] offset:2048
	global_load_dwordx4 v[156:159], v32, s[6:7] offset:3072
	s_waitcnt vmcnt(16)
	v_pk_mul_f32 v[96:97], v[112:113], v[112:113]
	v_pk_fma_f32 v[96:97], v[114:115], v[114:115], v[96:97]
	v_pk_fma_f32 v[96:97], v[116:117], v[116:117], v[96:97]
	v_pk_fma_f32 v[96:97], v[118:119], v[118:119], v[96:97]
	v_pk_fma_f32 v[96:97], v[120:121], v[120:121], v[96:97]
	v_pk_fma_f32 v[96:97], v[122:123], v[122:123], v[96:97]
	v_pk_fma_f32 v[96:97], v[124:125], v[124:125], v[96:97]
	v_pk_fma_f32 v[96:97], v[126:127], v[126:127], v[96:97]
	v_add_f32_e32 v96, v96, v97
	s_nop 1
	v_add_f32_dpp v97, v96, v96 quad_perm:[1,0,3,2] row_mask:0xf bank_mask:0xf
	s_nop 1
	v_add_f32_dpp v96, v97, v97 quad_perm:[2,3,0,1] row_mask:0xf bank_mask:0xf
	s_nop 1
	v_add_f32_dpp v97, v96, v96 row_half_mirror row_mask:0xf bank_mask:0xf
	s_nop 1
	v_add_f32_dpp v96, v97, v97 row_mirror row_mask:0xf bank_mask:0xf
	s_nop 1
	v_readlane_b32 s16, v96, 0
	v_readlane_b32 s17, v96, 16
	v_readlane_b32 s18, v96, 32
	v_readlane_b32 s19, v96, 48
	s_nop 1
	v_mov_b32_e32 v96, s16
	v_add_f32_e32 v96, s17, v96
	v_add_f32_e32 v96, s18, v96
	v_add_f32_e32 v96, s19, v96
	v_mov_b32_e32 v98, 0x358637bd
	v_fmamk_f32 v96, v96, 0x3a800000, v98
	v_rsq_f32_e32 v96, v96
	s_nop 0
	v_pk_mul_f32 v[112:113], v[112:113], v[96:97] op_sel_hi:[1,0]
	v_pk_mul_f32 v[114:115], v[114:115], v[96:97] op_sel_hi:[1,0]
	v_pk_mul_f32 v[116:117], v[116:117], v[96:97] op_sel_hi:[1,0]
	v_pk_mul_f32 v[118:119], v[118:119], v[96:97] op_sel_hi:[1,0]
	v_pk_mul_f32 v[120:121], v[120:121], v[96:97] op_sel_hi:[1,0]
	v_pk_mul_f32 v[122:123], v[122:123], v[96:97] op_sel_hi:[1,0]
	v_pk_mul_f32 v[124:125], v[124:125], v[96:97] op_sel_hi:[1,0]
	v_pk_mul_f32 v[126:127], v[126:127], v[96:97] op_sel_hi:[1,0]
	v_pk_mul_f32 v[112:113], v[48:49], v[112:113]
	v_pk_mul_f32 v[114:115], v[50:51], v[114:115]
	v_pk_mul_f32 v[116:117], v[52:53], v[116:117]
	v_pk_mul_f32 v[118:119], v[54:55], v[118:119]
	v_pk_mul_f32 v[120:121], v[56:57], v[120:121]
	v_pk_mul_f32 v[122:123], v[58:59], v[122:123]
	v_pk_mul_f32 v[124:125], v[60:61], v[124:125]
	v_pk_mul_f32 v[126:127], v[62:63], v[126:127]
	v_pk_fma_f32 v[112:113], v[64:65], v[112:113], v[80:81]
	v_pk_fma_f32 v[114:115], v[66:67], v[114:115], v[82:83]
	v_pk_fma_f32 v[116:117], v[68:69], v[116:117], v[84:85]
	v_pk_fma_f32 v[118:119], v[70:71], v[118:119], v[86:87]
	v_pk_fma_f32 v[120:121], v[72:73], v[120:121], v[88:89]
	v_pk_fma_f32 v[122:123], v[74:75], v[122:123], v[90:91]
	v_pk_fma_f32 v[124:125], v[76:77], v[124:125], v[92:93]
	v_pk_fma_f32 v[126:127], v[78:79], v[126:127], v[94:95]
	v_cvt_pk_bf16_f32 v100, v112, v113
	v_cvt_pk_bf16_f32 v101, v114, v115
	v_cvt_pk_bf16_f32 v102, v116, v117
	v_cvt_pk_bf16_f32 v103, v118, v119
	v_cvt_pk_bf16_f32 v104, v120, v121
	v_cvt_pk_bf16_f32 v105, v122, v123
	v_cvt_pk_bf16_f32 v106, v124, v125
	v_cvt_pk_bf16_f32 v107, v126, v127
	s_add_u32 s8, s8, 0x400000
	s_addc_u32 s9, s9, 0
	global_store_dwordx2 v33, v[100:101], s[8:9]
	global_store_dwordx2 v33, v[102:103], s[8:9] offset:512
	global_store_dwordx2 v33, v[104:105], s[8:9] offset:1024
	global_store_dwordx2 v33, v[106:107], s[8:9] offset:1536
	s_add_u32 s6, s6, 0x800000
	s_addc_u32 s7, s7, 0
	global_load_dwordx4 v[112:115], v32, s[6:7]
	global_load_dwordx4 v[116:119], v32, s[6:7] offset:1024
	global_load_dwordx4 v[120:123], v32, s[6:7] offset:2048
	global_load_dwordx4 v[124:127], v32, s[6:7] offset:3072
	s_mov_b32 s10, 110592
	s_add_u32 s12, s2, s10
	s_addc_u32 s13, s3, 0
	s_add_u32 s14, s12, 0x1000
	s_addc_u32 s15, s13, 0
	global_load_dwordx4 v[192:195], v32, s[12:13]
	global_load_dwordx4 v[196:199], v32, s[12:13] offset:1024
	global_load_dwordx4 v[200:203], v32, s[12:13] offset:2048
	global_load_dwordx4 v[204:207], v32, s[12:13] offset:3072
	global_load_dwordx4 v[176:179], v32, s[14:15]
	global_load_dwordx4 v[180:183], v32, s[14:15] offset:1024
	global_load_dwordx4 v[184:187], v32, s[14:15] offset:2048
	global_load_dwordx4 v[188:191], v32, s[14:15] offset:3072
	s_waitcnt vmcnt(24)
; __device__ __forceinline__ void store_bf4(bf16_t* p, f32x4 v) { uint2 o; o.x = pk2(v[0], v[1]); o.y = pk2(v[2], v[3]); *(uint2*)p = o; }
; __device__ __forceinline__ void norm_row_pre(const f32x4 (&v)[4], const float* __restrict__ g, const float* __restrict__ shift, const float* __restrict__ scale, bf16_t* __restrict__ dst, int lane) {
;     float ss = 0.f;
; #pragma unroll
;     for (int j = 0; j < 4; ++j) ss += v[j][0] * v[j][0] + v[j][1] * v[j][1] + v[j][2] * v[j][2] + v[j][3] * v[j][3];
;     ss = wave_sum(ss);
;     const float rstd = rsqrtf(ss * (1.f / 1024.f) + 1e-6f);
; #pragma unroll
;     for (int j = 0; j < 4; ++j) {
;         const int c4 = lane + 64 * j;
;         const f32x4 g4 = ((const f32x4*)g)[c4], sh = ((const f32x4*)shift)[c4], sc = ((const f32x4*)scale)[c4];
;         f32x4 h = (v[j] * rstd) * g4; h = h * (sc + 1.f) + sh;
;         store_bf4(dst + c4 * 4, h);
;     }
; __device__ __forceinline__ void phase1(const Params& P) {
;     ...
;         while (row < NT) {
;             f32x4 v[4];
; #pragma unroll
;             for (int j = 0; j < 4; ++j) v[j] = vn[j];
;             const int nrow = row + stride;
;             if (nrow < NT) { const float* src = nrow < NL ? P.in[0] + (size_t)nrow * 1024 : P.in[2] + (size_t)(nrow - NL) * 1024;
; #pragma unroll
;                 for (int j = 0; j < 4; ++j) vn[j] = ((const f32x4*)src)[lane + 64 * j]; }
;             const int mr = row < NL ? (row >> 13) : 4;
;             norm_row_pre(v, P.in[6], mod + mr * 9216 + 0, mod + mr * 9216 + 1024, H + (size_t)row * 1024, lane);
;             if (row >= NL) {
; #pragma unroll
;                 for (int j = 0; j < 4; ++j) ((f32x4*)((float*)(P.ws + OFF_E) + (size_t)(row - NL) * 1024))[lane + 64 * j] = v[j];
;             }
;             row = nrow;
	v_pk_mul_f32 v[96:97], v[128:129], v[128:129]
	v_pk_fma_f32 v[96:97], v[130:131], v[130:131], v[96:97]
	v_pk_fma_f32 v[96:97], v[132:133], v[132:133], v[96:97]
	v_pk_fma_f32 v[96:97], v[134:135], v[134:135], v[96:97]
	v_pk_fma_f32 v[96:97], v[136:137], v[136:137], v[96:97]
	v_pk_fma_f32 v[96:97], v[138:139], v[138:139], v[96:97]
	v_pk_fma_f32 v[96:97], v[140:141], v[140:141], v[96:97]
	v_pk_fma_f32 v[96:97], v[142:143], v[142:143], v[96:97]
	v_add_f32_e32 v96, v96, v97
	s_nop 1
	v_add_f32_dpp v97, v96, v96 quad_perm:[1,0,3,2] row_mask:0xf bank_mask:0xf
	s_nop 1
	v_add_f32_dpp v96, v97, v97 quad_perm:[2,3,0,1] row_mask:0xf bank_mask:0xf
	s_nop 1
	v_add_f32_dpp v97, v96, v96 row_half_mirror row_mask:0xf bank_mask:0xf
	s_nop 1
	v_add_f32_dpp v96, v97, v97 row_mirror row_mask:0xf bank_mask:0xf
	s_nop 1
	v_readlane_b32 s16, v96, 0
	v_readlane_b32 s17, v96, 16
	v_readlane_b32 s18, v96, 32
	v_readlane_b32 s19, v96, 48
	s_nop 1
	v_mov_b32_e32 v96, s16
	v_add_f32_e32 v96, s17, v96
	v_add_f32_e32 v96, s18, v96
	v_add_f32_e32 v96, s19, v96
	v_mov_b32_e32 v98, 0x358637bd
	v_fmamk_f32 v96, v96, 0x3a800000, v98
	v_rsq_f32_e32 v96, v96
	s_nop 0
	v_pk_mul_f32 v[128:129], v[128:129], v[96:97] op_sel_hi:[1,0]
	v_pk_mul_f32 v[130:131], v[130:131], v[96:97] op_sel_hi:[1,0]
	v_pk_mul_f32 v[132:133], v[132:133], v[96:97] op_sel_hi:[1,0]
	v_pk_mul_f32 v[134:135], v[134:135], v[96:97] op_sel_hi:[1,0]
	v_pk_mul_f32 v[136:137], v[136:137], v[96:97] op_sel_hi:[1,0]
	v_pk_mul_f32 v[138:139], v[138:139], v[96:97] op_sel_hi:[1,0]
	v_pk_mul_f32 v[140:141], v[140:141], v[96:97] op_sel_hi:[1,0]
	v_pk_mul_f32 v[142:143], v[142:143], v[96:97] op_sel_hi:[1,0]
	v_pk_mul_f32 v[128:129], v[48:49], v[128:129]
	v_pk_mul_f32 v[130:131], v[50:51], v[130:131]
	v_pk_mul_f32 v[132:133], v[52:53], v[132:133]
	v_pk_mul_f32 v[134:135], v[54:55], v[134:135]
	v_pk_mul_f32 v[136:137], v[56:57], v[136:137]
	v_pk_mul_f32 v[138:139], v[58:59], v[138:139]
	v_pk_mul_f32 v[140:141], v[60:61], v[140:141]
	v_pk_mul_f32 v[142:143], v[62:63], v[142:143]
	v_pk_fma_f32 v[128:129], v[64:65], v[128:129], v[80:81]
	v_pk_fma_f32 v[130:131], v[66:67], v[130:131], v[82:83]
	v_pk_fma_f32 v[132:133], v[68:69], v[132:133], v[84:85]
	v_pk_fma_f32 v[134:135], v[70:71], v[134:135], v[86:87]
	v_pk_fma_f32 v[136:137], v[72:73], v[136:137], v[88:89]
	v_pk_fma_f32 v[138:139], v[74:75], v[138:139], v[90:91]
	v_pk_fma_f32 v[140:141], v[76:77], v[140:141], v[92:93]
	v_pk_fma_f32 v[142:143], v[78:79], v[142:143], v[94:95]
	v_cvt_pk_bf16_f32 v100, v128, v129
	v_cvt_pk_bf16_f32 v101, v130, v131
	v_cvt_pk_bf16_f32 v102, v132, v133
	v_cvt_pk_bf16_f32 v103, v134, v135
	v_cvt_pk_bf16_f32 v104, v136, v137
	v_cvt_pk_bf16_f32 v105, v138, v139
	v_cvt_pk_bf16_f32 v106, v140, v141
	v_cvt_pk_bf16_f32 v107, v142, v143
	s_add_u32 s8, s8, 0x400000
	s_addc_u32 s9, s9, 0
	global_store_dwordx2 v33, v[100:101], s[8:9]
	global_store_dwordx2 v33, v[102:103], s[8:9] offset:512
	global_store_dwordx2 v33, v[104:105], s[8:9] offset:1024
	global_store_dwordx2 v33, v[106:107], s[8:9] offset:1536
	s_add_u32 s6, s6, 0x800000
	s_addc_u32 s7, s7, 0
	global_load_dwordx4 v[128:131], v32, s[6:7]
	global_load_dwordx4 v[132:135], v32, s[6:7] offset:1024
	global_load_dwordx4 v[136:139], v32, s[6:7] offset:2048
	global_load_dwordx4 v[140:143], v32, s[6:7] offset:3072
	s_waitcnt vmcnt(24)
	v_pk_mul_f32 v[96:97], v[144:145], v[144:145]
	v_pk_fma_f32 v[96:97], v[146:147], v[146:147], v[96:97]
	v_pk_fma_f32 v[96:97], v[148:149], v[148:149], v[96:97]
	v_pk_fma_f32 v[96:97], v[150:151], v[150:151], v[96:97]
	v_pk_fma_f32 v[96:97], v[152:153], v[152:153], v[96:97]
	v_pk_fma_f32 v[96:97], v[154:155], v[154:155], v[96:97]
	v_pk_fma_f32 v[96:97], v[156:157], v[156:157], v[96:97]
	v_pk_fma_f32 v[96:97], v[158:159], v[158:159], v[96:97]
	v_add_f32_e32 v96, v96, v97
	s_nop 1
	v_add_f32_dpp v97, v96, v96 quad_perm:[1,0,3,2] row_mask:0xf bank_mask:0xf
	s_nop 1
	v_add_f32_dpp v96, v97, v97 quad_perm:[2,3,0,1] row_mask:0xf bank_mask:0xf
	s_nop 1
	v_add_f32_dpp v97, v96, v96 row_half_mirror row_mask:0xf bank_mask:0xf
	s_nop 1
	v_add_f32_dpp v96, v97, v97 row_mirror row_mask:0xf bank_mask:0xf
	s_nop 1
	v_readlane_b32 s16, v96, 0
	v_readlane_b32 s17, v96, 16
	v_readlane_b32 s18, v96, 32
	v_readlane_b32 s19, v96, 48
	s_nop 1
	v_mov_b32_e32 v96, s16
	v_add_f32_e32 v96, s17, v96
	v_add_f32_e32 v96, s18, v96
	v_add_f32_e32 v96, s19, v96
	v_mov_b32_e32 v98, 0x358637bd
	v_fmamk_f32 v96, v96, 0x3a800000, v98
	v_rsq_f32_e32 v96, v96
	s_nop 0
	v_pk_mul_f32 v[144:145], v[144:145], v[96:97] op_sel_hi:[1,0]
	v_pk_mul_f32 v[146:147], v[146:147], v[96:97] op_sel_hi:[1,0]
	v_pk_mul_f32 v[148:149], v[148:149], v[96:97] op_sel_hi:[1,0]
	v_pk_mul_f32 v[150:151], v[150:151], v[96:97] op_sel_hi:[1,0]
	v_pk_mul_f32 v[152:153], v[152:153], v[96:97] op_sel_hi:[1,0]
	v_pk_mul_f32 v[154:155], v[154:155], v[96:97] op_sel_hi:[1,0]
	v_pk_mul_f32 v[156:157], v[156:157], v[96:97] op_sel_hi:[1,0]
	v_pk_mul_f32 v[158:159], v[158:159], v[96:97] op_sel_hi:[1,0]
	v_pk_mul_f32 v[144:145], v[48:49], v[144:145]
	v_pk_mul_f32 v[146:147], v[50:51], v[146:147]
	v_pk_mul_f32 v[148:149], v[52:53], v[148:149]
	v_pk_mul_f32 v[150:151], v[54:55], v[150:151]
	v_pk_mul_f32 v[152:153], v[56:57], v[152:153]
	v_pk_mul_f32 v[154:155], v[58:59], v[154:155]
	v_pk_mul_f32 v[156:157], v[60:61], v[156:157]
	v_pk_mul_f32 v[158:159], v[62:63], v[158:159]
	v_pk_fma_f32 v[144:145], v[64:65], v[144:145], v[80:81]
	v_pk_fma_f32 v[146:147], v[66:67], v[146:147], v[82:83]
	v_pk_fma_f32 v[148:149], v[68:69], v[148:149], v[84:85]
	v_pk_fma_f32 v[150:151], v[70:71], v[150:151], v[86:87]
	v_pk_fma_f32 v[152:153], v[72:73], v[152:153], v[88:89]
	v_pk_fma_f32 v[154:155], v[74:75], v[154:155], v[90:91]
	v_pk_fma_f32 v[156:157], v[76:77], v[156:157], v[92:93]
	v_pk_fma_f32 v[158:159], v[78:79], v[158:159], v[94:95]
	v_cvt_pk_bf16_f32 v100, v144, v145
	v_cvt_pk_bf16_f32 v101, v146, v147
	v_cvt_pk_bf16_f32 v102, v148, v149
	v_cvt_pk_bf16_f32 v103, v150, v151
	v_cvt_pk_bf16_f32 v104, v152, v153
	v_cvt_pk_bf16_f32 v105, v154, v155
	v_cvt_pk_bf16_f32 v106, v156, v157
	v_cvt_pk_bf16_f32 v107, v158, v159
	s_add_u32 s8, s8, 0x400000
	s_addc_u32 s9, s9, 0
	global_store_dwordx2 v33, v[100:101], s[8:9]
	global_store_dwordx2 v33, v[102:103], s[8:9] offset:512
	global_store_dwordx2 v33, v[104:105], s[8:9] offset:1024
	global_store_dwordx2 v33, v[106:107], s[8:9] offset:1536
	s_add_u32 s6, s6, 0x800000
	s_addc_u32 s7, s7, 0
	global_load_dwordx4 v[144:147], v32, s[6:7]
	global_load_dwordx4 v[148:151], v32, s[6:7] offset:1024
	global_load_dwordx4 v[152:155], v32, s[6:7] offset:2048
	global_load_dwordx4 v[156:159], v32, s[6:7] offset:3072
	s_waitcnt vmcnt(16)
; __device__ __forceinline__ void store_bf4(bf16_t* p, f32x4 v) { uint2 o; o.x = pk2(v[0], v[1]); o.y = pk2(v[2], v[3]); *(uint2*)p = o; }
; __device__ __forceinline__ void norm_row_pre(const f32x4 (&v)[4], const float* __restrict__ g, const float* __restrict__ shift, const float* __restrict__ scale, bf16_t* __restrict__ dst, int lane) {
;     float ss = 0.f;
; #pragma unroll
;     for (int j = 0; j < 4; ++j) ss += v[j][0] * v[j][0] + v[j][1] * v[j][1] + v[j][2] * v[j][2] + v[j][3] * v[j][3];
;     ss = wave_sum(ss);
;     const float rstd = rsqrtf(ss * (1.f / 1024.f) + 1e-6f);
; #pragma unroll
;     for (int j = 0; j < 4; ++j) {
;         const int c4 = lane + 64 * j;
;         const f32x4 g4 = ((const f32x4*)g)[c4], sh = ((const f32x4*)shift)[c4], sc = ((const f32x4*)scale)[c4];
;         f32x4 h = (v[j] * rstd) * g4; h = h * (sc + 1.f) + sh;
;         store_bf4(dst + c4 * 4, h);
;     }
; __device__ __forceinline__ void phase1(const Params& P) {
;     ...
;         while (row < NT) {
;             f32x4 v[4];
; #pragma unroll
;             for (int j = 0; j < 4; ++j) v[j] = vn[j];
;             const int nrow = row + stride;
;             if (nrow < NT) { const float* src = nrow < NL ? P.in[0] + (size_t)nrow * 1024 : P.in[2] + (size_t)(nrow - NL) * 1024;
; #pragma unroll
;                 for (int j = 0; j < 4; ++j) vn[j] = ((const f32x4*)src)[lane + 64 * j]; }
;             const int mr = row < NL ? (row >> 13) : 4;
;             norm_row_pre(v, P.in[6], mod + mr * 9216 + 0, mod + mr * 9216 + 1024, H + (size_t)row * 1024, lane);
;             if (row >= NL) {
; #pragma unroll
;                 for (int j = 0; j < 4; ++j) ((f32x4*)((float*)(P.ws + OFF_E) + (size_t)(row - NL) * 1024))[lane + 64 * j] = v[j];
;             }
;             row = nrow;
	v_pk_add_f32 v[176:177], v[176:177], 1.0 op_sel_hi:[1,0]
	v_pk_add_f32 v[178:179], v[178:179], 1.0 op_sel_hi:[1,0]
	v_pk_add_f32 v[180:181], v[180:181], 1.0 op_sel_hi:[1,0]
	v_pk_add_f32 v[182:183], v[182:183], 1.0 op_sel_hi:[1,0]
	v_pk_add_f32 v[184:185], v[184:185], 1.0 op_sel_hi:[1,0]
	v_pk_add_f32 v[186:187], v[186:187], 1.0 op_sel_hi:[1,0]
	v_pk_add_f32 v[188:189], v[188:189], 1.0 op_sel_hi:[1,0]
	v_pk_add_f32 v[190:191], v[190:191], 1.0 op_sel_hi:[1,0]
	v_pk_mul_f32 v[96:97], v[112:113], v[112:113]
	v_pk_fma_f32 v[96:97], v[114:115], v[114:115], v[96:97]
	v_pk_fma_f32 v[96:97], v[116:117], v[116:117], v[96:97]
	v_pk_fma_f32 v[96:97], v[118:119], v[118:119], v[96:97]
	v_pk_fma_f32 v[96:97], v[120:121], v[120:121], v[96:97]
	v_pk_fma_f32 v[96:97], v[122:123], v[122:123], v[96:97]
	v_pk_fma_f32 v[96:97], v[124:125], v[124:125], v[96:97]
	v_pk_fma_f32 v[96:97], v[126:127], v[126:127], v[96:97]
	v_add_f32_e32 v96, v96, v97
	s_nop 1
	v_add_f32_dpp v97, v96, v96 quad_perm:[1,0,3,2] row_mask:0xf bank_mask:0xf
	s_nop 1
	v_add_f32_dpp v96, v97, v97 quad_perm:[2,3,0,1] row_mask:0xf bank_mask:0xf
	s_nop 1
	v_add_f32_dpp v97, v96, v96 row_half_mirror row_mask:0xf bank_mask:0xf
	s_nop 1
	v_add_f32_dpp v96, v97, v97 row_mirror row_mask:0xf bank_mask:0xf
	s_nop 1
	v_readlane_b32 s16, v96, 0
	v_readlane_b32 s17, v96, 16
	v_readlane_b32 s18, v96, 32
	v_readlane_b32 s19, v96, 48
	s_nop 1
	v_mov_b32_e32 v96, s16
	v_add_f32_e32 v96, s17, v96
	v_add_f32_e32 v96, s18, v96
	v_add_f32_e32 v96, s19, v96
	v_mov_b32_e32 v98, 0x358637bd
	v_fmamk_f32 v96, v96, 0x3a800000, v98
	v_rsq_f32_e32 v96, v96
	s_nop 0
	v_pk_mul_f32 v[112:113], v[112:113], v[96:97] op_sel_hi:[1,0]
	v_pk_mul_f32 v[114:115], v[114:115], v[96:97] op_sel_hi:[1,0]
	v_pk_mul_f32 v[116:117], v[116:117], v[96:97] op_sel_hi:[1,0]
	v_pk_mul_f32 v[118:119], v[118:119], v[96:97] op_sel_hi:[1,0]
	v_pk_mul_f32 v[120:121], v[120:121], v[96:97] op_sel_hi:[1,0]
	v_pk_mul_f32 v[122:123], v[122:123], v[96:97] op_sel_hi:[1,0]
	v_pk_mul_f32 v[124:125], v[124:125], v[96:97] op_sel_hi:[1,0]
	v_pk_mul_f32 v[126:127], v[126:127], v[96:97] op_sel_hi:[1,0]
	v_pk_mul_f32 v[112:113], v[48:49], v[112:113]
	v_pk_mul_f32 v[114:115], v[50:51], v[114:115]
	v_pk_mul_f32 v[116:117], v[52:53], v[116:117]
	v_pk_mul_f32 v[118:119], v[54:55], v[118:119]
	v_pk_mul_f32 v[120:121], v[56:57], v[120:121]
	v_pk_mul_f32 v[122:123], v[58:59], v[122:123]
	v_pk_mul_f32 v[124:125], v[60:61], v[124:125]
	v_pk_mul_f32 v[126:127], v[62:63], v[126:127]
	v_pk_fma_f32 v[112:113], v[176:177], v[112:113], v[192:193]
	v_pk_fma_f32 v[114:115], v[178:179], v[114:115], v[194:195]
	v_pk_fma_f32 v[116:117], v[180:181], v[116:117], v[196:197]
	v_pk_fma_f32 v[118:119], v[182:183], v[118:119], v[198:199]
	v_pk_fma_f32 v[120:121], v[184:185], v[120:121], v[200:201]
	v_pk_fma_f32 v[122:123], v[186:187], v[122:123], v[202:203]
	v_pk_fma_f32 v[124:125], v[188:189], v[124:125], v[204:205]
	v_pk_fma_f32 v[126:127], v[190:191], v[126:127], v[206:207]
	v_cvt_pk_bf16_f32 v100, v112, v113
	v_cvt_pk_bf16_f32 v101, v114, v115
	v_cvt_pk_bf16_f32 v102, v116, v117
	v_cvt_pk_bf16_f32 v103, v118, v119
	v_cvt_pk_bf16_f32 v104, v120, v121
	v_cvt_pk_bf16_f32 v105, v122, v123
	v_cvt_pk_bf16_f32 v106, v124, v125
	v_cvt_pk_bf16_f32 v107, v126, v127
	s_add_u32 s8, s8, 0x400000
	s_addc_u32 s9, s9, 0
	global_store_dwordx2 v33, v[100:101], s[8:9]
	global_store_dwordx2 v33, v[102:103], s[8:9] offset:512
	global_store_dwordx2 v33, v[104:105], s[8:9] offset:1024
	global_store_dwordx2 v33, v[106:107], s[8:9] offset:1536
	s_add_u32 s6, s6, 0x800000
	s_addc_u32 s7, s7, 0
	global_load_dwordx4 v[112:115], v32, s[6:7]
	global_load_dwordx4 v[116:119], v32, s[6:7] offset:1024
	global_load_dwordx4 v[120:123], v32, s[6:7] offset:2048
	global_load_dwordx4 v[124:127], v32, s[6:7] offset:3072
	s_waitcnt vmcnt(16)
	v_pk_mul_f32 v[96:97], v[128:129], v[128:129]
	v_pk_fma_f32 v[96:97], v[130:131], v[130:131], v[96:97]
	v_pk_fma_f32 v[96:97], v[132:133], v[132:133], v[96:97]
	v_pk_fma_f32 v[96:97], v[134:135], v[134:135], v[96:97]
	v_pk_fma_f32 v[96:97], v[136:137], v[136:137], v[96:97]
	v_pk_fma_f32 v[96:97], v[138:139], v[138:139], v[96:97]
	v_pk_fma_f32 v[96:97], v[140:141], v[140:141], v[96:97]
	v_pk_fma_f32 v[96:97], v[142:143], v[142:143], v[96:97]
	v_add_f32_e32 v96, v96, v97
	s_nop 1
	v_add_f32_dpp v97, v96, v96 quad_perm:[1,0,3,2] row_mask:0xf bank_mask:0xf
	s_nop 1
	v_add_f32_dpp v96, v97, v97 quad_perm:[2,3,0,1] row_mask:0xf bank_mask:0xf
	s_nop 1
	v_add_f32_dpp v97, v96, v96 row_half_mirror row_mask:0xf bank_mask:0xf
	s_nop 1
	v_add_f32_dpp v96, v97, v97 row_mirror row_mask:0xf bank_mask:0xf
	s_nop 1
	v_readlane_b32 s16, v96, 0
	v_readlane_b32 s17, v96, 16
	v_readlane_b32 s18, v96, 32
	v_readlane_b32 s19, v96, 48
	s_nop 1
	v_mov_b32_e32 v96, s16
	v_add_f32_e32 v96, s17, v96
	v_add_f32_e32 v96, s18, v96
	v_add_f32_e32 v96, s19, v96
	v_mov_b32_e32 v98, 0x358637bd
	v_fmamk_f32 v96, v96, 0x3a800000, v98
	v_rsq_f32_e32 v96, v96
	s_nop 0
	v_pk_mul_f32 v[128:129], v[128:129], v[96:97] op_sel_hi:[1,0]
	v_pk_mul_f32 v[130:131], v[130:131], v[96:97] op_sel_hi:[1,0]
	v_pk_mul_f32 v[132:133], v[132:133], v[96:97] op_sel_hi:[1,0]
	v_pk_mul_f32 v[134:135], v[134:135], v[96:97] op_sel_hi:[1,0]
	v_pk_mul_f32 v[136:137], v[136:137], v[96:97] op_sel_hi:[1,0]
	v_pk_mul_f32 v[138:139], v[138:139], v[96:97] op_sel_hi:[1,0]
	v_pk_mul_f32 v[140:141], v[140:141], v[96:97] op_sel_hi:[1,0]
	v_pk_mul_f32 v[142:143], v[142:143], v[96:97] op_sel_hi:[1,0]
	v_pk_mul_f32 v[128:129], v[48:49], v[128:129]
	v_pk_mul_f32 v[130:131], v[50:51], v[130:131]
	v_pk_mul_f32 v[132:133], v[52:53], v[132:133]
; __device__ __forceinline__ void store_bf4(bf16_t* p, f32x4 v) { uint2 o; o.x = pk2(v[0], v[1]); o.y = pk2(v[2], v[3]); *(uint2*)p = o; }
; __device__ __forceinline__ void norm_row_pre(const f32x4 (&v)[4], const float* __restrict__ g, const float* __restrict__ shift, const float* __restrict__ scale, bf16_t* __restrict__ dst, int lane) {
;     float ss = 0.f;
; #pragma unroll
;     for (int j = 0; j < 4; ++j) ss += v[j][0] * v[j][0] + v[j][1] * v[j][1] + v[j][2] * v[j][2] + v[j][3] * v[j][3];
;     ss = wave_sum(ss);
;     const float rstd = rsqrtf(ss * (1.f / 1024.f) + 1e-6f);
; #pragma unroll
;     for (int j = 0; j < 4; ++j) {
;         const int c4 = lane + 64 * j;
;         const f32x4 g4 = ((const f32x4*)g)[c4], sh = ((const f32x4*)shift)[c4], sc = ((const f32x4*)scale)[c4];
;         f32x4 h = (v[j] * rstd) * g4; h = h * (sc + 1.f) + sh;
;         store_bf4(dst + c4 * 4, h);
;     }
; __device__ __forceinline__ void phase1(const Params& P) {
;     ...
;             if (nrow < NT) { const float* src = nrow < NL ? P.in[0] + (size_t)nrow * 1024 : P.in[2] + (size_t)(nrow - NL) * 1024;
; #pragma unroll
;                 for (int j = 0; j < 4; ++j) vn[j] = ((const f32x4*)src)[lane + 64 * j]; }
;             const int mr = row < NL ? (row >> 13) : 4;
;             norm_row_pre(v, P.in[6], mod + mr * 9216 + 0, mod + mr * 9216 + 1024, H + (size_t)row * 1024, lane);
;             if (row >= NL) {
; #pragma unroll
;                 for (int j = 0; j < 4; ++j) ((f32x4*)((float*)(P.ws + OFF_E) + (size_t)(row - NL) * 1024))[lane + 64 * j] = v[j];
;             }
	v_pk_mul_f32 v[134:135], v[54:55], v[134:135]
	v_pk_mul_f32 v[136:137], v[56:57], v[136:137]
	v_pk_mul_f32 v[138:139], v[58:59], v[138:139]
	v_pk_mul_f32 v[140:141], v[60:61], v[140:141]
	v_pk_mul_f32 v[142:143], v[62:63], v[142:143]
	v_pk_fma_f32 v[128:129], v[176:177], v[128:129], v[192:193]
	v_pk_fma_f32 v[130:131], v[178:179], v[130:131], v[194:195]
	v_pk_fma_f32 v[132:133], v[180:181], v[132:133], v[196:197]
	v_pk_fma_f32 v[134:135], v[182:183], v[134:135], v[198:199]
	v_pk_fma_f32 v[136:137], v[184:185], v[136:137], v[200:201]
	v_pk_fma_f32 v[138:139], v[186:187], v[138:139], v[202:203]
	v_pk_fma_f32 v[140:141], v[188:189], v[140:141], v[204:205]
	v_pk_fma_f32 v[142:143], v[190:191], v[142:143], v[206:207]
	v_cvt_pk_bf16_f32 v100, v128, v129
	v_cvt_pk_bf16_f32 v101, v130, v131
	v_cvt_pk_bf16_f32 v102, v132, v133
	v_cvt_pk_bf16_f32 v103, v134, v135
	v_cvt_pk_bf16_f32 v104, v136, v137
	v_cvt_pk_bf16_f32 v105, v138, v139
	v_cvt_pk_bf16_f32 v106, v140, v141
	v_cvt_pk_bf16_f32 v107, v142, v143
	s_add_u32 s8, s8, 0x400000
	s_addc_u32 s9, s9, 0
	global_store_dwordx2 v33, v[100:101], s[8:9]
	global_store_dwordx2 v33, v[102:103], s[8:9] offset:512
	global_store_dwordx2 v33, v[104:105], s[8:9] offset:1024
	global_store_dwordx2 v33, v[106:107], s[8:9] offset:1536
	s_lshl_b32 s10, s20, 12
	s_add_u32 s6, s40, s10
	s_addc_u32 s7, s41, 0
	global_load_dwordx4 v[128:131], v32, s[6:7]
	global_load_dwordx4 v[132:135], v32, s[6:7] offset:1024
	global_load_dwordx4 v[136:139], v32, s[6:7] offset:2048
	global_load_dwordx4 v[140:143], v32, s[6:7] offset:3072
	s_mov_b32 s10, 147456
	s_add_u32 s12, s2, s10
	s_addc_u32 s13, s3, 0
	s_add_u32 s14, s12, 0x1000
	s_addc_u32 s15, s13, 0
	global_load_dwordx4 v[80:83], v32, s[12:13]
	global_load_dwordx4 v[84:87], v32, s[12:13] offset:1024
	global_load_dwordx4 v[88:91], v32, s[12:13] offset:2048
	global_load_dwordx4 v[92:95], v32, s[12:13] offset:3072
	global_load_dwordx4 v[64:67], v32, s[14:15]
	global_load_dwordx4 v[68:71], v32, s[14:15] offset:1024
	global_load_dwordx4 v[72:75], v32, s[14:15] offset:2048
	global_load_dwordx4 v[76:79], v32, s[14:15] offset:3072
	s_waitcnt vmcnt(24)
	v_pk_mul_f32 v[96:97], v[144:145], v[144:145]
	v_pk_fma_f32 v[96:97], v[146:147], v[146:147], v[96:97]
	v_pk_fma_f32 v[96:97], v[148:149], v[148:149], v[96:97]
	v_pk_fma_f32 v[96:97], v[150:151], v[150:151], v[96:97]
	v_pk_fma_f32 v[96:97], v[152:153], v[152:153], v[96:97]
	v_pk_fma_f32 v[96:97], v[154:155], v[154:155], v[96:97]
	v_pk_fma_f32 v[96:97], v[156:157], v[156:157], v[96:97]
	v_pk_fma_f32 v[96:97], v[158:159], v[158:159], v[96:97]
	v_add_f32_e32 v96, v96, v97
	s_nop 1
	v_add_f32_dpp v97, v96, v96 quad_perm:[1,0,3,2] row_mask:0xf bank_mask:0xf
	s_nop 1
	v_add_f32_dpp v96, v97, v97 quad_perm:[2,3,0,1] row_mask:0xf bank_mask:0xf
	s_nop 1
	v_add_f32_dpp v97, v96, v96 row_half_mirror row_mask:0xf bank_mask:0xf
	s_nop 1
	v_add_f32_dpp v96, v97, v97 row_mirror row_mask:0xf bank_mask:0xf
	s_nop 1
	v_readlane_b32 s16, v96, 0
	v_readlane_b32 s17, v96, 16
	v_readlane_b32 s18, v96, 32
	v_readlane_b32 s19, v96, 48
	s_nop 1
	v_mov_b32_e32 v96, s16
	v_add_f32_e32 v96, s17, v96
	v_add_f32_e32 v96, s18, v96
	v_add_f32_e32 v96, s19, v96
	v_mov_b32_e32 v98, 0x358637bd
	v_fmamk_f32 v96, v96, 0x3a800000, v98
	v_rsq_f32_e32 v96, v96
	s_nop 0
	v_pk_mul_f32 v[144:145], v[144:145], v[96:97] op_sel_hi:[1,0]
	v_pk_mul_f32 v[146:147], v[146:147], v[96:97] op_sel_hi:[1,0]
	v_pk_mul_f32 v[148:149], v[148:149], v[96:97] op_sel_hi:[1,0]
	v_pk_mul_f32 v[150:151], v[150:151], v[96:97] op_sel_hi:[1,0]
	v_pk_mul_f32 v[152:153], v[152:153], v[96:97] op_sel_hi:[1,0]
	v_pk_mul_f32 v[154:155], v[154:155], v[96:97] op_sel_hi:[1,0]
	v_pk_mul_f32 v[156:157], v[156:157], v[96:97] op_sel_hi:[1,0]
	v_pk_mul_f32 v[158:159], v[158:159], v[96:97] op_sel_hi:[1,0]
	v_pk_mul_f32 v[144:145], v[48:49], v[144:145]
	v_pk_mul_f32 v[146:147], v[50:51], v[146:147]
	v_pk_mul_f32 v[148:149], v[52:53], v[148:149]
	v_pk_mul_f32 v[150:151], v[54:55], v[150:151]
	v_pk_mul_f32 v[152:153], v[56:57], v[152:153]
	v_pk_mul_f32 v[154:155], v[58:59], v[154:155]
	v_pk_mul_f32 v[156:157], v[60:61], v[156:157]
	v_pk_mul_f32 v[158:159], v[62:63], v[158:159]
	v_pk_fma_f32 v[144:145], v[176:177], v[144:145], v[192:193]
	v_pk_fma_f32 v[146:147], v[178:179], v[146:147], v[194:195]
	v_pk_fma_f32 v[148:149], v[180:181], v[148:149], v[196:197]
	v_pk_fma_f32 v[150:151], v[182:183], v[150:151], v[198:199]
	v_pk_fma_f32 v[152:153], v[184:185], v[152:153], v[200:201]
	v_pk_fma_f32 v[154:155], v[186:187], v[154:155], v[202:203]
	v_pk_fma_f32 v[156:157], v[188:189], v[156:157], v[204:205]
	v_pk_fma_f32 v[158:159], v[190:191], v[158:159], v[206:207]
	v_cvt_pk_bf16_f32 v100, v144, v145
	v_cvt_pk_bf16_f32 v101, v146, v147
	v_cvt_pk_bf16_f32 v102, v148, v149
	v_cvt_pk_bf16_f32 v103, v150, v151
	v_cvt_pk_bf16_f32 v104, v152, v153
	v_cvt_pk_bf16_f32 v105, v154, v155
	v_cvt_pk_bf16_f32 v106, v156, v157
	v_cvt_pk_bf16_f32 v107, v158, v159
	s_add_u32 s8, s8, 0x400000
	s_addc_u32 s9, s9, 0
	global_store_dwordx2 v33, v[100:101], s[8:9]
	global_store_dwordx2 v33, v[102:103], s[8:9] offset:512
	global_store_dwordx2 v33, v[104:105], s[8:9] offset:1024
	global_store_dwordx2 v33, v[106:107], s[8:9] offset:1536
	s_waitcnt vmcnt(20)
; __device__ __forceinline__ void store_bf4(bf16_t* p, f32x4 v) { uint2 o; o.x = pk2(v[0], v[1]); o.y = pk2(v[2], v[3]); *(uint2*)p = o; }
; __device__ __forceinline__ void norm_row_pre(const f32x4 (&v)[4], const float* __restrict__ g, const float* __restrict__ shift, const float* __restrict__ scale, bf16_t* __restrict__ dst, int lane) {
;     float ss = 0.f;
; #pragma unroll
;     for (int j = 0; j < 4; ++j) ss += v[j][0] * v[j][0] + v[j][1] * v[j][1] + v[j][2] * v[j][2] + v[j][3] * v[j][3];
;     ss = wave_sum(ss);
;     const float rstd = rsqrtf(ss * (1.f / 1024.f) + 1e-6f);
; #pragma unroll
;     for (int j = 0; j < 4; ++j) {
;         const int c4 = lane + 64 * j;
;         const f32x4 g4 = ((const f32x4*)g)[c4], sh = ((const f32x4*)shift)[c4], sc = ((const f32x4*)scale)[c4];
;         f32x4 h = (v[j] * rstd) * g4; h = h * (sc + 1.f) + sh;
;         store_bf4(dst + c4 * 4, h);
;     }
; __device__ __forceinline__ void phase1(const Params& P) {
;     ...
;         while (row < NT) {
;             f32x4 v[4];
; #pragma unroll
;             for (int j = 0; j < 4; ++j) v[j] = vn[j];
;             const int nrow = row + stride;
;             if (nrow < NT) { const float* src = nrow < NL ? P.in[0] + (size_t)nrow * 1024 : P.in[2] + (size_t)(nrow - NL) * 1024;
; #pragma unroll
;                 for (int j = 0; j < 4; ++j) vn[j] = ((const f32x4*)src)[lane + 64 * j]; }
;             const int mr = row < NL ? (row >> 13) : 4;
;             norm_row_pre(v, P.in[6], mod + mr * 9216 + 0, mod + mr * 9216 + 1024, H + (size_t)row * 1024, lane);
;             if (row >= NL) {
; #pragma unroll
;                 for (int j = 0; j < 4; ++j) ((f32x4*)((float*)(P.ws + OFF_E) + (size_t)(row - NL) * 1024))[lane + 64 * j] = v[j];
;             }
;             row = nrow;
	v_pk_mul_f32 v[96:97], v[112:113], v[112:113]
	v_pk_fma_f32 v[96:97], v[114:115], v[114:115], v[96:97]
	v_pk_fma_f32 v[96:97], v[116:117], v[116:117], v[96:97]
	v_pk_fma_f32 v[96:97], v[118:119], v[118:119], v[96:97]
	v_pk_fma_f32 v[96:97], v[120:121], v[120:121], v[96:97]
	v_pk_fma_f32 v[96:97], v[122:123], v[122:123], v[96:97]
	v_pk_fma_f32 v[96:97], v[124:125], v[124:125], v[96:97]
	v_pk_fma_f32 v[96:97], v[126:127], v[126:127], v[96:97]
	v_add_f32_e32 v96, v96, v97
	s_nop 1
	v_add_f32_dpp v97, v96, v96 quad_perm:[1,0,3,2] row_mask:0xf bank_mask:0xf
	s_nop 1
	v_add_f32_dpp v96, v97, v97 quad_perm:[2,3,0,1] row_mask:0xf bank_mask:0xf
	s_nop 1
	v_add_f32_dpp v97, v96, v96 row_half_mirror row_mask:0xf bank_mask:0xf
	s_nop 1
	v_add_f32_dpp v96, v97, v97 row_mirror row_mask:0xf bank_mask:0xf
	s_nop 1
	v_readlane_b32 s16, v96, 0
	v_readlane_b32 s17, v96, 16
	v_readlane_b32 s18, v96, 32
	v_readlane_b32 s19, v96, 48
	s_nop 1
	v_mov_b32_e32 v96, s16
	v_add_f32_e32 v96, s17, v96
	v_add_f32_e32 v96, s18, v96
	v_add_f32_e32 v96, s19, v96
	v_mov_b32_e32 v98, 0x358637bd
	v_fmamk_f32 v96, v96, 0x3a800000, v98
	v_rsq_f32_e32 v96, v96
	s_nop 0
	v_pk_mul_f32 v[112:113], v[112:113], v[96:97] op_sel_hi:[1,0]
	v_pk_mul_f32 v[114:115], v[114:115], v[96:97] op_sel_hi:[1,0]
	v_pk_mul_f32 v[116:117], v[116:117], v[96:97] op_sel_hi:[1,0]
	v_pk_mul_f32 v[118:119], v[118:119], v[96:97] op_sel_hi:[1,0]
	v_pk_mul_f32 v[120:121], v[120:121], v[96:97] op_sel_hi:[1,0]
	v_pk_mul_f32 v[122:123], v[122:123], v[96:97] op_sel_hi:[1,0]
	v_pk_mul_f32 v[124:125], v[124:125], v[96:97] op_sel_hi:[1,0]
	v_pk_mul_f32 v[126:127], v[126:127], v[96:97] op_sel_hi:[1,0]
	v_pk_mul_f32 v[112:113], v[48:49], v[112:113]
	v_pk_mul_f32 v[114:115], v[50:51], v[114:115]
	v_pk_mul_f32 v[116:117], v[52:53], v[116:117]
	v_pk_mul_f32 v[118:119], v[54:55], v[118:119]
	v_pk_mul_f32 v[120:121], v[56:57], v[120:121]
	v_pk_mul_f32 v[122:123], v[58:59], v[122:123]
	v_pk_mul_f32 v[124:125], v[60:61], v[124:125]
	v_pk_mul_f32 v[126:127], v[62:63], v[126:127]
	v_pk_fma_f32 v[112:113], v[176:177], v[112:113], v[192:193]
	v_pk_fma_f32 v[114:115], v[178:179], v[114:115], v[194:195]
	v_pk_fma_f32 v[116:117], v[180:181], v[116:117], v[196:197]
	v_pk_fma_f32 v[118:119], v[182:183], v[118:119], v[198:199]
	v_pk_fma_f32 v[120:121], v[184:185], v[120:121], v[200:201]
	v_pk_fma_f32 v[122:123], v[186:187], v[122:123], v[202:203]
	v_pk_fma_f32 v[124:125], v[188:189], v[124:125], v[204:205]
	v_pk_fma_f32 v[126:127], v[190:191], v[126:127], v[206:207]
	v_cvt_pk_bf16_f32 v100, v112, v113
	v_cvt_pk_bf16_f32 v101, v114, v115
	v_cvt_pk_bf16_f32 v102, v116, v117
	v_cvt_pk_bf16_f32 v103, v118, v119
	v_cvt_pk_bf16_f32 v104, v120, v121
	v_cvt_pk_bf16_f32 v105, v122, v123
	v_cvt_pk_bf16_f32 v106, v124, v125
	v_cvt_pk_bf16_f32 v107, v126, v127
	s_add_u32 s8, s8, 0x400000
	s_addc_u32 s9, s9, 0
	global_store_dwordx2 v33, v[100:101], s[8:9]
	global_store_dwordx2 v33, v[102:103], s[8:9] offset:512
	global_store_dwordx2 v33, v[104:105], s[8:9] offset:1024
	global_store_dwordx2 v33, v[106:107], s[8:9] offset:1536
	s_waitcnt vmcnt(8)
; __device__ __forceinline__ float bflo(unsigned u) { return __uint_as_float(u << 16); }
; __device__ __forceinline__ float bfhi(unsigned u) { return __uint_as_float(u & 0xffff0000u); }
; __device__ __forceinline__ void phase1(const Params& P) {
;     ...
;             if (nrow < NT) { const float* src = nrow < NL ? P.in[0] + (size_t)nrow * 1024 : P.in[2] + (size_t)(nrow - NL) * 1024;
; #pragma unroll
;                 for (int j = 0; j < 4; ++j) vn[j] = ((const f32x4*)src)[lane + 64 * j]; }
;             const int mr = row < NL ? (row >> 13) : 4;
;             norm_row_pre(v, P.in[6], mod + mr * 9216 + 0, mod + mr * 9216 + 1024, H + (size_t)row * 1024, lane);
;             if (row >= NL) {
; #pragma unroll
;                 for (int j = 0; j < 4; ++j) ((f32x4*)((float*)(P.ws + OFF_E) + (size_t)(row - NL) * 1024))[lane + 64 * j] = v[j];
;             }
;     ...
;     for (int r0 = blockIdx.x * 32 + w * 4; r0 < 4352 + 5632; r0 += gridDim.x * 32) {
;         const bool first = r0 < 4352;
;         const bf16_t* wt = first ? (const bf16_t*)(P.ws + OFF_WIN) + (size_t)r0 * 1024 : (const bf16_t*)(P.ws + OFF_WGU2) + (size_t)(r0 - 4352) * 1024;
;         const float* sh = mod + (first ? 3 : 6) * 1024 + lane * 16;
;         uint4 wq[4][2];
; #pragma unroll
;         for (int i = 0; i < 4; ++i) { wq[i][0] = *(const uint4*)(wt + (size_t)i * 1024 + lane * 16); wq[i][1] = *(const uint4*)(wt + (size_t)i * 1024 + lane * 16 + 8); }
;         f32x4 s4[5][4];
; #pragma unroll
;         for (int mr = 0; mr < 5; ++mr)
; #pragma unroll
;             for (int q = 0; q < 4; ++q) s4[mr][q] = *(const f32x4*)(sh + mr * 9216 + q * 4);
;         float* BW = (float*)(P.ws + OFF_BW);
; #pragma unroll
;         for (int i = 0; i < 4; ++i) {
;             const uint4 w0 = wq[i][0], w1 = wq[i][1];
;             const float wv[16] = {bflo(w0.x), bfhi(w0.x), bflo(w0.y), bfhi(w0.y), bflo(w0.z), bfhi(w0.z), bflo(w0.w), bfhi(w0.w),
;                                   bflo(w1.x), bfhi(w1.x), bflo(w1.y), bfhi(w1.y), bflo(w1.z), bfhi(w1.z), bflo(w1.w), bfhi(w1.w)};
;             const int r = r0 + i;
; #pragma unroll
;             for (int mr = 0; mr < 5; ++mr) {
;                 float a = 0.f;
; #pragma unroll
;                 for (int q = 0; q < 4; ++q) a += s4[mr][q][0] * wv[q * 4] + s4[mr][q][1] * wv[q * 4 + 1] + s4[mr][q][2] * wv[q * 4 + 2] + s4[mr][q][3] * wv[q * 4 + 3];
;                 a = wave_sum(a);
	v_pk_add_f32 v[64:65], v[64:65], 1.0 op_sel_hi:[1,0]
	v_pk_add_f32 v[66:67], v[66:67], 1.0 op_sel_hi:[1,0]
	v_pk_add_f32 v[68:69], v[68:69], 1.0 op_sel_hi:[1,0]
	v_pk_add_f32 v[70:71], v[70:71], 1.0 op_sel_hi:[1,0]
	v_pk_add_f32 v[72:73], v[72:73], 1.0 op_sel_hi:[1,0]
	v_pk_add_f32 v[74:75], v[74:75], 1.0 op_sel_hi:[1,0]
	v_pk_add_f32 v[76:77], v[76:77], 1.0 op_sel_hi:[1,0]
	v_pk_add_f32 v[78:79], v[78:79], 1.0 op_sel_hi:[1,0]
	v_pk_mul_f32 v[96:97], v[128:129], v[128:129]
	v_pk_fma_f32 v[96:97], v[130:131], v[130:131], v[96:97]
	v_pk_fma_f32 v[96:97], v[132:133], v[132:133], v[96:97]
	v_pk_fma_f32 v[96:97], v[134:135], v[134:135], v[96:97]
	v_pk_fma_f32 v[96:97], v[136:137], v[136:137], v[96:97]
	v_pk_fma_f32 v[96:97], v[138:139], v[138:139], v[96:97]
	v_pk_fma_f32 v[96:97], v[140:141], v[140:141], v[96:97]
	v_pk_fma_f32 v[96:97], v[142:143], v[142:143], v[96:97]
	v_add_f32_e32 v96, v96, v97
	s_nop 1
	v_add_f32_dpp v97, v96, v96 quad_perm:[1,0,3,2] row_mask:0xf bank_mask:0xf
	s_nop 1
	v_add_f32_dpp v96, v97, v97 quad_perm:[2,3,0,1] row_mask:0xf bank_mask:0xf
	s_nop 1
	v_add_f32_dpp v97, v96, v96 row_half_mirror row_mask:0xf bank_mask:0xf
	s_nop 1
	v_add_f32_dpp v96, v97, v97 row_mirror row_mask:0xf bank_mask:0xf
	s_nop 1
	v_readlane_b32 s16, v96, 0
	v_readlane_b32 s17, v96, 16
	v_readlane_b32 s18, v96, 32
	v_readlane_b32 s19, v96, 48
	s_nop 1
	v_mov_b32_e32 v96, s16
	v_add_f32_e32 v96, s17, v96
	v_add_f32_e32 v96, s18, v96
	v_add_f32_e32 v96, s19, v96
	v_mov_b32_e32 v98, 0x358637bd
	v_fmamk_f32 v96, v96, 0x3a800000, v98
	v_rsq_f32_e32 v96, v96
	s_lshl_b32 s10, s20, 12
	s_add_u32 s12, s68, s10
	s_addc_u32 s13, s69, 0
	s_add_u32 s12, s12, 0x1ce3d000
	s_addc_u32 s13, s13, 0
	global_store_dwordx4 v32, v[128:131], s[12:13]
	global_store_dwordx4 v32, v[132:135], s[12:13] offset:1024
	global_store_dwordx4 v32, v[136:139], s[12:13] offset:2048
	global_store_dwordx4 v32, v[140:143], s[12:13] offset:3072
	v_pk_mul_f32 v[128:129], v[128:129], v[96:97] op_sel_hi:[1,0]
	v_pk_mul_f32 v[130:131], v[130:131], v[96:97] op_sel_hi:[1,0]
	v_pk_mul_f32 v[132:133], v[132:133], v[96:97] op_sel_hi:[1,0]
	v_pk_mul_f32 v[134:135], v[134:135], v[96:97] op_sel_hi:[1,0]
	v_pk_mul_f32 v[136:137], v[136:137], v[96:97] op_sel_hi:[1,0]
	v_pk_mul_f32 v[138:139], v[138:139], v[96:97] op_sel_hi:[1,0]
	v_pk_mul_f32 v[140:141], v[140:141], v[96:97] op_sel_hi:[1,0]
	v_pk_mul_f32 v[142:143], v[142:143], v[96:97] op_sel_hi:[1,0]
	v_pk_mul_f32 v[128:129], v[48:49], v[128:129]
	v_pk_mul_f32 v[130:131], v[50:51], v[130:131]
	v_pk_mul_f32 v[132:133], v[52:53], v[132:133]
	v_pk_mul_f32 v[134:135], v[54:55], v[134:135]
	v_pk_mul_f32 v[136:137], v[56:57], v[136:137]
	v_pk_mul_f32 v[138:139], v[58:59], v[138:139]
	v_pk_mul_f32 v[140:141], v[60:61], v[140:141]
	v_pk_mul_f32 v[142:143], v[62:63], v[142:143]
	v_pk_fma_f32 v[128:129], v[64:65], v[128:129], v[80:81]
	v_pk_fma_f32 v[130:131], v[66:67], v[130:131], v[82:83]
	v_pk_fma_f32 v[132:133], v[68:69], v[132:133], v[84:85]
	v_pk_fma_f32 v[134:135], v[70:71], v[134:135], v[86:87]
	v_pk_fma_f32 v[136:137], v[72:73], v[136:137], v[88:89]
	v_pk_fma_f32 v[138:139], v[74:75], v[138:139], v[90:91]
	v_pk_fma_f32 v[140:141], v[76:77], v[140:141], v[92:93]
	v_pk_fma_f32 v[142:143], v[78:79], v[142:143], v[94:95]
	v_cvt_pk_bf16_f32 v100, v128, v129
	v_cvt_pk_bf16_f32 v101, v130, v131
	v_cvt_pk_bf16_f32 v102, v132, v133
	v_cvt_pk_bf16_f32 v103, v134, v135
	v_cvt_pk_bf16_f32 v104, v136, v137
	v_cvt_pk_bf16_f32 v105, v138, v139
	v_cvt_pk_bf16_f32 v106, v140, v141
	v_cvt_pk_bf16_f32 v107, v142, v143
	s_add_u32 s10, s20, 0x8000
	s_lshl_b32 s11, s10, 11
	s_lshr_b32 s10, s10, 21
	s_add_u32 s8, s68, s11
	s_addc_u32 s9, s69, s10
	s_add_u32 s8, s8, 0x52bd000
	s_addc_u32 s9, s9, 0
	global_store_dwordx2 v33, v[100:101], s[8:9]
	global_store_dwordx2 v33, v[102:103], s[8:9] offset:512
	global_store_dwordx2 v33, v[104:105], s[8:9] offset:1024
	global_store_dwordx2 v33, v[106:107], s[8:9] offset:1536
	s_branch .Lp1n_done
.Lp1n_done:
.LBB0_139:
	s_or_b64 exec, exec, s[4:5]
	s_lshl_b32 s0, s33, 5
	v_lshl_add_u32 v104, v171, 2, s0
	s_movk_i32 s0, 0x2700
	v_cmp_gt_i32_e32 vcc, s0, v104
	s_and_saveexec_b64 s[0:1], vcc
	s_cbranch_execz .LBB0_194
	v_mbcnt_lo_u32_b32 v0, -1, 0
	v_mbcnt_hi_u32_b32 v0, -1, v0
	v_and_b32_e32 v1, 64, v0
	v_add_u32_e32 v1, 64, v1
	v_xor_b32_e32 v2, 1, v0
	v_cmp_lt_i32_e32 vcc, v2, v1
	v_mov_b32_e32 v107, 0
	v_lshlrev_b32_e32 v106, 6, v170
	v_cndmask_b32_e32 v2, v0, v2, vcc
	v_lshlrev_b32_e32 v114, 2, v2
	v_xor_b32_e32 v2, 2, v0
	v_cmp_lt_i32_e32 vcc, v2, v1
	s_add_u32 s10, s68, 0x1efa3000
	v_lshl_add_u64 v[108:109], s[2:3], 0, v[106:107]
	v_cndmask_b32_e32 v2, v0, v2, vcc
	v_lshlrev_b32_e32 v115, 2, v2
	v_xor_b32_e32 v2, 4, v0
	v_cmp_lt_i32_e32 vcc, v2, v1
	s_addc_u32 s11, s69, 0
	v_cmp_eq_u32_e64 s[2:3], 0, v170
	v_cndmask_b32_e32 v2, v0, v2, vcc
	v_lshlrev_b32_e32 v116, 2, v2
	v_xor_b32_e32 v2, 8, v0
	v_cmp_lt_i32_e32 vcc, v2, v1
	s_lshl_b32 s30, s90, 5
	s_mov_b64 s[12:13], 0
	v_cndmask_b32_e32 v2, v0, v2, vcc
	v_lshlrev_b32_e32 v117, 2, v2
	v_xor_b32_e32 v2, 16, v0
	v_cmp_lt_i32_e32 vcc, v2, v1
	s_movk_i32 s31, 0x10ff
	s_movk_i32 s34, 0x1100
	v_cndmask_b32_e32 v2, v0, v2, vcc
	v_lshlrev_b32_e32 v118, 2, v2
	v_xor_b32_e32 v2, 32, v0
	v_cmp_lt_i32_e32 vcc, v2, v1
	v_mov_b32_e32 v120, 0x1080000
	v_mov_b32_e32 v121, 0x2100000
	v_cndmask_b32_e32 v0, v0, v2, vcc
	v_lshlrev_b32_e32 v119, 2, v0
	v_mov_b32_e32 v122, 0x6000
	v_mov_b32_e32 v123, 0x3000
	v_lshlrev_b32_e32 v110, 1, v32
	v_mov_b32_e32 v111, v107
	s_mov_b64 s[14:15], 0x1000
	s_movk_i32 s35, 0x1000
	s_mov_b64 s[16:17], 0x1800
	s_mov_b64 s[18:19], 0x9000
	s_mov_b32 s38, 0x9000
	s_mov_b64 s[20:21], 0x12000
	s_mov_b32 s39, 0x12000
	s_mov_b64 s[22:23], 0x1b000
	s_mov_b32 s40, 0x1b000
	s_mov_b64 s[24:25], 0x24000
	s_mov_b32 s41, 0x24000
	s_movk_i32 s42, 0x26ff
	v_mov_b32_e32 v124, 0x16800
	v_mov_b32_e32 v125, 0x4400
	v_mov_b32_e32 v126, 0x1c000
	v_mov_b32_e32 v127, 0x8800
	v_mov_b32_e32 v128, 0x21800
	v_mov_b32_e32 v129, 0xcc00
	v_mov_b32_e32 v130, 0x16804
	v_mov_b32_e32 v131, 0x4404
	v_mov_b32_e32 v132, 0x1c004
	v_mov_b32_e32 v133, 0x8804
	v_mov_b32_e32 v134, 0x21804
	v_mov_b32_e32 v135, 0xcc04
	v_mov_b32_e32 v136, 0x16808
	v_mov_b32_e32 v137, 0x4408
	v_mov_b32_e32 v138, 0x1c008
	v_mov_b32_e32 v139, 0x8808
	v_mov_b32_e32 v140, 0x21808
	v_mov_b32_e32 v141, 0xcc08
	v_mov_b32_e32 v142, 0x1680c
	v_mov_b32_e32 v143, 0x440c
	v_mov_b32_e32 v144, 0x1c00c
	v_mov_b32_e32 v145, 0x880c
	v_mov_b32_e32 v146, 0x2180c
	v_mov_b32_e32 v147, 0xcc0c
	s_branch .LBB0_142
